# plus GEMM K-loops: the redundant s_setprio 0 / s_setprio 1 pair between the two 16-MFMA groups of every super-phase removed (32 MFMAs now issue back to back)
# speedup vs baseline: 1.0069x; 1.0069x over previous
.LBB0_849:
	ds_read_b128 v[146:149], v155
	ds_read_b128 v[160:163], v155 offset:1024
	ds_read_b128 v[164:167], v155 offset:2048
	ds_read_b128 v[168:171], v155 offset:3072
	ds_read_b128 v[172:175], v156
	ds_read_b128 v[176:179], v156 offset:1024
	ds_read_b128 v[180:183], v156 offset:2048
	ds_read_b128 v[184:187], v156 offset:3072
	s_add_u32 s74, s72, 0xfff80080
	s_addc_u32 s75, s73, -1
	s_cmp_eq_u32 s85, 28
	s_cselect_b32 s77, s63, s75
	s_cselect_b32 s76, s69, s74
	s_cselect_b32 s75, s57, s84
	s_cselect_b32 s74, s71, s83
	v_lshl_add_u64 v[220:221], s[72:73], 0, v[138:139]
	s_add_i32 m0, s3, 0xc000
	ds_read_b128 v[188:191], v157
	ds_read_b128 v[192:195], v157 offset:1024
	ds_read_b128 v[196:199], v157 offset:2048
	ds_read_b128 v[200:203], v157 offset:3072
	ds_read_b128 v[204:207], v157 offset:4096
	ds_read_b128 v[208:211], v157 offset:5120
	ds_read_b128 v[212:215], v157 offset:6144
	ds_read_b128 v[216:219], v157 offset:7168
	global_load_lds_dwordx4 v[220:221], off
	v_lshl_add_u64 v[220:221], s[72:73], 0, v[140:141]
	s_add_i32 m0, s3, 0xe000
	s_nop 0
	global_load_lds_dwordx4 v[220:221], off
	s_waitcnt vmcnt(8)
	s_waitcnt lgkmcnt(0)
	s_barrier
	s_setprio 1
	s_waitcnt lgkmcnt(0)
	v_mfma_f32_16x16x32_bf16 v[124:127], v[146:149], v[188:191], v[124:127]
	v_mfma_f32_16x16x32_bf16 v[120:123], v[164:167], v[188:191], v[120:123]
	v_mfma_f32_16x16x32_bf16 v[108:111], v[146:149], v[196:199], v[108:111]
	v_mfma_f32_16x16x32_bf16 v[104:107], v[164:167], v[196:199], v[104:107]
	v_mfma_f32_16x16x32_bf16 v[92:95], v[146:149], v[204:207], v[92:95]
	v_mfma_f32_16x16x32_bf16 v[88:91], v[164:167], v[204:207], v[88:91]
	v_mfma_f32_16x16x32_bf16 v[76:79], v[146:149], v[212:215], v[76:79]
	v_mfma_f32_16x16x32_bf16 v[72:75], v[164:167], v[212:215], v[72:75]
	v_mfma_f32_16x16x32_bf16 v[124:127], v[160:163], v[192:195], v[124:127]
	v_mfma_f32_16x16x32_bf16 v[120:123], v[168:171], v[192:195], v[120:123]
	v_mfma_f32_16x16x32_bf16 v[108:111], v[160:163], v[200:203], v[108:111]
	v_mfma_f32_16x16x32_bf16 v[104:107], v[168:171], v[200:203], v[104:107]
	v_mfma_f32_16x16x32_bf16 v[92:95], v[160:163], v[208:211], v[92:95]
	v_mfma_f32_16x16x32_bf16 v[88:91], v[168:171], v[208:211], v[88:91]
	v_mfma_f32_16x16x32_bf16 v[76:79], v[160:163], v[216:219], v[76:79]
	v_mfma_f32_16x16x32_bf16 v[72:75], v[168:171], v[216:219], v[72:75]
	v_mfma_f32_16x16x32_bf16 v[116:119], v[172:175], v[188:191], v[116:119]
	v_mfma_f32_16x16x32_bf16 v[112:115], v[180:183], v[188:191], v[112:115]
	v_mfma_f32_16x16x32_bf16 v[100:103], v[172:175], v[196:199], v[100:103]
	v_mfma_f32_16x16x32_bf16 v[96:99], v[180:183], v[196:199], v[96:99]
	v_mfma_f32_16x16x32_bf16 v[84:87], v[172:175], v[204:207], v[84:87]
	v_mfma_f32_16x16x32_bf16 v[80:83], v[180:183], v[204:207], v[80:83]
	v_mfma_f32_16x16x32_bf16 v[68:71], v[172:175], v[212:215], v[68:71]
	v_mfma_f32_16x16x32_bf16 v[64:67], v[180:183], v[212:215], v[64:67]
	v_mfma_f32_16x16x32_bf16 v[116:119], v[176:179], v[192:195], v[116:119]
	v_mfma_f32_16x16x32_bf16 v[112:115], v[184:187], v[192:195], v[112:115]
	v_mfma_f32_16x16x32_bf16 v[100:103], v[176:179], v[200:203], v[100:103]
	v_mfma_f32_16x16x32_bf16 v[96:99], v[184:187], v[200:203], v[96:99]
	v_mfma_f32_16x16x32_bf16 v[84:87], v[176:179], v[208:211], v[84:87]
	v_mfma_f32_16x16x32_bf16 v[80:83], v[184:187], v[208:211], v[80:83]
	v_mfma_f32_16x16x32_bf16 v[68:71], v[176:179], v[216:219], v[68:71]
	v_mfma_f32_16x16x32_bf16 v[64:67], v[184:187], v[216:219], v[64:67]
	s_setprio 0
	s_barrier
	s_add_i32 s86, s79, s94
	v_lshl_add_u64 v[220:221], s[74:75], 0, v[130:131]
	s_mov_b32 m0, s86
	ds_read_b128 v[188:191], v157 offset:16384
	ds_read_b128 v[192:195], v157 offset:17408
	ds_read_b128 v[196:199], v157 offset:18432
	ds_read_b128 v[200:203], v157 offset:19456
	ds_read_b128 v[204:207], v157 offset:20480
	ds_read_b128 v[208:211], v157 offset:21504
	ds_read_b128 v[212:215], v157 offset:22528
	ds_read_b128 v[216:219], v157 offset:23552
	global_load_lds_dwordx4 v[220:221], off
	s_add_i32 m0, s86, 0x2000
	s_add_u32 s86, s74, 0x80000
	v_lshl_add_u64 v[222:223], s[74:75], 0, v[134:135]
	s_addc_u32 s87, s75, 0
	s_add_i32 s88, s81, s94
	global_load_lds_dwordx4 v[222:223], off
	v_lshl_add_u64 v[224:225], s[86:87], 0, v[130:131]
	s_mov_b32 m0, s88
	v_lshl_add_u64 v[226:227], s[76:77], 0, v[132:133]
	global_load_lds_dwordx4 v[224:225], off
	v_lshl_add_u64 v[224:225], s[86:87], 0, v[134:135]
	s_add_i32 m0, s88, 0x2000
	s_nop 0
	global_load_lds_dwordx4 v[224:225], off
	v_lshl_add_u64 v[224:225], s[76:77], 0, v[128:129]
	s_mov_b32 m0, s3
	s_nop 0
	global_load_lds_dwordx4 v[224:225], off
	s_mov_b32 m0, s6
	s_nop 0
	global_load_lds_dwordx4 v[226:227], off
	s_waitcnt vmcnt(8)
	s_waitcnt lgkmcnt(0)
	s_barrier
	s_setprio 1
	s_waitcnt lgkmcnt(0)
	v_mfma_f32_16x16x32_bf16 v[60:63], v[146:149], v[188:191], v[60:63]
	v_mfma_f32_16x16x32_bf16 v[56:59], v[164:167], v[188:191], v[56:59]
	v_mfma_f32_16x16x32_bf16 v[44:47], v[146:149], v[196:199], v[44:47]
	v_mfma_f32_16x16x32_bf16 v[40:43], v[164:167], v[196:199], v[40:43]
	v_mfma_f32_16x16x32_bf16 v[28:31], v[146:149], v[204:207], v[28:31]
	v_mfma_f32_16x16x32_bf16 v[24:27], v[164:167], v[204:207], v[24:27]
	v_mfma_f32_16x16x32_bf16 v[12:15], v[146:149], v[212:215], v[12:15]
	v_mfma_f32_16x16x32_bf16 v[8:11], v[164:167], v[212:215], v[8:11]
	v_mfma_f32_16x16x32_bf16 v[60:63], v[160:163], v[192:195], v[60:63]
	v_mfma_f32_16x16x32_bf16 v[56:59], v[168:171], v[192:195], v[56:59]
	v_mfma_f32_16x16x32_bf16 v[44:47], v[160:163], v[200:203], v[44:47]
	v_mfma_f32_16x16x32_bf16 v[40:43], v[168:171], v[200:203], v[40:43]
	v_mfma_f32_16x16x32_bf16 v[28:31], v[160:163], v[208:211], v[28:31]
	v_mfma_f32_16x16x32_bf16 v[24:27], v[168:171], v[208:211], v[24:27]
	v_mfma_f32_16x16x32_bf16 v[12:15], v[160:163], v[216:219], v[12:15]
	v_mfma_f32_16x16x32_bf16 v[8:11], v[168:171], v[216:219], v[8:11]
	v_mfma_f32_16x16x32_bf16 v[52:55], v[172:175], v[188:191], v[52:55]
	v_mfma_f32_16x16x32_bf16 v[48:51], v[180:183], v[188:191], v[48:51]
	v_mfma_f32_16x16x32_bf16 v[36:39], v[172:175], v[196:199], v[36:39]
	v_mfma_f32_16x16x32_bf16 v[32:35], v[180:183], v[196:199], v[32:35]
	v_mfma_f32_16x16x32_bf16 v[20:23], v[172:175], v[204:207], v[20:23]
	v_mfma_f32_16x16x32_bf16 v[16:19], v[180:183], v[204:207], v[16:19]
	v_mfma_f32_16x16x32_bf16 v[4:7], v[172:175], v[212:215], v[4:7]
	v_mfma_f32_16x16x32_bf16 v[0:3], v[180:183], v[212:215], v[0:3]
	v_mfma_f32_16x16x32_bf16 v[52:55], v[176:179], v[192:195], v[52:55]
	v_mfma_f32_16x16x32_bf16 v[48:51], v[184:187], v[192:195], v[48:51]
	v_mfma_f32_16x16x32_bf16 v[36:39], v[176:179], v[200:203], v[36:39]
	v_mfma_f32_16x16x32_bf16 v[32:35], v[184:187], v[200:203], v[32:35]
	v_mfma_f32_16x16x32_bf16 v[20:23], v[176:179], v[208:211], v[20:23]
	v_mfma_f32_16x16x32_bf16 v[16:19], v[184:187], v[208:211], v[16:19]
	v_mfma_f32_16x16x32_bf16 v[4:7], v[176:179], v[216:219], v[4:7]
	v_mfma_f32_16x16x32_bf16 v[0:3], v[184:187], v[216:219], v[0:3]
	s_setprio 0
	s_barrier
	s_add_i32 s86, 0, 0x18000
	v_add_u32_e32 v159, s86, v151
	s_add_i32 s87, 0, 0x1c000
	ds_read_b128 v[146:149], v159
	ds_read_b128 v[160:163], v159 offset:1024
	ds_read_b128 v[164:167], v159 offset:2048
	ds_read_b128 v[168:171], v159 offset:3072
	v_add_u32_e32 v159, s87, v151
	ds_read_b128 v[172:175], v159
	ds_read_b128 v[176:179], v159 offset:1024
	ds_read_b128 v[180:183], v159 offset:2048
	ds_read_b128 v[184:187], v159 offset:3072
	s_add_u32 s76, s76, 0x80000
	s_addc_u32 s77, s77, 0
	s_mov_b32 m0, s7
	v_lshl_add_u64 v[228:229], s[76:77], 0, v[128:129]
	ds_read_b128 v[188:191], v157 offset:32768
	ds_read_b128 v[192:195], v157 offset:33792
	ds_read_b128 v[196:199], v157 offset:34816
	ds_read_b128 v[200:203], v157 offset:35840
	ds_read_b128 v[204:207], v157 offset:36864
	ds_read_b128 v[208:211], v157 offset:37888
	ds_read_b128 v[212:215], v157 offset:38912
	ds_read_b128 v[216:219], v157 offset:39936
	global_load_lds_dwordx4 v[228:229], off
	v_lshl_add_u64 v[228:229], s[76:77], 0, v[132:133]
	s_mov_b32 m0, s29
	s_nop 0
	global_load_lds_dwordx4 v[228:229], off
	s_waitcnt vmcnt(8)
	s_waitcnt lgkmcnt(0)
	s_barrier
	s_setprio 1
	s_waitcnt lgkmcnt(0)
	v_mfma_f32_16x16x32_bf16 v[124:127], v[146:149], v[188:191], v[124:127]
	v_mfma_f32_16x16x32_bf16 v[120:123], v[164:167], v[188:191], v[120:123]
	v_mfma_f32_16x16x32_bf16 v[108:111], v[146:149], v[196:199], v[108:111]
	v_mfma_f32_16x16x32_bf16 v[104:107], v[164:167], v[196:199], v[104:107]
	v_mfma_f32_16x16x32_bf16 v[92:95], v[146:149], v[204:207], v[92:95]
	v_mfma_f32_16x16x32_bf16 v[88:91], v[164:167], v[204:207], v[88:91]
	v_mfma_f32_16x16x32_bf16 v[76:79], v[146:149], v[212:215], v[76:79]
	v_mfma_f32_16x16x32_bf16 v[72:75], v[164:167], v[212:215], v[72:75]
	v_mfma_f32_16x16x32_bf16 v[124:127], v[160:163], v[192:195], v[124:127]
	v_mfma_f32_16x16x32_bf16 v[120:123], v[168:171], v[192:195], v[120:123]
	v_mfma_f32_16x16x32_bf16 v[108:111], v[160:163], v[200:203], v[108:111]
	v_mfma_f32_16x16x32_bf16 v[104:107], v[168:171], v[200:203], v[104:107]
	v_mfma_f32_16x16x32_bf16 v[92:95], v[160:163], v[208:211], v[92:95]
	v_mfma_f32_16x16x32_bf16 v[88:91], v[168:171], v[208:211], v[88:91]
	v_mfma_f32_16x16x32_bf16 v[76:79], v[160:163], v[216:219], v[76:79]
	v_mfma_f32_16x16x32_bf16 v[72:75], v[168:171], v[216:219], v[72:75]
	v_mfma_f32_16x16x32_bf16 v[116:119], v[172:175], v[188:191], v[116:119]
	v_mfma_f32_16x16x32_bf16 v[112:115], v[180:183], v[188:191], v[112:115]
	v_mfma_f32_16x16x32_bf16 v[100:103], v[172:175], v[196:199], v[100:103]
	v_mfma_f32_16x16x32_bf16 v[96:99], v[180:183], v[196:199], v[96:99]
	v_mfma_f32_16x16x32_bf16 v[84:87], v[172:175], v[204:207], v[84:87]
	v_mfma_f32_16x16x32_bf16 v[80:83], v[180:183], v[204:207], v[80:83]
	v_mfma_f32_16x16x32_bf16 v[68:71], v[172:175], v[212:215], v[68:71]
	v_mfma_f32_16x16x32_bf16 v[64:67], v[180:183], v[212:215], v[64:67]
	v_mfma_f32_16x16x32_bf16 v[116:119], v[176:179], v[192:195], v[116:119]
	v_mfma_f32_16x16x32_bf16 v[112:115], v[184:187], v[192:195], v[112:115]
	v_mfma_f32_16x16x32_bf16 v[100:103], v[176:179], v[200:203], v[100:103]
	v_mfma_f32_16x16x32_bf16 v[96:99], v[184:187], v[200:203], v[96:99]
	v_mfma_f32_16x16x32_bf16 v[84:87], v[176:179], v[208:211], v[84:87]
	v_mfma_f32_16x16x32_bf16 v[80:83], v[184:187], v[208:211], v[80:83]
	v_mfma_f32_16x16x32_bf16 v[68:71], v[176:179], v[216:219], v[68:71]
	v_mfma_f32_16x16x32_bf16 v[64:67], v[184:187], v[216:219], v[64:67]
	s_setprio 0
	s_barrier
	s_add_i32 s76, s86, s94
	v_lshl_add_u64 v[220:221], v[220:221], 0, s[18:19]
	s_mov_b32 m0, s76
	ds_read_b128 v[188:191], v157 offset:49152
	ds_read_b128 v[192:195], v157 offset:50176
	ds_read_b128 v[196:199], v157 offset:51200
	ds_read_b128 v[200:203], v157 offset:52224
	ds_read_b128 v[204:207], v157 offset:53248
	ds_read_b128 v[208:211], v157 offset:54272
	ds_read_b128 v[212:215], v157 offset:55296
	ds_read_b128 v[216:219], v157 offset:56320
	global_load_lds_dwordx4 v[220:221], off
	s_add_i32 m0, s76, 0x2000
	s_add_u32 s74, s74, 0x80080
	v_lshl_add_u64 v[220:221], v[222:223], 0, s[18:19]
	s_addc_u32 s75, s75, 0
	s_add_i32 s76, s87, s94
	global_load_lds_dwordx4 v[220:221], off
	v_lshl_add_u64 v[220:221], s[74:75], 0, v[130:131]
	s_mov_b32 m0, s76
	s_nop 0
	global_load_lds_dwordx4 v[220:221], off
	v_lshl_add_u64 v[220:221], s[74:75], 0, v[134:135]
	s_add_i32 m0, s76, 0x2000
	s_nop 0
	global_load_lds_dwordx4 v[220:221], off
	v_lshl_add_u64 v[220:221], v[224:225], 0, s[18:19]
	s_mov_b32 m0, s34
	s_nop 0
	global_load_lds_dwordx4 v[220:221], off
	v_lshl_add_u64 v[220:221], v[226:227], 0, s[18:19]
	s_mov_b32 m0, s35
	s_nop 0
	global_load_lds_dwordx4 v[220:221], off
	s_waitcnt vmcnt(8)
	s_waitcnt lgkmcnt(0)
	s_barrier
	s_setprio 1
	s_waitcnt lgkmcnt(0)
	v_mfma_f32_16x16x32_bf16 v[60:63], v[146:149], v[188:191], v[60:63]
	v_mfma_f32_16x16x32_bf16 v[56:59], v[164:167], v[188:191], v[56:59]
	v_mfma_f32_16x16x32_bf16 v[44:47], v[146:149], v[196:199], v[44:47]
	v_mfma_f32_16x16x32_bf16 v[40:43], v[164:167], v[196:199], v[40:43]
	v_mfma_f32_16x16x32_bf16 v[28:31], v[146:149], v[204:207], v[28:31]
	v_mfma_f32_16x16x32_bf16 v[24:27], v[164:167], v[204:207], v[24:27]
	v_mfma_f32_16x16x32_bf16 v[12:15], v[146:149], v[212:215], v[12:15]
	v_mfma_f32_16x16x32_bf16 v[8:11], v[164:167], v[212:215], v[8:11]
	v_mfma_f32_16x16x32_bf16 v[60:63], v[160:163], v[192:195], v[60:63]
	v_mfma_f32_16x16x32_bf16 v[56:59], v[168:171], v[192:195], v[56:59]
	v_mfma_f32_16x16x32_bf16 v[44:47], v[160:163], v[200:203], v[44:47]
	v_mfma_f32_16x16x32_bf16 v[40:43], v[168:171], v[200:203], v[40:43]
	v_mfma_f32_16x16x32_bf16 v[28:31], v[160:163], v[208:211], v[28:31]
	v_mfma_f32_16x16x32_bf16 v[24:27], v[168:171], v[208:211], v[24:27]
	v_mfma_f32_16x16x32_bf16 v[12:15], v[160:163], v[216:219], v[12:15]
	v_mfma_f32_16x16x32_bf16 v[8:11], v[168:171], v[216:219], v[8:11]
	v_mfma_f32_16x16x32_bf16 v[52:55], v[172:175], v[188:191], v[52:55]
	v_mfma_f32_16x16x32_bf16 v[48:51], v[180:183], v[188:191], v[48:51]
	v_mfma_f32_16x16x32_bf16 v[36:39], v[172:175], v[196:199], v[36:39]
	v_mfma_f32_16x16x32_bf16 v[32:35], v[180:183], v[196:199], v[32:35]
	v_mfma_f32_16x16x32_bf16 v[20:23], v[172:175], v[204:207], v[20:23]
	v_mfma_f32_16x16x32_bf16 v[16:19], v[180:183], v[204:207], v[16:19]
	v_mfma_f32_16x16x32_bf16 v[4:7], v[172:175], v[212:215], v[4:7]
	v_mfma_f32_16x16x32_bf16 v[0:3], v[180:183], v[212:215], v[0:3]
	v_mfma_f32_16x16x32_bf16 v[52:55], v[176:179], v[192:195], v[52:55]
	v_mfma_f32_16x16x32_bf16 v[48:51], v[184:187], v[192:195], v[48:51]
	v_mfma_f32_16x16x32_bf16 v[36:39], v[176:179], v[200:203], v[36:39]
	v_mfma_f32_16x16x32_bf16 v[32:35], v[184:187], v[200:203], v[32:35]
	v_mfma_f32_16x16x32_bf16 v[20:23], v[176:179], v[208:211], v[20:23]
	v_mfma_f32_16x16x32_bf16 v[16:19], v[184:187], v[208:211], v[16:19]
	v_mfma_f32_16x16x32_bf16 v[4:7], v[176:179], v[216:219], v[4:7]
	v_mfma_f32_16x16x32_bf16 v[0:3], v[184:187], v[216:219], v[0:3]
	s_setprio 0
	s_barrier
	s_add_i32 s85, s85, 2
	s_add_u32 s72, s72, 0x100
	s_addc_u32 s73, s73, 0
	s_add_u32 s83, s83, 0x100
	s_addc_u32 s84, s84, 0
	s_cmp_gt_u32 s85, 29
	s_cbranch_scc0 .LBB0_849
	s_and_b64 vcc, exec, s[20:21]
	s_cbranch_vccz .LBB0_852
	s_barrier

.LBB0_946:
	ds_read_b128 v[148:151], v143
	ds_read_b128 v[152:155], v143 offset:1024
	ds_read_b128 v[156:159], v143 offset:2048
	ds_read_b128 v[160:163], v143 offset:3072
	ds_read_b128 v[164:167], v144
	ds_read_b128 v[168:171], v144 offset:1024
	ds_read_b128 v[172:175], v144 offset:2048
	ds_read_b128 v[176:179], v144 offset:3072
	s_add_u32 s18, s14, s16
	s_addc_u32 s19, s15, s17
	s_add_u32 s18, s18, 0x7498100
	s_addc_u32 s19, s19, 0
	s_add_u32 s20, s24, s16
	s_addc_u32 s21, s25, s17
	s_add_u32 s69, s20, 0x1308100
	s_addc_u32 s70, s21, 0
	s_cmpk_eq_i32 s16, 0xf00
	s_cselect_b32 s21, s11, s19
	s_cselect_b32 s20, s10, s18
	s_cselect_b32 s19, s9, s70
	s_cselect_b32 s18, s8, s69
	s_mov_b32 m0, s46
	v_lshl_add_u64 v[212:213], v[136:137], 0, s[16:17]
	ds_read_b128 v[180:183], v145
	ds_read_b128 v[184:187], v145 offset:1024
	ds_read_b128 v[188:191], v145 offset:2048
	ds_read_b128 v[192:195], v145 offset:3072
	ds_read_b128 v[196:199], v145 offset:4096
	ds_read_b128 v[200:203], v145 offset:5120
	ds_read_b128 v[204:207], v145 offset:6144
	ds_read_b128 v[208:211], v145 offset:7168
	global_load_lds_dwordx4 v[212:213], off
	v_lshl_add_u64 v[212:213], v[138:139], 0, s[16:17]
	s_mov_b32 m0, s56
	s_nop 0
	global_load_lds_dwordx4 v[212:213], off
	s_waitcnt vmcnt(8)
	s_waitcnt lgkmcnt(0)
	s_barrier
	s_setprio 1
	s_waitcnt lgkmcnt(0)
	v_mfma_f32_16x16x32_bf16 v[124:127], v[148:151], v[180:183], v[124:127]
	v_mfma_f32_16x16x32_bf16 v[120:123], v[156:159], v[180:183], v[120:123]
	v_mfma_f32_16x16x32_bf16 v[108:111], v[148:151], v[188:191], v[108:111]
	v_mfma_f32_16x16x32_bf16 v[104:107], v[156:159], v[188:191], v[104:107]
	v_mfma_f32_16x16x32_bf16 v[92:95], v[148:151], v[196:199], v[92:95]
	v_mfma_f32_16x16x32_bf16 v[88:91], v[156:159], v[196:199], v[88:91]
	v_mfma_f32_16x16x32_bf16 v[76:79], v[148:151], v[204:207], v[76:79]
	v_mfma_f32_16x16x32_bf16 v[72:75], v[156:159], v[204:207], v[72:75]
	v_mfma_f32_16x16x32_bf16 v[124:127], v[152:155], v[184:187], v[124:127]
	v_mfma_f32_16x16x32_bf16 v[120:123], v[160:163], v[184:187], v[120:123]
	v_mfma_f32_16x16x32_bf16 v[108:111], v[152:155], v[192:195], v[108:111]
	v_mfma_f32_16x16x32_bf16 v[104:107], v[160:163], v[192:195], v[104:107]
	v_mfma_f32_16x16x32_bf16 v[92:95], v[152:155], v[200:203], v[92:95]
	v_mfma_f32_16x16x32_bf16 v[88:91], v[160:163], v[200:203], v[88:91]
	v_mfma_f32_16x16x32_bf16 v[76:79], v[152:155], v[208:211], v[76:79]
	v_mfma_f32_16x16x32_bf16 v[72:75], v[160:163], v[208:211], v[72:75]
	v_mfma_f32_16x16x32_bf16 v[116:119], v[164:167], v[180:183], v[116:119]
	v_mfma_f32_16x16x32_bf16 v[112:115], v[172:175], v[180:183], v[112:115]
	v_mfma_f32_16x16x32_bf16 v[100:103], v[164:167], v[188:191], v[100:103]
	v_mfma_f32_16x16x32_bf16 v[96:99], v[172:175], v[188:191], v[96:99]
	v_mfma_f32_16x16x32_bf16 v[84:87], v[164:167], v[196:199], v[84:87]
	v_mfma_f32_16x16x32_bf16 v[80:83], v[172:175], v[196:199], v[80:83]
	v_mfma_f32_16x16x32_bf16 v[68:71], v[164:167], v[204:207], v[68:71]
	v_mfma_f32_16x16x32_bf16 v[64:67], v[172:175], v[204:207], v[64:67]
	v_mfma_f32_16x16x32_bf16 v[116:119], v[168:171], v[184:187], v[116:119]
	v_mfma_f32_16x16x32_bf16 v[112:115], v[176:179], v[184:187], v[112:115]
	v_mfma_f32_16x16x32_bf16 v[100:103], v[168:171], v[192:195], v[100:103]
	v_mfma_f32_16x16x32_bf16 v[96:99], v[176:179], v[192:195], v[96:99]
	v_mfma_f32_16x16x32_bf16 v[84:87], v[168:171], v[200:203], v[84:87]
	v_mfma_f32_16x16x32_bf16 v[80:83], v[176:179], v[200:203], v[80:83]
	v_mfma_f32_16x16x32_bf16 v[68:71], v[168:171], v[208:211], v[68:71]
	v_mfma_f32_16x16x32_bf16 v[64:67], v[176:179], v[208:211], v[64:67]
	s_setprio 0
	s_barrier
	s_mov_b32 m0, s57
	v_lshl_add_u64 v[212:213], s[18:19], 0, v[132:133]
	s_add_u32 s70, s18, 0x80000
	ds_read_b128 v[180:183], v145 offset:16384
	ds_read_b128 v[184:187], v145 offset:17408
	ds_read_b128 v[188:191], v145 offset:18432
	ds_read_b128 v[192:195], v145 offset:19456
	ds_read_b128 v[196:199], v145 offset:20480
	ds_read_b128 v[200:203], v145 offset:21504
	ds_read_b128 v[204:207], v145 offset:22528
	ds_read_b128 v[208:211], v145 offset:23552
	global_load_lds_dwordx4 v[212:213], off
	v_lshl_add_u64 v[214:215], s[18:19], 0, v[128:129]
	s_mov_b32 m0, s62
	s_addc_u32 s71, s19, 0
	global_load_lds_dwordx4 v[214:215], off
	v_lshl_add_u64 v[216:217], s[70:71], 0, v[132:133]
	s_mov_b32 m0, s63
	v_lshl_add_u64 v[218:219], s[20:21], 0, v[130:131]
	global_load_lds_dwordx4 v[216:217], off
	v_lshl_add_u64 v[216:217], s[70:71], 0, v[128:129]
	s_mov_b32 m0, s64
	s_nop 0
	global_load_lds_dwordx4 v[216:217], off
	v_lshl_add_u64 v[216:217], s[20:21], 0, v[134:135]
	s_mov_b32 m0, s3
	s_nop 0
	global_load_lds_dwordx4 v[216:217], off
	s_mov_b32 m0, s6
	s_nop 0
	global_load_lds_dwordx4 v[218:219], off
	s_waitcnt vmcnt(8)
	s_waitcnt lgkmcnt(0)
	s_barrier
	s_setprio 1
	s_waitcnt lgkmcnt(0)
	v_mfma_f32_16x16x32_bf16 v[60:63], v[148:151], v[180:183], v[60:63]
	v_mfma_f32_16x16x32_bf16 v[56:59], v[156:159], v[180:183], v[56:59]
	v_mfma_f32_16x16x32_bf16 v[44:47], v[148:151], v[188:191], v[44:47]
	v_mfma_f32_16x16x32_bf16 v[40:43], v[156:159], v[188:191], v[40:43]
	v_mfma_f32_16x16x32_bf16 v[28:31], v[148:151], v[196:199], v[28:31]
	v_mfma_f32_16x16x32_bf16 v[24:27], v[156:159], v[196:199], v[24:27]
	v_mfma_f32_16x16x32_bf16 v[12:15], v[148:151], v[204:207], v[12:15]
	v_mfma_f32_16x16x32_bf16 v[8:11], v[156:159], v[204:207], v[8:11]
	v_mfma_f32_16x16x32_bf16 v[60:63], v[152:155], v[184:187], v[60:63]
	v_mfma_f32_16x16x32_bf16 v[56:59], v[160:163], v[184:187], v[56:59]
	v_mfma_f32_16x16x32_bf16 v[44:47], v[152:155], v[192:195], v[44:47]
	v_mfma_f32_16x16x32_bf16 v[40:43], v[160:163], v[192:195], v[40:43]
	v_mfma_f32_16x16x32_bf16 v[28:31], v[152:155], v[200:203], v[28:31]
	v_mfma_f32_16x16x32_bf16 v[24:27], v[160:163], v[200:203], v[24:27]
	v_mfma_f32_16x16x32_bf16 v[12:15], v[152:155], v[208:211], v[12:15]
	v_mfma_f32_16x16x32_bf16 v[8:11], v[160:163], v[208:211], v[8:11]
	v_mfma_f32_16x16x32_bf16 v[52:55], v[164:167], v[180:183], v[52:55]
	v_mfma_f32_16x16x32_bf16 v[48:51], v[172:175], v[180:183], v[48:51]
	v_mfma_f32_16x16x32_bf16 v[36:39], v[164:167], v[188:191], v[36:39]
	v_mfma_f32_16x16x32_bf16 v[32:35], v[172:175], v[188:191], v[32:35]
	v_mfma_f32_16x16x32_bf16 v[20:23], v[164:167], v[196:199], v[20:23]
	v_mfma_f32_16x16x32_bf16 v[16:19], v[172:175], v[196:199], v[16:19]
	v_mfma_f32_16x16x32_bf16 v[4:7], v[164:167], v[204:207], v[4:7]
	v_mfma_f32_16x16x32_bf16 v[0:3], v[172:175], v[204:207], v[0:3]
	v_mfma_f32_16x16x32_bf16 v[52:55], v[168:171], v[184:187], v[52:55]
	v_mfma_f32_16x16x32_bf16 v[48:51], v[176:179], v[184:187], v[48:51]
	v_mfma_f32_16x16x32_bf16 v[36:39], v[168:171], v[192:195], v[36:39]
	v_mfma_f32_16x16x32_bf16 v[32:35], v[176:179], v[192:195], v[32:35]
	v_mfma_f32_16x16x32_bf16 v[20:23], v[168:171], v[200:203], v[20:23]
	v_mfma_f32_16x16x32_bf16 v[16:19], v[176:179], v[200:203], v[16:19]
	v_mfma_f32_16x16x32_bf16 v[4:7], v[168:171], v[208:211], v[4:7]
	v_mfma_f32_16x16x32_bf16 v[0:3], v[176:179], v[208:211], v[0:3]
	s_setprio 0
	s_barrier
	ds_read_b128 v[148:151], v146
	ds_read_b128 v[152:155], v146 offset:1024
	ds_read_b128 v[156:159], v146 offset:2048
	ds_read_b128 v[160:163], v146 offset:3072
	ds_read_b128 v[164:167], v147
	ds_read_b128 v[168:171], v147 offset:1024
	ds_read_b128 v[172:175], v147 offset:2048
	ds_read_b128 v[176:179], v147 offset:3072
	s_add_u32 s20, s20, 0x80000
	s_addc_u32 s21, s21, 0
	s_mov_b32 m0, s7
	v_lshl_add_u64 v[220:221], s[20:21], 0, v[134:135]
	ds_read_b128 v[180:183], v145 offset:32768
	ds_read_b128 v[184:187], v145 offset:33792
	ds_read_b128 v[188:191], v145 offset:34816
	ds_read_b128 v[192:195], v145 offset:35840
	ds_read_b128 v[196:199], v145 offset:36864
	ds_read_b128 v[200:203], v145 offset:37888
	ds_read_b128 v[204:207], v145 offset:38912
	ds_read_b128 v[208:211], v145 offset:39936
	global_load_lds_dwordx4 v[220:221], off
	v_lshl_add_u64 v[220:221], s[20:21], 0, v[130:131]
	s_mov_b32 m0, s29
	s_nop 0
	global_load_lds_dwordx4 v[220:221], off
	s_waitcnt vmcnt(8)
	s_waitcnt lgkmcnt(0)
	s_barrier
	s_setprio 1
	s_waitcnt lgkmcnt(0)
	v_mfma_f32_16x16x32_bf16 v[124:127], v[148:151], v[180:183], v[124:127]
	v_mfma_f32_16x16x32_bf16 v[120:123], v[156:159], v[180:183], v[120:123]
	v_mfma_f32_16x16x32_bf16 v[108:111], v[148:151], v[188:191], v[108:111]
	v_mfma_f32_16x16x32_bf16 v[104:107], v[156:159], v[188:191], v[104:107]
	v_mfma_f32_16x16x32_bf16 v[92:95], v[148:151], v[196:199], v[92:95]
	v_mfma_f32_16x16x32_bf16 v[88:91], v[156:159], v[196:199], v[88:91]
	v_mfma_f32_16x16x32_bf16 v[76:79], v[148:151], v[204:207], v[76:79]
	v_mfma_f32_16x16x32_bf16 v[72:75], v[156:159], v[204:207], v[72:75]
	v_mfma_f32_16x16x32_bf16 v[124:127], v[152:155], v[184:187], v[124:127]
	v_mfma_f32_16x16x32_bf16 v[120:123], v[160:163], v[184:187], v[120:123]
	v_mfma_f32_16x16x32_bf16 v[108:111], v[152:155], v[192:195], v[108:111]
	v_mfma_f32_16x16x32_bf16 v[104:107], v[160:163], v[192:195], v[104:107]
	v_mfma_f32_16x16x32_bf16 v[92:95], v[152:155], v[200:203], v[92:95]
	v_mfma_f32_16x16x32_bf16 v[88:91], v[160:163], v[200:203], v[88:91]
	v_mfma_f32_16x16x32_bf16 v[76:79], v[152:155], v[208:211], v[76:79]
	v_mfma_f32_16x16x32_bf16 v[72:75], v[160:163], v[208:211], v[72:75]
	v_mfma_f32_16x16x32_bf16 v[116:119], v[164:167], v[180:183], v[116:119]
	v_mfma_f32_16x16x32_bf16 v[112:115], v[172:175], v[180:183], v[112:115]
	v_mfma_f32_16x16x32_bf16 v[100:103], v[164:167], v[188:191], v[100:103]
	v_mfma_f32_16x16x32_bf16 v[96:99], v[172:175], v[188:191], v[96:99]
	v_mfma_f32_16x16x32_bf16 v[84:87], v[164:167], v[196:199], v[84:87]
	v_mfma_f32_16x16x32_bf16 v[80:83], v[172:175], v[196:199], v[80:83]
	v_mfma_f32_16x16x32_bf16 v[68:71], v[164:167], v[204:207], v[68:71]
	v_mfma_f32_16x16x32_bf16 v[64:67], v[172:175], v[204:207], v[64:67]
	v_mfma_f32_16x16x32_bf16 v[116:119], v[168:171], v[184:187], v[116:119]
	v_mfma_f32_16x16x32_bf16 v[112:115], v[176:179], v[184:187], v[112:115]
	v_mfma_f32_16x16x32_bf16 v[100:103], v[168:171], v[192:195], v[100:103]
	v_mfma_f32_16x16x32_bf16 v[96:99], v[176:179], v[192:195], v[96:99]
	v_mfma_f32_16x16x32_bf16 v[84:87], v[168:171], v[200:203], v[84:87]
	v_mfma_f32_16x16x32_bf16 v[80:83], v[176:179], v[200:203], v[80:83]
	v_mfma_f32_16x16x32_bf16 v[68:71], v[168:171], v[208:211], v[68:71]
	v_mfma_f32_16x16x32_bf16 v[64:67], v[176:179], v[208:211], v[64:67]
	s_setprio 0
	s_barrier
	s_mov_b32 m0, s65
	v_lshl_add_u64 v[212:213], v[212:213], 0, s[12:13]
	s_add_u32 s18, s18, 0x80080
	ds_read_b128 v[180:183], v145 offset:49152
	ds_read_b128 v[184:187], v145 offset:50176
	ds_read_b128 v[188:191], v145 offset:51200
	ds_read_b128 v[192:195], v145 offset:52224
	ds_read_b128 v[196:199], v145 offset:53248
	ds_read_b128 v[200:203], v145 offset:54272
	ds_read_b128 v[204:207], v145 offset:55296
	ds_read_b128 v[208:211], v145 offset:56320
	global_load_lds_dwordx4 v[212:213], off
	v_lshl_add_u64 v[212:213], v[214:215], 0, s[12:13]
	s_mov_b32 m0, s66
	s_addc_u32 s19, s19, 0
	global_load_lds_dwordx4 v[212:213], off
	v_lshl_add_u64 v[212:213], s[18:19], 0, v[132:133]
	s_mov_b32 m0, s67
	s_nop 0
	global_load_lds_dwordx4 v[212:213], off
	v_lshl_add_u64 v[212:213], s[18:19], 0, v[128:129]
	s_mov_b32 m0, s68
	s_nop 0
	global_load_lds_dwordx4 v[212:213], off
	v_lshl_add_u64 v[212:213], v[216:217], 0, s[12:13]
	s_mov_b32 m0, s30
	s_nop 0
	global_load_lds_dwordx4 v[212:213], off
	v_lshl_add_u64 v[212:213], v[218:219], 0, s[12:13]
	s_mov_b32 m0, s34
	s_nop 0
	global_load_lds_dwordx4 v[212:213], off
	s_waitcnt vmcnt(8)
	s_waitcnt lgkmcnt(0)
	s_barrier
	s_setprio 1
	s_waitcnt lgkmcnt(0)
	v_mfma_f32_16x16x32_bf16 v[60:63], v[148:151], v[180:183], v[60:63]
	v_mfma_f32_16x16x32_bf16 v[56:59], v[156:159], v[180:183], v[56:59]
	v_mfma_f32_16x16x32_bf16 v[44:47], v[148:151], v[188:191], v[44:47]
	v_mfma_f32_16x16x32_bf16 v[40:43], v[156:159], v[188:191], v[40:43]
	v_mfma_f32_16x16x32_bf16 v[28:31], v[148:151], v[196:199], v[28:31]
	v_mfma_f32_16x16x32_bf16 v[24:27], v[156:159], v[196:199], v[24:27]
	v_mfma_f32_16x16x32_bf16 v[12:15], v[148:151], v[204:207], v[12:15]
	v_mfma_f32_16x16x32_bf16 v[8:11], v[156:159], v[204:207], v[8:11]
	v_mfma_f32_16x16x32_bf16 v[60:63], v[152:155], v[184:187], v[60:63]
	v_mfma_f32_16x16x32_bf16 v[56:59], v[160:163], v[184:187], v[56:59]
	v_mfma_f32_16x16x32_bf16 v[44:47], v[152:155], v[192:195], v[44:47]
	v_mfma_f32_16x16x32_bf16 v[40:43], v[160:163], v[192:195], v[40:43]
	v_mfma_f32_16x16x32_bf16 v[28:31], v[152:155], v[200:203], v[28:31]
	v_mfma_f32_16x16x32_bf16 v[24:27], v[160:163], v[200:203], v[24:27]
	v_mfma_f32_16x16x32_bf16 v[12:15], v[152:155], v[208:211], v[12:15]
	v_mfma_f32_16x16x32_bf16 v[8:11], v[160:163], v[208:211], v[8:11]
	v_mfma_f32_16x16x32_bf16 v[52:55], v[164:167], v[180:183], v[52:55]
	v_mfma_f32_16x16x32_bf16 v[48:51], v[172:175], v[180:183], v[48:51]
	v_mfma_f32_16x16x32_bf16 v[36:39], v[164:167], v[188:191], v[36:39]
	v_mfma_f32_16x16x32_bf16 v[32:35], v[172:175], v[188:191], v[32:35]
	v_mfma_f32_16x16x32_bf16 v[20:23], v[164:167], v[196:199], v[20:23]
	v_mfma_f32_16x16x32_bf16 v[16:19], v[172:175], v[196:199], v[16:19]
	v_mfma_f32_16x16x32_bf16 v[4:7], v[164:167], v[204:207], v[4:7]
	v_mfma_f32_16x16x32_bf16 v[0:3], v[172:175], v[204:207], v[0:3]
	v_mfma_f32_16x16x32_bf16 v[52:55], v[168:171], v[184:187], v[52:55]
	v_mfma_f32_16x16x32_bf16 v[48:51], v[176:179], v[184:187], v[48:51]
	v_mfma_f32_16x16x32_bf16 v[36:39], v[168:171], v[192:195], v[36:39]
	v_mfma_f32_16x16x32_bf16 v[32:35], v[176:179], v[192:195], v[32:35]
	v_mfma_f32_16x16x32_bf16 v[20:23], v[168:171], v[200:203], v[20:23]
	v_mfma_f32_16x16x32_bf16 v[16:19], v[176:179], v[200:203], v[16:19]
	v_mfma_f32_16x16x32_bf16 v[4:7], v[168:171], v[208:211], v[4:7]
	v_mfma_f32_16x16x32_bf16 v[0:3], v[176:179], v[208:211], v[0:3]
	s_setprio 0
	s_barrier
	s_add_i32 s35, s35, 2
	s_add_u32 s16, s16, 0x100
	s_addc_u32 s17, s17, 0
	s_cmp_gt_u32 s35, 29
	s_cbranch_scc0 .LBB0_946
	s_cmpk_lt_u32 s80, 0x100
	s_cbranch_scc0 .LBB0_949
	s_barrier

.LBB0_1693:
	ds_read_b128 v[140:143], v149
	ds_read_b128 v[152:155], v149 offset:1024
	ds_read_b128 v[156:159], v149 offset:2048
	ds_read_b128 v[160:163], v149 offset:3072
	ds_read_b128 v[164:167], v150
	ds_read_b128 v[168:171], v150 offset:1024
	ds_read_b128 v[172:175], v150 offset:2048
	ds_read_b128 v[176:179], v150 offset:3072
	s_add_u32 s76, s74, 0xfff80080
	s_addc_u32 s77, s75, -1
	s_cmp_eq_u32 s86, 28
	s_cselect_b32 s79, s67, s77
	s_cselect_b32 s78, s73, s76
	s_cselect_b32 s77, s65, s85
	s_cselect_b32 s76, s83, s84
	v_lshl_add_u64 v[212:213], s[74:75], 0, v[132:133]
	s_add_i32 m0, s6, 0xc000
	ds_read_b128 v[180:183], v151
	ds_read_b128 v[184:187], v151 offset:1024
	ds_read_b128 v[188:191], v151 offset:2048
	ds_read_b128 v[192:195], v151 offset:3072
	ds_read_b128 v[196:199], v151 offset:4096
	ds_read_b128 v[200:203], v151 offset:5120
	ds_read_b128 v[204:207], v151 offset:6144
	ds_read_b128 v[208:211], v151 offset:7168
	global_load_lds_dwordx4 v[212:213], off
	v_lshl_add_u64 v[212:213], s[74:75], 0, v[134:135]
	s_add_i32 m0, s6, 0xe000
	s_nop 0
	global_load_lds_dwordx4 v[212:213], off
	s_waitcnt vmcnt(8)
	s_waitcnt lgkmcnt(0)
	s_barrier
	s_setprio 1
	s_waitcnt lgkmcnt(0)
	v_mfma_f32_16x16x32_bf16 v[124:127], v[140:143], v[180:183], v[124:127]
	v_mfma_f32_16x16x32_bf16 v[120:123], v[156:159], v[180:183], v[120:123]
	v_mfma_f32_16x16x32_bf16 v[108:111], v[140:143], v[188:191], v[108:111]
	v_mfma_f32_16x16x32_bf16 v[104:107], v[156:159], v[188:191], v[104:107]
	v_mfma_f32_16x16x32_bf16 v[92:95], v[140:143], v[196:199], v[92:95]
	v_mfma_f32_16x16x32_bf16 v[88:91], v[156:159], v[196:199], v[88:91]
	v_mfma_f32_16x16x32_bf16 v[76:79], v[140:143], v[204:207], v[76:79]
	v_mfma_f32_16x16x32_bf16 v[72:75], v[156:159], v[204:207], v[72:75]
	v_mfma_f32_16x16x32_bf16 v[124:127], v[152:155], v[184:187], v[124:127]
	v_mfma_f32_16x16x32_bf16 v[120:123], v[160:163], v[184:187], v[120:123]
	v_mfma_f32_16x16x32_bf16 v[108:111], v[152:155], v[192:195], v[108:111]
	v_mfma_f32_16x16x32_bf16 v[104:107], v[160:163], v[192:195], v[104:107]
	v_mfma_f32_16x16x32_bf16 v[92:95], v[152:155], v[200:203], v[92:95]
	v_mfma_f32_16x16x32_bf16 v[88:91], v[160:163], v[200:203], v[88:91]
	v_mfma_f32_16x16x32_bf16 v[76:79], v[152:155], v[208:211], v[76:79]
	v_mfma_f32_16x16x32_bf16 v[72:75], v[160:163], v[208:211], v[72:75]
	v_mfma_f32_16x16x32_bf16 v[116:119], v[164:167], v[180:183], v[116:119]
	v_mfma_f32_16x16x32_bf16 v[112:115], v[172:175], v[180:183], v[112:115]
	v_mfma_f32_16x16x32_bf16 v[100:103], v[164:167], v[188:191], v[100:103]
	v_mfma_f32_16x16x32_bf16 v[96:99], v[172:175], v[188:191], v[96:99]
	v_mfma_f32_16x16x32_bf16 v[84:87], v[164:167], v[196:199], v[84:87]
	v_mfma_f32_16x16x32_bf16 v[80:83], v[172:175], v[196:199], v[80:83]
	v_mfma_f32_16x16x32_bf16 v[68:71], v[164:167], v[204:207], v[68:71]
	v_mfma_f32_16x16x32_bf16 v[64:67], v[172:175], v[204:207], v[64:67]
	v_mfma_f32_16x16x32_bf16 v[116:119], v[168:171], v[184:187], v[116:119]
	v_mfma_f32_16x16x32_bf16 v[112:115], v[176:179], v[184:187], v[112:115]
	v_mfma_f32_16x16x32_bf16 v[100:103], v[168:171], v[192:195], v[100:103]
	v_mfma_f32_16x16x32_bf16 v[96:99], v[176:179], v[192:195], v[96:99]
	v_mfma_f32_16x16x32_bf16 v[84:87], v[168:171], v[200:203], v[84:87]
	v_mfma_f32_16x16x32_bf16 v[80:83], v[176:179], v[200:203], v[80:83]
	v_mfma_f32_16x16x32_bf16 v[68:71], v[168:171], v[208:211], v[68:71]
	v_mfma_f32_16x16x32_bf16 v[64:67], v[176:179], v[208:211], v[64:67]
	s_setprio 0
	s_barrier
	s_add_i32 s87, s57, s94
	v_lshl_add_u64 v[212:213], s[76:77], 0, v[128:129]
	s_mov_b32 m0, s87
	ds_read_b128 v[180:183], v151 offset:16384
	ds_read_b128 v[184:187], v151 offset:17408
	ds_read_b128 v[188:191], v151 offset:18432
	ds_read_b128 v[192:195], v151 offset:19456
	ds_read_b128 v[196:199], v151 offset:20480
	ds_read_b128 v[200:203], v151 offset:21504
	ds_read_b128 v[204:207], v151 offset:22528
	ds_read_b128 v[208:211], v151 offset:23552
	global_load_lds_dwordx4 v[212:213], off
	s_add_i32 m0, s87, 0x2000
	s_add_u32 s88, s76, 0x80000
	v_lshl_add_u64 v[214:215], s[76:77], 0, v[130:131]
	s_addc_u32 s89, s77, 0
	s_add_i32 s87, s81, s94
	global_load_lds_dwordx4 v[214:215], off
	v_lshl_add_u64 v[216:217], s[88:89], 0, v[128:129]
	s_mov_b32 m0, s87
	v_lshl_add_u64 v[218:219], s[78:79], 0, v[130:131]
	global_load_lds_dwordx4 v[216:217], off
	v_lshl_add_u64 v[216:217], s[88:89], 0, v[130:131]
	s_add_i32 m0, s87, 0x2000
	s_nop 0
	global_load_lds_dwordx4 v[216:217], off
	v_lshl_add_u64 v[216:217], s[78:79], 0, v[128:129]
	s_mov_b32 m0, s6
	s_nop 0
	global_load_lds_dwordx4 v[216:217], off
	s_mov_b32 m0, s7
	s_nop 0
	global_load_lds_dwordx4 v[218:219], off
	s_waitcnt vmcnt(8)
	s_waitcnt lgkmcnt(0)
	s_barrier
	s_setprio 1
	s_waitcnt lgkmcnt(0)
	v_mfma_f32_16x16x32_bf16 v[60:63], v[140:143], v[180:183], v[60:63]
	v_mfma_f32_16x16x32_bf16 v[56:59], v[156:159], v[180:183], v[56:59]
	v_mfma_f32_16x16x32_bf16 v[44:47], v[140:143], v[188:191], v[44:47]
	v_mfma_f32_16x16x32_bf16 v[40:43], v[156:159], v[188:191], v[40:43]
	v_mfma_f32_16x16x32_bf16 v[28:31], v[140:143], v[196:199], v[28:31]
	v_mfma_f32_16x16x32_bf16 v[24:27], v[156:159], v[196:199], v[24:27]
	v_mfma_f32_16x16x32_bf16 v[12:15], v[140:143], v[204:207], v[12:15]
	v_mfma_f32_16x16x32_bf16 v[8:11], v[156:159], v[204:207], v[8:11]
	v_mfma_f32_16x16x32_bf16 v[60:63], v[152:155], v[184:187], v[60:63]
	v_mfma_f32_16x16x32_bf16 v[56:59], v[160:163], v[184:187], v[56:59]
	v_mfma_f32_16x16x32_bf16 v[44:47], v[152:155], v[192:195], v[44:47]
	v_mfma_f32_16x16x32_bf16 v[40:43], v[160:163], v[192:195], v[40:43]
	v_mfma_f32_16x16x32_bf16 v[28:31], v[152:155], v[200:203], v[28:31]
	v_mfma_f32_16x16x32_bf16 v[24:27], v[160:163], v[200:203], v[24:27]
	v_mfma_f32_16x16x32_bf16 v[12:15], v[152:155], v[208:211], v[12:15]
	v_mfma_f32_16x16x32_bf16 v[8:11], v[160:163], v[208:211], v[8:11]
	v_mfma_f32_16x16x32_bf16 v[52:55], v[164:167], v[180:183], v[52:55]
	v_mfma_f32_16x16x32_bf16 v[48:51], v[172:175], v[180:183], v[48:51]
	v_mfma_f32_16x16x32_bf16 v[36:39], v[164:167], v[188:191], v[36:39]
	v_mfma_f32_16x16x32_bf16 v[32:35], v[172:175], v[188:191], v[32:35]
	v_mfma_f32_16x16x32_bf16 v[20:23], v[164:167], v[196:199], v[20:23]
	v_mfma_f32_16x16x32_bf16 v[16:19], v[172:175], v[196:199], v[16:19]
	v_mfma_f32_16x16x32_bf16 v[4:7], v[164:167], v[204:207], v[4:7]
	v_mfma_f32_16x16x32_bf16 v[0:3], v[172:175], v[204:207], v[0:3]
	v_mfma_f32_16x16x32_bf16 v[52:55], v[168:171], v[184:187], v[52:55]
	v_mfma_f32_16x16x32_bf16 v[48:51], v[176:179], v[184:187], v[48:51]
	v_mfma_f32_16x16x32_bf16 v[36:39], v[168:171], v[192:195], v[36:39]
	v_mfma_f32_16x16x32_bf16 v[32:35], v[176:179], v[192:195], v[32:35]
	v_mfma_f32_16x16x32_bf16 v[20:23], v[168:171], v[200:203], v[20:23]
	v_mfma_f32_16x16x32_bf16 v[16:19], v[176:179], v[200:203], v[16:19]
	v_mfma_f32_16x16x32_bf16 v[4:7], v[168:171], v[208:211], v[4:7]
	v_mfma_f32_16x16x32_bf16 v[0:3], v[176:179], v[208:211], v[0:3]
	s_setprio 0
	s_barrier
	s_add_i32 s87, 0, 0x18000
	s_add_i32 s88, 0, 0x1c000
	v_add_u32_e32 v160, s87, v145
	v_add_u32_e32 v176, s88, v145
	ds_read_b128 v[140:143], v160
	ds_read_b128 v[152:155], v160 offset:1024
	ds_read_b128 v[156:159], v160 offset:2048
	ds_read_b128 v[160:163], v160 offset:3072
	ds_read_b128 v[164:167], v176
	ds_read_b128 v[168:171], v176 offset:1024
	ds_read_b128 v[172:175], v176 offset:2048
	ds_read_b128 v[176:179], v176 offset:3072
	s_add_u32 s78, s78, 0x80000
	s_addc_u32 s79, s79, 0
	s_mov_b32 m0, s29
	v_lshl_add_u64 v[220:221], s[78:79], 0, v[128:129]
	ds_read_b128 v[180:183], v151 offset:32768
	ds_read_b128 v[184:187], v151 offset:33792
	ds_read_b128 v[188:191], v151 offset:34816
	ds_read_b128 v[192:195], v151 offset:35840
	ds_read_b128 v[196:199], v151 offset:36864
	ds_read_b128 v[200:203], v151 offset:37888
	ds_read_b128 v[204:207], v151 offset:38912
	ds_read_b128 v[208:211], v151 offset:39936
	global_load_lds_dwordx4 v[220:221], off
	v_lshl_add_u64 v[220:221], s[78:79], 0, v[130:131]
	s_mov_b32 m0, s30
	s_nop 0
	global_load_lds_dwordx4 v[220:221], off
	s_waitcnt vmcnt(8)
	s_waitcnt lgkmcnt(0)
	s_barrier
	s_setprio 1
	s_waitcnt lgkmcnt(0)
	v_mfma_f32_16x16x32_bf16 v[124:127], v[140:143], v[180:183], v[124:127]
	v_mfma_f32_16x16x32_bf16 v[120:123], v[156:159], v[180:183], v[120:123]
	v_mfma_f32_16x16x32_bf16 v[108:111], v[140:143], v[188:191], v[108:111]
	v_mfma_f32_16x16x32_bf16 v[104:107], v[156:159], v[188:191], v[104:107]
	v_mfma_f32_16x16x32_bf16 v[92:95], v[140:143], v[196:199], v[92:95]
	v_mfma_f32_16x16x32_bf16 v[88:91], v[156:159], v[196:199], v[88:91]
	v_mfma_f32_16x16x32_bf16 v[76:79], v[140:143], v[204:207], v[76:79]
	v_mfma_f32_16x16x32_bf16 v[72:75], v[156:159], v[204:207], v[72:75]
	v_mfma_f32_16x16x32_bf16 v[124:127], v[152:155], v[184:187], v[124:127]
	v_mfma_f32_16x16x32_bf16 v[120:123], v[160:163], v[184:187], v[120:123]
	v_mfma_f32_16x16x32_bf16 v[108:111], v[152:155], v[192:195], v[108:111]
	v_mfma_f32_16x16x32_bf16 v[104:107], v[160:163], v[192:195], v[104:107]
	v_mfma_f32_16x16x32_bf16 v[92:95], v[152:155], v[200:203], v[92:95]
	v_mfma_f32_16x16x32_bf16 v[88:91], v[160:163], v[200:203], v[88:91]
	v_mfma_f32_16x16x32_bf16 v[76:79], v[152:155], v[208:211], v[76:79]
	v_mfma_f32_16x16x32_bf16 v[72:75], v[160:163], v[208:211], v[72:75]
	v_mfma_f32_16x16x32_bf16 v[116:119], v[164:167], v[180:183], v[116:119]
	v_mfma_f32_16x16x32_bf16 v[112:115], v[172:175], v[180:183], v[112:115]
	v_mfma_f32_16x16x32_bf16 v[100:103], v[164:167], v[188:191], v[100:103]
	v_mfma_f32_16x16x32_bf16 v[96:99], v[172:175], v[188:191], v[96:99]
	v_mfma_f32_16x16x32_bf16 v[84:87], v[164:167], v[196:199], v[84:87]
	v_mfma_f32_16x16x32_bf16 v[80:83], v[172:175], v[196:199], v[80:83]
	v_mfma_f32_16x16x32_bf16 v[68:71], v[164:167], v[204:207], v[68:71]
	v_mfma_f32_16x16x32_bf16 v[64:67], v[172:175], v[204:207], v[64:67]
	v_mfma_f32_16x16x32_bf16 v[116:119], v[168:171], v[184:187], v[116:119]
	v_mfma_f32_16x16x32_bf16 v[112:115], v[176:179], v[184:187], v[112:115]
	v_mfma_f32_16x16x32_bf16 v[100:103], v[168:171], v[192:195], v[100:103]
	v_mfma_f32_16x16x32_bf16 v[96:99], v[176:179], v[192:195], v[96:99]
	v_mfma_f32_16x16x32_bf16 v[84:87], v[168:171], v[200:203], v[84:87]
	v_mfma_f32_16x16x32_bf16 v[80:83], v[176:179], v[200:203], v[80:83]
	v_mfma_f32_16x16x32_bf16 v[68:71], v[168:171], v[208:211], v[68:71]
	v_mfma_f32_16x16x32_bf16 v[64:67], v[176:179], v[208:211], v[64:67]
	s_setprio 0
	s_barrier
	s_add_i32 s78, s87, s94
	v_lshl_add_u64 v[212:213], v[212:213], 0, s[58:59]
	s_mov_b32 m0, s78
	ds_read_b128 v[180:183], v151 offset:49152
	ds_read_b128 v[184:187], v151 offset:50176
	ds_read_b128 v[188:191], v151 offset:51200
	ds_read_b128 v[192:195], v151 offset:52224
	ds_read_b128 v[196:199], v151 offset:53248
	ds_read_b128 v[200:203], v151 offset:54272
	ds_read_b128 v[204:207], v151 offset:55296
	ds_read_b128 v[208:211], v151 offset:56320
	global_load_lds_dwordx4 v[212:213], off
	s_add_i32 m0, s78, 0x2000
	s_add_u32 s76, s76, 0x80080
	v_lshl_add_u64 v[212:213], v[214:215], 0, s[58:59]
	s_addc_u32 s77, s77, 0
	s_add_i32 s78, s88, s94
	global_load_lds_dwordx4 v[212:213], off
	v_lshl_add_u64 v[212:213], s[76:77], 0, v[128:129]
	s_mov_b32 m0, s78
	s_nop 0
	global_load_lds_dwordx4 v[212:213], off
	v_lshl_add_u64 v[212:213], s[76:77], 0, v[130:131]
	s_add_i32 m0, s78, 0x2000
	s_nop 0
	global_load_lds_dwordx4 v[212:213], off
	v_lshl_add_u64 v[212:213], v[216:217], 0, s[58:59]
	s_mov_b32 m0, s34
	s_nop 0
	global_load_lds_dwordx4 v[212:213], off
	v_lshl_add_u64 v[212:213], v[218:219], 0, s[58:59]
	s_mov_b32 m0, s35
	s_nop 0
	global_load_lds_dwordx4 v[212:213], off
	s_waitcnt vmcnt(8)
	s_waitcnt lgkmcnt(0)
	s_barrier
	s_setprio 1
	s_waitcnt lgkmcnt(0)
	v_mfma_f32_16x16x32_bf16 v[60:63], v[140:143], v[180:183], v[60:63]
	v_mfma_f32_16x16x32_bf16 v[56:59], v[156:159], v[180:183], v[56:59]
	v_mfma_f32_16x16x32_bf16 v[44:47], v[140:143], v[188:191], v[44:47]
	v_mfma_f32_16x16x32_bf16 v[40:43], v[156:159], v[188:191], v[40:43]
	v_mfma_f32_16x16x32_bf16 v[28:31], v[140:143], v[196:199], v[28:31]
	v_mfma_f32_16x16x32_bf16 v[24:27], v[156:159], v[196:199], v[24:27]
	v_mfma_f32_16x16x32_bf16 v[12:15], v[140:143], v[204:207], v[12:15]
	v_mfma_f32_16x16x32_bf16 v[8:11], v[156:159], v[204:207], v[8:11]
	v_mfma_f32_16x16x32_bf16 v[60:63], v[152:155], v[184:187], v[60:63]
	v_mfma_f32_16x16x32_bf16 v[56:59], v[160:163], v[184:187], v[56:59]
	v_mfma_f32_16x16x32_bf16 v[44:47], v[152:155], v[192:195], v[44:47]
	v_mfma_f32_16x16x32_bf16 v[40:43], v[160:163], v[192:195], v[40:43]
	v_mfma_f32_16x16x32_bf16 v[28:31], v[152:155], v[200:203], v[28:31]
	v_mfma_f32_16x16x32_bf16 v[24:27], v[160:163], v[200:203], v[24:27]
	v_mfma_f32_16x16x32_bf16 v[12:15], v[152:155], v[208:211], v[12:15]
	v_mfma_f32_16x16x32_bf16 v[8:11], v[160:163], v[208:211], v[8:11]
	v_mfma_f32_16x16x32_bf16 v[52:55], v[164:167], v[180:183], v[52:55]
	v_mfma_f32_16x16x32_bf16 v[48:51], v[172:175], v[180:183], v[48:51]
	v_mfma_f32_16x16x32_bf16 v[36:39], v[164:167], v[188:191], v[36:39]
	v_mfma_f32_16x16x32_bf16 v[32:35], v[172:175], v[188:191], v[32:35]
	v_mfma_f32_16x16x32_bf16 v[20:23], v[164:167], v[196:199], v[20:23]
	v_mfma_f32_16x16x32_bf16 v[16:19], v[172:175], v[196:199], v[16:19]
	v_mfma_f32_16x16x32_bf16 v[4:7], v[164:167], v[204:207], v[4:7]
	v_mfma_f32_16x16x32_bf16 v[0:3], v[172:175], v[204:207], v[0:3]
	v_mfma_f32_16x16x32_bf16 v[52:55], v[168:171], v[184:187], v[52:55]
	v_mfma_f32_16x16x32_bf16 v[48:51], v[176:179], v[184:187], v[48:51]
	v_mfma_f32_16x16x32_bf16 v[36:39], v[168:171], v[192:195], v[36:39]
	v_mfma_f32_16x16x32_bf16 v[32:35], v[176:179], v[192:195], v[32:35]
	v_mfma_f32_16x16x32_bf16 v[20:23], v[168:171], v[200:203], v[20:23]
	v_mfma_f32_16x16x32_bf16 v[16:19], v[176:179], v[200:203], v[16:19]
	v_mfma_f32_16x16x32_bf16 v[4:7], v[168:171], v[208:211], v[4:7]
	v_mfma_f32_16x16x32_bf16 v[0:3], v[176:179], v[208:211], v[0:3]
	s_setprio 0
	s_barrier
	s_add_i32 s86, s86, 2
	s_add_u32 s74, s74, 0x100
	s_addc_u32 s75, s75, 0
	s_add_u32 s84, s84, 0x100
	s_addc_u32 s85, s85, 0
	s_cmp_gt_u32 s86, 29
	s_cbranch_scc0 .LBB0_1693
	s_and_b64 vcc, exec, s[60:61]
	s_cbranch_vccz .LBB0_1696
	s_barrier

.LBB0_1785:
	ds_read_b128 v[146:149], v155
	ds_read_b128 v[160:163], v155 offset:1024
	ds_read_b128 v[164:167], v155 offset:2048
	ds_read_b128 v[168:171], v155 offset:3072
	ds_read_b128 v[172:175], v156
	ds_read_b128 v[176:179], v156 offset:1024
	ds_read_b128 v[180:183], v156 offset:2048
	ds_read_b128 v[184:187], v156 offset:3072
	s_add_u32 s60, s72, 0xfff80080
	s_addc_u32 s61, s73, -1
	s_cmp_eq_u32 s78, 28
	s_cselect_b32 s77, s56, s61
	s_cselect_b32 s76, s57, s60
	s_cselect_b32 s75, s23, s71
	s_cselect_b32 s74, s63, s69
	v_lshl_add_u64 v[220:221], s[72:73], 0, v[138:139]
	s_add_i32 m0, s6, 0xc000
	ds_read_b128 v[188:191], v157
	ds_read_b128 v[192:195], v157 offset:1024
	ds_read_b128 v[196:199], v157 offset:2048
	ds_read_b128 v[200:203], v157 offset:3072
	ds_read_b128 v[204:207], v157 offset:4096
	ds_read_b128 v[208:211], v157 offset:5120
	ds_read_b128 v[212:215], v157 offset:6144
	ds_read_b128 v[216:219], v157 offset:7168
	global_load_lds_dwordx4 v[220:221], off
	v_lshl_add_u64 v[220:221], s[72:73], 0, v[140:141]
	s_add_i32 m0, s6, 0xe000
	s_nop 0
	global_load_lds_dwordx4 v[220:221], off
	s_waitcnt vmcnt(8)
	s_waitcnt lgkmcnt(0)
	s_barrier
	s_setprio 1
	s_waitcnt lgkmcnt(0)
	v_mfma_f32_16x16x32_bf16 v[124:127], v[146:149], v[188:191], v[124:127]
	v_mfma_f32_16x16x32_bf16 v[120:123], v[164:167], v[188:191], v[120:123]
	v_mfma_f32_16x16x32_bf16 v[108:111], v[146:149], v[196:199], v[108:111]
	v_mfma_f32_16x16x32_bf16 v[104:107], v[164:167], v[196:199], v[104:107]
	v_mfma_f32_16x16x32_bf16 v[92:95], v[146:149], v[204:207], v[92:95]
	v_mfma_f32_16x16x32_bf16 v[88:91], v[164:167], v[204:207], v[88:91]
	v_mfma_f32_16x16x32_bf16 v[76:79], v[146:149], v[212:215], v[76:79]
	v_mfma_f32_16x16x32_bf16 v[72:75], v[164:167], v[212:215], v[72:75]
	v_mfma_f32_16x16x32_bf16 v[124:127], v[160:163], v[192:195], v[124:127]
	v_mfma_f32_16x16x32_bf16 v[120:123], v[168:171], v[192:195], v[120:123]
	v_mfma_f32_16x16x32_bf16 v[108:111], v[160:163], v[200:203], v[108:111]
	v_mfma_f32_16x16x32_bf16 v[104:107], v[168:171], v[200:203], v[104:107]
	v_mfma_f32_16x16x32_bf16 v[92:95], v[160:163], v[208:211], v[92:95]
	v_mfma_f32_16x16x32_bf16 v[88:91], v[168:171], v[208:211], v[88:91]
	v_mfma_f32_16x16x32_bf16 v[76:79], v[160:163], v[216:219], v[76:79]
	v_mfma_f32_16x16x32_bf16 v[72:75], v[168:171], v[216:219], v[72:75]
	v_mfma_f32_16x16x32_bf16 v[116:119], v[172:175], v[188:191], v[116:119]
	v_mfma_f32_16x16x32_bf16 v[112:115], v[180:183], v[188:191], v[112:115]
	v_mfma_f32_16x16x32_bf16 v[100:103], v[172:175], v[196:199], v[100:103]
	v_mfma_f32_16x16x32_bf16 v[96:99], v[180:183], v[196:199], v[96:99]
	v_mfma_f32_16x16x32_bf16 v[84:87], v[172:175], v[204:207], v[84:87]
	v_mfma_f32_16x16x32_bf16 v[80:83], v[180:183], v[204:207], v[80:83]
	v_mfma_f32_16x16x32_bf16 v[68:71], v[172:175], v[212:215], v[68:71]
	v_mfma_f32_16x16x32_bf16 v[64:67], v[180:183], v[212:215], v[64:67]
	v_mfma_f32_16x16x32_bf16 v[116:119], v[176:179], v[192:195], v[116:119]
	v_mfma_f32_16x16x32_bf16 v[112:115], v[184:187], v[192:195], v[112:115]
	v_mfma_f32_16x16x32_bf16 v[100:103], v[176:179], v[200:203], v[100:103]
	v_mfma_f32_16x16x32_bf16 v[96:99], v[184:187], v[200:203], v[96:99]
	v_mfma_f32_16x16x32_bf16 v[84:87], v[176:179], v[208:211], v[84:87]
	v_mfma_f32_16x16x32_bf16 v[80:83], v[184:187], v[208:211], v[80:83]
	v_mfma_f32_16x16x32_bf16 v[68:71], v[176:179], v[216:219], v[68:71]
	v_mfma_f32_16x16x32_bf16 v[64:67], v[184:187], v[216:219], v[64:67]
	s_setprio 0
	s_barrier
	s_add_i32 s60, s35, s94
	v_lshl_add_u64 v[220:221], s[74:75], 0, v[130:131]
	s_mov_b32 m0, s60
	ds_read_b128 v[188:191], v157 offset:16384
	ds_read_b128 v[192:195], v157 offset:17408
	ds_read_b128 v[196:199], v157 offset:18432
	ds_read_b128 v[200:203], v157 offset:19456
	ds_read_b128 v[204:207], v157 offset:20480
	ds_read_b128 v[208:211], v157 offset:21504
	ds_read_b128 v[212:215], v157 offset:22528
	ds_read_b128 v[216:219], v157 offset:23552
	global_load_lds_dwordx4 v[220:221], off
	s_add_i32 m0, s60, 0x2000
	s_add_u32 s80, s74, 0x80000
	v_lshl_add_u64 v[222:223], s[74:75], 0, v[134:135]
	s_addc_u32 s81, s75, 0
	s_add_i32 s60, s46, s94
	global_load_lds_dwordx4 v[222:223], off
	v_lshl_add_u64 v[224:225], s[80:81], 0, v[130:131]
	s_mov_b32 m0, s60
	v_lshl_add_u64 v[226:227], s[76:77], 0, v[132:133]
	global_load_lds_dwordx4 v[224:225], off
	v_lshl_add_u64 v[224:225], s[80:81], 0, v[134:135]
	s_add_i32 m0, s60, 0x2000
	s_nop 0
	global_load_lds_dwordx4 v[224:225], off
	v_lshl_add_u64 v[224:225], s[76:77], 0, v[128:129]
	s_mov_b32 m0, s6
	s_nop 0
	global_load_lds_dwordx4 v[224:225], off
	s_mov_b32 m0, s7
	s_nop 0
	global_load_lds_dwordx4 v[226:227], off
	s_waitcnt vmcnt(8)
	s_waitcnt lgkmcnt(0)
	s_barrier
	s_setprio 1
	s_waitcnt lgkmcnt(0)
	v_mfma_f32_16x16x32_bf16 v[60:63], v[146:149], v[188:191], v[60:63]
	v_mfma_f32_16x16x32_bf16 v[56:59], v[164:167], v[188:191], v[56:59]
	v_mfma_f32_16x16x32_bf16 v[44:47], v[146:149], v[196:199], v[44:47]
	v_mfma_f32_16x16x32_bf16 v[40:43], v[164:167], v[196:199], v[40:43]
	v_mfma_f32_16x16x32_bf16 v[28:31], v[146:149], v[204:207], v[28:31]
	v_mfma_f32_16x16x32_bf16 v[24:27], v[164:167], v[204:207], v[24:27]
	v_mfma_f32_16x16x32_bf16 v[12:15], v[146:149], v[212:215], v[12:15]
	v_mfma_f32_16x16x32_bf16 v[8:11], v[164:167], v[212:215], v[8:11]
	v_mfma_f32_16x16x32_bf16 v[60:63], v[160:163], v[192:195], v[60:63]
	v_mfma_f32_16x16x32_bf16 v[56:59], v[168:171], v[192:195], v[56:59]
	v_mfma_f32_16x16x32_bf16 v[44:47], v[160:163], v[200:203], v[44:47]
	v_mfma_f32_16x16x32_bf16 v[40:43], v[168:171], v[200:203], v[40:43]
	v_mfma_f32_16x16x32_bf16 v[28:31], v[160:163], v[208:211], v[28:31]
	v_mfma_f32_16x16x32_bf16 v[24:27], v[168:171], v[208:211], v[24:27]
	v_mfma_f32_16x16x32_bf16 v[12:15], v[160:163], v[216:219], v[12:15]
	v_mfma_f32_16x16x32_bf16 v[8:11], v[168:171], v[216:219], v[8:11]
	v_mfma_f32_16x16x32_bf16 v[52:55], v[172:175], v[188:191], v[52:55]
	v_mfma_f32_16x16x32_bf16 v[48:51], v[180:183], v[188:191], v[48:51]
	v_mfma_f32_16x16x32_bf16 v[36:39], v[172:175], v[196:199], v[36:39]
	v_mfma_f32_16x16x32_bf16 v[32:35], v[180:183], v[196:199], v[32:35]
	v_mfma_f32_16x16x32_bf16 v[20:23], v[172:175], v[204:207], v[20:23]
	v_mfma_f32_16x16x32_bf16 v[16:19], v[180:183], v[204:207], v[16:19]
	v_mfma_f32_16x16x32_bf16 v[4:7], v[172:175], v[212:215], v[4:7]
	v_mfma_f32_16x16x32_bf16 v[0:3], v[180:183], v[212:215], v[0:3]
	v_mfma_f32_16x16x32_bf16 v[52:55], v[176:179], v[192:195], v[52:55]
	v_mfma_f32_16x16x32_bf16 v[48:51], v[184:187], v[192:195], v[48:51]
	v_mfma_f32_16x16x32_bf16 v[36:39], v[176:179], v[200:203], v[36:39]
	v_mfma_f32_16x16x32_bf16 v[32:35], v[184:187], v[200:203], v[32:35]
	v_mfma_f32_16x16x32_bf16 v[20:23], v[176:179], v[208:211], v[20:23]
	v_mfma_f32_16x16x32_bf16 v[16:19], v[184:187], v[208:211], v[16:19]
	v_mfma_f32_16x16x32_bf16 v[4:7], v[176:179], v[216:219], v[4:7]
	v_mfma_f32_16x16x32_bf16 v[0:3], v[184:187], v[216:219], v[0:3]
	s_setprio 0
	s_barrier
	s_add_i32 s60, 0, 0x18000
	v_add_u32_e32 v159, s60, v151
	s_add_i32 s61, 0, 0x1c000
	ds_read_b128 v[146:149], v159
	ds_read_b128 v[160:163], v159 offset:1024
	ds_read_b128 v[164:167], v159 offset:2048
	ds_read_b128 v[168:171], v159 offset:3072
	v_add_u32_e32 v159, s61, v151
	ds_read_b128 v[172:175], v159
	ds_read_b128 v[176:179], v159 offset:1024
	ds_read_b128 v[180:183], v159 offset:2048
	ds_read_b128 v[184:187], v159 offset:3072
	s_add_u32 s76, s76, 0x80000
	s_addc_u32 s77, s77, 0
	s_mov_b32 m0, s12
	v_lshl_add_u64 v[228:229], s[76:77], 0, v[128:129]
	ds_read_b128 v[188:191], v157 offset:32768
	ds_read_b128 v[192:195], v157 offset:33792
	ds_read_b128 v[196:199], v157 offset:34816
	ds_read_b128 v[200:203], v157 offset:35840
	ds_read_b128 v[204:207], v157 offset:36864
	ds_read_b128 v[208:211], v157 offset:37888
	ds_read_b128 v[212:215], v157 offset:38912
	ds_read_b128 v[216:219], v157 offset:39936
	global_load_lds_dwordx4 v[228:229], off
	v_lshl_add_u64 v[228:229], s[76:77], 0, v[132:133]
	s_mov_b32 m0, s13
	s_nop 0
	global_load_lds_dwordx4 v[228:229], off
	s_waitcnt vmcnt(8)
	s_waitcnt lgkmcnt(0)
	s_barrier
	s_setprio 1
	s_waitcnt lgkmcnt(0)
	v_mfma_f32_16x16x32_bf16 v[124:127], v[146:149], v[188:191], v[124:127]
	v_mfma_f32_16x16x32_bf16 v[120:123], v[164:167], v[188:191], v[120:123]
	v_mfma_f32_16x16x32_bf16 v[108:111], v[146:149], v[196:199], v[108:111]
	v_mfma_f32_16x16x32_bf16 v[104:107], v[164:167], v[196:199], v[104:107]
	v_mfma_f32_16x16x32_bf16 v[92:95], v[146:149], v[204:207], v[92:95]
	v_mfma_f32_16x16x32_bf16 v[88:91], v[164:167], v[204:207], v[88:91]
	v_mfma_f32_16x16x32_bf16 v[76:79], v[146:149], v[212:215], v[76:79]
	v_mfma_f32_16x16x32_bf16 v[72:75], v[164:167], v[212:215], v[72:75]
	v_mfma_f32_16x16x32_bf16 v[124:127], v[160:163], v[192:195], v[124:127]
	v_mfma_f32_16x16x32_bf16 v[120:123], v[168:171], v[192:195], v[120:123]
	v_mfma_f32_16x16x32_bf16 v[108:111], v[160:163], v[200:203], v[108:111]
	v_mfma_f32_16x16x32_bf16 v[104:107], v[168:171], v[200:203], v[104:107]
	v_mfma_f32_16x16x32_bf16 v[92:95], v[160:163], v[208:211], v[92:95]
	v_mfma_f32_16x16x32_bf16 v[88:91], v[168:171], v[208:211], v[88:91]
	v_mfma_f32_16x16x32_bf16 v[76:79], v[160:163], v[216:219], v[76:79]
	v_mfma_f32_16x16x32_bf16 v[72:75], v[168:171], v[216:219], v[72:75]
	v_mfma_f32_16x16x32_bf16 v[116:119], v[172:175], v[188:191], v[116:119]
	v_mfma_f32_16x16x32_bf16 v[112:115], v[180:183], v[188:191], v[112:115]
	v_mfma_f32_16x16x32_bf16 v[100:103], v[172:175], v[196:199], v[100:103]
	v_mfma_f32_16x16x32_bf16 v[96:99], v[180:183], v[196:199], v[96:99]
	v_mfma_f32_16x16x32_bf16 v[84:87], v[172:175], v[204:207], v[84:87]
	v_mfma_f32_16x16x32_bf16 v[80:83], v[180:183], v[204:207], v[80:83]
	v_mfma_f32_16x16x32_bf16 v[68:71], v[172:175], v[212:215], v[68:71]
	v_mfma_f32_16x16x32_bf16 v[64:67], v[180:183], v[212:215], v[64:67]
	v_mfma_f32_16x16x32_bf16 v[116:119], v[176:179], v[192:195], v[116:119]
	v_mfma_f32_16x16x32_bf16 v[112:115], v[184:187], v[192:195], v[112:115]
	v_mfma_f32_16x16x32_bf16 v[100:103], v[176:179], v[200:203], v[100:103]
	v_mfma_f32_16x16x32_bf16 v[96:99], v[184:187], v[200:203], v[96:99]
	v_mfma_f32_16x16x32_bf16 v[84:87], v[176:179], v[208:211], v[84:87]
	v_mfma_f32_16x16x32_bf16 v[80:83], v[184:187], v[208:211], v[80:83]
	v_mfma_f32_16x16x32_bf16 v[68:71], v[176:179], v[216:219], v[68:71]
	v_mfma_f32_16x16x32_bf16 v[64:67], v[184:187], v[216:219], v[64:67]
	s_setprio 0
	s_barrier
	s_add_i32 s60, s60, s94
	v_lshl_add_u64 v[220:221], v[220:221], 0, s[20:21]
	s_mov_b32 m0, s60
	ds_read_b128 v[188:191], v157 offset:49152
	ds_read_b128 v[192:195], v157 offset:50176
	ds_read_b128 v[196:199], v157 offset:51200
	ds_read_b128 v[200:203], v157 offset:52224
	ds_read_b128 v[204:207], v157 offset:53248
	ds_read_b128 v[208:211], v157 offset:54272
	ds_read_b128 v[212:215], v157 offset:55296
	ds_read_b128 v[216:219], v157 offset:56320
	global_load_lds_dwordx4 v[220:221], off
	s_add_i32 m0, s60, 0x2000
	s_add_u32 s74, s74, 0x80080
	v_lshl_add_u64 v[220:221], v[222:223], 0, s[20:21]
	s_addc_u32 s75, s75, 0
	s_add_i32 s60, s61, s94
	global_load_lds_dwordx4 v[220:221], off
	v_lshl_add_u64 v[220:221], s[74:75], 0, v[130:131]
	s_mov_b32 m0, s60
	s_nop 0
	global_load_lds_dwordx4 v[220:221], off
	v_lshl_add_u64 v[220:221], s[74:75], 0, v[134:135]
	s_add_i32 m0, s60, 0x2000
	s_nop 0
	global_load_lds_dwordx4 v[220:221], off
	v_lshl_add_u64 v[220:221], v[224:225], 0, s[20:21]
	s_mov_b32 m0, s30
	s_nop 0
	global_load_lds_dwordx4 v[220:221], off
	v_lshl_add_u64 v[220:221], v[226:227], 0, s[20:21]
	s_mov_b32 m0, s34
	s_nop 0
	global_load_lds_dwordx4 v[220:221], off
	s_waitcnt vmcnt(8)
	s_waitcnt lgkmcnt(0)
	s_barrier
	s_setprio 1
	s_waitcnt lgkmcnt(0)
	v_mfma_f32_16x16x32_bf16 v[60:63], v[146:149], v[188:191], v[60:63]
	v_mfma_f32_16x16x32_bf16 v[56:59], v[164:167], v[188:191], v[56:59]
	v_mfma_f32_16x16x32_bf16 v[44:47], v[146:149], v[196:199], v[44:47]
	v_mfma_f32_16x16x32_bf16 v[40:43], v[164:167], v[196:199], v[40:43]
	v_mfma_f32_16x16x32_bf16 v[28:31], v[146:149], v[204:207], v[28:31]
	v_mfma_f32_16x16x32_bf16 v[24:27], v[164:167], v[204:207], v[24:27]
	v_mfma_f32_16x16x32_bf16 v[12:15], v[146:149], v[212:215], v[12:15]
	v_mfma_f32_16x16x32_bf16 v[8:11], v[164:167], v[212:215], v[8:11]
	v_mfma_f32_16x16x32_bf16 v[60:63], v[160:163], v[192:195], v[60:63]
	v_mfma_f32_16x16x32_bf16 v[56:59], v[168:171], v[192:195], v[56:59]
	v_mfma_f32_16x16x32_bf16 v[44:47], v[160:163], v[200:203], v[44:47]
	v_mfma_f32_16x16x32_bf16 v[40:43], v[168:171], v[200:203], v[40:43]
	v_mfma_f32_16x16x32_bf16 v[28:31], v[160:163], v[208:211], v[28:31]
	v_mfma_f32_16x16x32_bf16 v[24:27], v[168:171], v[208:211], v[24:27]
	v_mfma_f32_16x16x32_bf16 v[12:15], v[160:163], v[216:219], v[12:15]
	v_mfma_f32_16x16x32_bf16 v[8:11], v[168:171], v[216:219], v[8:11]
	v_mfma_f32_16x16x32_bf16 v[52:55], v[172:175], v[188:191], v[52:55]
	v_mfma_f32_16x16x32_bf16 v[48:51], v[180:183], v[188:191], v[48:51]
	v_mfma_f32_16x16x32_bf16 v[36:39], v[172:175], v[196:199], v[36:39]
	v_mfma_f32_16x16x32_bf16 v[32:35], v[180:183], v[196:199], v[32:35]
	v_mfma_f32_16x16x32_bf16 v[20:23], v[172:175], v[204:207], v[20:23]
	v_mfma_f32_16x16x32_bf16 v[16:19], v[180:183], v[204:207], v[16:19]
	v_mfma_f32_16x16x32_bf16 v[4:7], v[172:175], v[212:215], v[4:7]
	v_mfma_f32_16x16x32_bf16 v[0:3], v[180:183], v[212:215], v[0:3]
	v_mfma_f32_16x16x32_bf16 v[52:55], v[176:179], v[192:195], v[52:55]
	v_mfma_f32_16x16x32_bf16 v[48:51], v[184:187], v[192:195], v[48:51]
	v_mfma_f32_16x16x32_bf16 v[36:39], v[176:179], v[200:203], v[36:39]
	v_mfma_f32_16x16x32_bf16 v[32:35], v[184:187], v[200:203], v[32:35]
	v_mfma_f32_16x16x32_bf16 v[20:23], v[176:179], v[208:211], v[20:23]
	v_mfma_f32_16x16x32_bf16 v[16:19], v[184:187], v[208:211], v[16:19]
	v_mfma_f32_16x16x32_bf16 v[4:7], v[176:179], v[216:219], v[4:7]
	v_mfma_f32_16x16x32_bf16 v[0:3], v[184:187], v[216:219], v[0:3]
	s_setprio 0
	s_barrier
	s_add_i32 s78, s78, 2
	s_add_u32 s72, s72, 0x100
	s_addc_u32 s73, s73, 0
	s_add_u32 s69, s69, 0x100
	s_addc_u32 s71, s71, 0
	s_cmp_gt_u32 s78, 29
	s_cbranch_scc0 .LBB0_1785
	s_and_b64 vcc, exec, s[58:59]
	s_cbranch_vccz .LBB0_1788
	s_barrier

.LBB0_1897:
	ds_read_b128 v[140:143], v149
	ds_read_b128 v[152:155], v149 offset:1024
	ds_read_b128 v[156:159], v149 offset:2048
	ds_read_b128 v[160:163], v149 offset:3072
	ds_read_b128 v[164:167], v150
	ds_read_b128 v[168:171], v150 offset:1024
	ds_read_b128 v[172:175], v150 offset:2048
	ds_read_b128 v[176:179], v150 offset:3072
	s_add_u32 s60, s72, 0xffe00080
	s_addc_u32 s61, s73, -1
	s_cmpk_eq_i32 s79, 0x7c
	s_cselect_b32 s77, s56, s61
	s_cselect_b32 s76, s57, s60
	s_cselect_b32 s75, s63, s78
	s_cselect_b32 s74, s65, s71
	v_lshl_add_u64 v[212:213], s[72:73], 0, v[132:133]
	s_add_i32 m0, s6, 0xc000
	ds_read_b128 v[180:183], v151
	ds_read_b128 v[184:187], v151 offset:1024
	ds_read_b128 v[188:191], v151 offset:2048
	ds_read_b128 v[192:195], v151 offset:3072
	ds_read_b128 v[196:199], v151 offset:4096
	ds_read_b128 v[200:203], v151 offset:5120
	ds_read_b128 v[204:207], v151 offset:6144
	ds_read_b128 v[208:211], v151 offset:7168
	global_load_lds_dwordx4 v[212:213], off
	v_lshl_add_u64 v[212:213], s[72:73], 0, v[134:135]
	s_add_i32 m0, s6, 0xe000
	s_nop 0
	global_load_lds_dwordx4 v[212:213], off
	s_waitcnt vmcnt(8)
	s_waitcnt lgkmcnt(0)
	s_barrier
	s_setprio 1
	s_waitcnt lgkmcnt(0)
	v_mfma_f32_16x16x32_bf16 v[124:127], v[140:143], v[180:183], v[124:127]
	v_mfma_f32_16x16x32_bf16 v[120:123], v[156:159], v[180:183], v[120:123]
	v_mfma_f32_16x16x32_bf16 v[108:111], v[140:143], v[188:191], v[108:111]
	v_mfma_f32_16x16x32_bf16 v[104:107], v[156:159], v[188:191], v[104:107]
	v_mfma_f32_16x16x32_bf16 v[92:95], v[140:143], v[196:199], v[92:95]
	v_mfma_f32_16x16x32_bf16 v[88:91], v[156:159], v[196:199], v[88:91]
	v_mfma_f32_16x16x32_bf16 v[76:79], v[140:143], v[204:207], v[76:79]
	v_mfma_f32_16x16x32_bf16 v[72:75], v[156:159], v[204:207], v[72:75]
	v_mfma_f32_16x16x32_bf16 v[124:127], v[152:155], v[184:187], v[124:127]
	v_mfma_f32_16x16x32_bf16 v[120:123], v[160:163], v[184:187], v[120:123]
	v_mfma_f32_16x16x32_bf16 v[108:111], v[152:155], v[192:195], v[108:111]
	v_mfma_f32_16x16x32_bf16 v[104:107], v[160:163], v[192:195], v[104:107]
	v_mfma_f32_16x16x32_bf16 v[92:95], v[152:155], v[200:203], v[92:95]
	v_mfma_f32_16x16x32_bf16 v[88:91], v[160:163], v[200:203], v[88:91]
	v_mfma_f32_16x16x32_bf16 v[76:79], v[152:155], v[208:211], v[76:79]
	v_mfma_f32_16x16x32_bf16 v[72:75], v[160:163], v[208:211], v[72:75]
	v_mfma_f32_16x16x32_bf16 v[116:119], v[164:167], v[180:183], v[116:119]
	v_mfma_f32_16x16x32_bf16 v[112:115], v[172:175], v[180:183], v[112:115]
	v_mfma_f32_16x16x32_bf16 v[100:103], v[164:167], v[188:191], v[100:103]
	v_mfma_f32_16x16x32_bf16 v[96:99], v[172:175], v[188:191], v[96:99]
	v_mfma_f32_16x16x32_bf16 v[84:87], v[164:167], v[196:199], v[84:87]
	v_mfma_f32_16x16x32_bf16 v[80:83], v[172:175], v[196:199], v[80:83]
	v_mfma_f32_16x16x32_bf16 v[68:71], v[164:167], v[204:207], v[68:71]
	v_mfma_f32_16x16x32_bf16 v[64:67], v[172:175], v[204:207], v[64:67]
	v_mfma_f32_16x16x32_bf16 v[116:119], v[168:171], v[184:187], v[116:119]
	v_mfma_f32_16x16x32_bf16 v[112:115], v[176:179], v[184:187], v[112:115]
	v_mfma_f32_16x16x32_bf16 v[100:103], v[168:171], v[192:195], v[100:103]
	v_mfma_f32_16x16x32_bf16 v[96:99], v[176:179], v[192:195], v[96:99]
	v_mfma_f32_16x16x32_bf16 v[84:87], v[168:171], v[200:203], v[84:87]
	v_mfma_f32_16x16x32_bf16 v[80:83], v[176:179], v[200:203], v[80:83]
	v_mfma_f32_16x16x32_bf16 v[68:71], v[168:171], v[208:211], v[68:71]
	v_mfma_f32_16x16x32_bf16 v[64:67], v[176:179], v[208:211], v[64:67]
	s_setprio 0
	s_barrier
	s_add_i32 s60, s34, s94
	v_lshl_add_u64 v[212:213], s[74:75], 0, v[128:129]
	s_mov_b32 m0, s60
	ds_read_b128 v[180:183], v151 offset:16384
	ds_read_b128 v[184:187], v151 offset:17408
	ds_read_b128 v[188:191], v151 offset:18432
	ds_read_b128 v[192:195], v151 offset:19456
	ds_read_b128 v[196:199], v151 offset:20480
	ds_read_b128 v[200:203], v151 offset:21504
	ds_read_b128 v[204:207], v151 offset:22528
	ds_read_b128 v[208:211], v151 offset:23552
	global_load_lds_dwordx4 v[212:213], off
	s_add_i32 m0, s60, 0x2000
	s_add_u32 s80, s74, 0x200000
	v_lshl_add_u64 v[214:215], s[74:75], 0, v[130:131]
	s_addc_u32 s81, s75, 0
	s_add_i32 s60, s35, s94
	global_load_lds_dwordx4 v[214:215], off
	v_lshl_add_u64 v[216:217], s[80:81], 0, v[128:129]
	s_mov_b32 m0, s60
	v_lshl_add_u64 v[218:219], s[76:77], 0, v[130:131]
	global_load_lds_dwordx4 v[216:217], off
	v_lshl_add_u64 v[216:217], s[80:81], 0, v[130:131]
	s_add_i32 m0, s60, 0x2000
	s_nop 0
	global_load_lds_dwordx4 v[216:217], off
	v_lshl_add_u64 v[216:217], s[76:77], 0, v[128:129]
	s_mov_b32 m0, s6
	s_nop 0
	global_load_lds_dwordx4 v[216:217], off
	s_mov_b32 m0, s7
	s_nop 0
	global_load_lds_dwordx4 v[218:219], off
	s_waitcnt vmcnt(8)
	s_waitcnt lgkmcnt(0)
	s_barrier
	s_setprio 1
	s_waitcnt lgkmcnt(0)
	v_mfma_f32_16x16x32_bf16 v[60:63], v[140:143], v[180:183], v[60:63]
	v_mfma_f32_16x16x32_bf16 v[56:59], v[156:159], v[180:183], v[56:59]
	v_mfma_f32_16x16x32_bf16 v[44:47], v[140:143], v[188:191], v[44:47]
	v_mfma_f32_16x16x32_bf16 v[40:43], v[156:159], v[188:191], v[40:43]
	v_mfma_f32_16x16x32_bf16 v[28:31], v[140:143], v[196:199], v[28:31]
	v_mfma_f32_16x16x32_bf16 v[24:27], v[156:159], v[196:199], v[24:27]
	v_mfma_f32_16x16x32_bf16 v[12:15], v[140:143], v[204:207], v[12:15]
	v_mfma_f32_16x16x32_bf16 v[8:11], v[156:159], v[204:207], v[8:11]
	v_mfma_f32_16x16x32_bf16 v[60:63], v[152:155], v[184:187], v[60:63]
	v_mfma_f32_16x16x32_bf16 v[56:59], v[160:163], v[184:187], v[56:59]
	v_mfma_f32_16x16x32_bf16 v[44:47], v[152:155], v[192:195], v[44:47]
	v_mfma_f32_16x16x32_bf16 v[40:43], v[160:163], v[192:195], v[40:43]
	v_mfma_f32_16x16x32_bf16 v[28:31], v[152:155], v[200:203], v[28:31]
	v_mfma_f32_16x16x32_bf16 v[24:27], v[160:163], v[200:203], v[24:27]
	v_mfma_f32_16x16x32_bf16 v[12:15], v[152:155], v[208:211], v[12:15]
	v_mfma_f32_16x16x32_bf16 v[8:11], v[160:163], v[208:211], v[8:11]
	v_mfma_f32_16x16x32_bf16 v[52:55], v[164:167], v[180:183], v[52:55]
	v_mfma_f32_16x16x32_bf16 v[48:51], v[172:175], v[180:183], v[48:51]
	v_mfma_f32_16x16x32_bf16 v[36:39], v[164:167], v[188:191], v[36:39]
	v_mfma_f32_16x16x32_bf16 v[32:35], v[172:175], v[188:191], v[32:35]
	v_mfma_f32_16x16x32_bf16 v[20:23], v[164:167], v[196:199], v[20:23]
	v_mfma_f32_16x16x32_bf16 v[16:19], v[172:175], v[196:199], v[16:19]
	v_mfma_f32_16x16x32_bf16 v[4:7], v[164:167], v[204:207], v[4:7]
	v_mfma_f32_16x16x32_bf16 v[0:3], v[172:175], v[204:207], v[0:3]
	v_mfma_f32_16x16x32_bf16 v[52:55], v[168:171], v[184:187], v[52:55]
	v_mfma_f32_16x16x32_bf16 v[48:51], v[176:179], v[184:187], v[48:51]
	v_mfma_f32_16x16x32_bf16 v[36:39], v[168:171], v[192:195], v[36:39]
	v_mfma_f32_16x16x32_bf16 v[32:35], v[176:179], v[192:195], v[32:35]
	v_mfma_f32_16x16x32_bf16 v[20:23], v[168:171], v[200:203], v[20:23]
	v_mfma_f32_16x16x32_bf16 v[16:19], v[176:179], v[200:203], v[16:19]
	v_mfma_f32_16x16x32_bf16 v[4:7], v[168:171], v[208:211], v[4:7]
	v_mfma_f32_16x16x32_bf16 v[0:3], v[176:179], v[208:211], v[0:3]
	s_setprio 0
	s_barrier
	s_add_i32 s60, 0, 0x18000
	s_add_i32 s61, 0, 0x1c000
	v_add_u32_e32 v160, s60, v145
	v_add_u32_e32 v176, s61, v145
	ds_read_b128 v[140:143], v160
	ds_read_b128 v[152:155], v160 offset:1024
	ds_read_b128 v[156:159], v160 offset:2048
	ds_read_b128 v[160:163], v160 offset:3072
	ds_read_b128 v[164:167], v176
	ds_read_b128 v[168:171], v176 offset:1024
	ds_read_b128 v[172:175], v176 offset:2048
	ds_read_b128 v[176:179], v176 offset:3072
	s_add_u32 s76, s76, 0x200000
	s_addc_u32 s77, s77, 0
	s_mov_b32 m0, s12
	v_lshl_add_u64 v[220:221], s[76:77], 0, v[128:129]
	ds_read_b128 v[180:183], v151 offset:32768
	ds_read_b128 v[184:187], v151 offset:33792
	ds_read_b128 v[188:191], v151 offset:34816
	ds_read_b128 v[192:195], v151 offset:35840
	ds_read_b128 v[196:199], v151 offset:36864
	ds_read_b128 v[200:203], v151 offset:37888
	ds_read_b128 v[204:207], v151 offset:38912
	ds_read_b128 v[208:211], v151 offset:39936
	global_load_lds_dwordx4 v[220:221], off
	v_lshl_add_u64 v[220:221], s[76:77], 0, v[130:131]
	s_mov_b32 m0, s13
	s_nop 0
	global_load_lds_dwordx4 v[220:221], off
	s_waitcnt vmcnt(8)
	s_waitcnt lgkmcnt(0)
	s_barrier
	s_setprio 1
	s_waitcnt lgkmcnt(0)
	v_mfma_f32_16x16x32_bf16 v[124:127], v[140:143], v[180:183], v[124:127]
	v_mfma_f32_16x16x32_bf16 v[120:123], v[156:159], v[180:183], v[120:123]
	v_mfma_f32_16x16x32_bf16 v[108:111], v[140:143], v[188:191], v[108:111]
	v_mfma_f32_16x16x32_bf16 v[104:107], v[156:159], v[188:191], v[104:107]
	v_mfma_f32_16x16x32_bf16 v[92:95], v[140:143], v[196:199], v[92:95]
	v_mfma_f32_16x16x32_bf16 v[88:91], v[156:159], v[196:199], v[88:91]
	v_mfma_f32_16x16x32_bf16 v[76:79], v[140:143], v[204:207], v[76:79]
	v_mfma_f32_16x16x32_bf16 v[72:75], v[156:159], v[204:207], v[72:75]
	v_mfma_f32_16x16x32_bf16 v[124:127], v[152:155], v[184:187], v[124:127]
	v_mfma_f32_16x16x32_bf16 v[120:123], v[160:163], v[184:187], v[120:123]
	v_mfma_f32_16x16x32_bf16 v[108:111], v[152:155], v[192:195], v[108:111]
	v_mfma_f32_16x16x32_bf16 v[104:107], v[160:163], v[192:195], v[104:107]
	v_mfma_f32_16x16x32_bf16 v[92:95], v[152:155], v[200:203], v[92:95]
	v_mfma_f32_16x16x32_bf16 v[88:91], v[160:163], v[200:203], v[88:91]
	v_mfma_f32_16x16x32_bf16 v[76:79], v[152:155], v[208:211], v[76:79]
	v_mfma_f32_16x16x32_bf16 v[72:75], v[160:163], v[208:211], v[72:75]
	v_mfma_f32_16x16x32_bf16 v[116:119], v[164:167], v[180:183], v[116:119]
	v_mfma_f32_16x16x32_bf16 v[112:115], v[172:175], v[180:183], v[112:115]
	v_mfma_f32_16x16x32_bf16 v[100:103], v[164:167], v[188:191], v[100:103]
	v_mfma_f32_16x16x32_bf16 v[96:99], v[172:175], v[188:191], v[96:99]
	v_mfma_f32_16x16x32_bf16 v[84:87], v[164:167], v[196:199], v[84:87]
	v_mfma_f32_16x16x32_bf16 v[80:83], v[172:175], v[196:199], v[80:83]
	v_mfma_f32_16x16x32_bf16 v[68:71], v[164:167], v[204:207], v[68:71]
	v_mfma_f32_16x16x32_bf16 v[64:67], v[172:175], v[204:207], v[64:67]
	v_mfma_f32_16x16x32_bf16 v[116:119], v[168:171], v[184:187], v[116:119]
	v_mfma_f32_16x16x32_bf16 v[112:115], v[176:179], v[184:187], v[112:115]
	v_mfma_f32_16x16x32_bf16 v[100:103], v[168:171], v[192:195], v[100:103]
	v_mfma_f32_16x16x32_bf16 v[96:99], v[176:179], v[192:195], v[96:99]
	v_mfma_f32_16x16x32_bf16 v[84:87], v[168:171], v[200:203], v[84:87]
	v_mfma_f32_16x16x32_bf16 v[80:83], v[176:179], v[200:203], v[80:83]
	v_mfma_f32_16x16x32_bf16 v[68:71], v[168:171], v[208:211], v[68:71]
	v_mfma_f32_16x16x32_bf16 v[64:67], v[176:179], v[208:211], v[64:67]
	s_setprio 0
	s_barrier
	s_add_i32 s60, s60, s94
	v_lshl_add_u64 v[212:213], v[212:213], 0, s[22:23]
	s_mov_b32 m0, s60
	ds_read_b128 v[180:183], v151 offset:49152
	ds_read_b128 v[184:187], v151 offset:50176
	ds_read_b128 v[188:191], v151 offset:51200
	ds_read_b128 v[192:195], v151 offset:52224
	ds_read_b128 v[196:199], v151 offset:53248
	ds_read_b128 v[200:203], v151 offset:54272
	ds_read_b128 v[204:207], v151 offset:55296
	ds_read_b128 v[208:211], v151 offset:56320
	global_load_lds_dwordx4 v[212:213], off
	s_add_i32 m0, s60, 0x2000
	s_add_u32 s74, s74, 0x200080
	v_lshl_add_u64 v[212:213], v[214:215], 0, s[22:23]
	s_addc_u32 s75, s75, 0
	s_add_i32 s60, s61, s94
	global_load_lds_dwordx4 v[212:213], off
	v_lshl_add_u64 v[212:213], s[74:75], 0, v[128:129]
	s_mov_b32 m0, s60
	s_nop 0
	global_load_lds_dwordx4 v[212:213], off
	v_lshl_add_u64 v[212:213], s[74:75], 0, v[130:131]
	s_add_i32 m0, s60, 0x2000
	s_nop 0
	global_load_lds_dwordx4 v[212:213], off
	v_lshl_add_u64 v[212:213], v[216:217], 0, s[22:23]
	s_mov_b32 m0, s29
	s_nop 0
	global_load_lds_dwordx4 v[212:213], off
	v_lshl_add_u64 v[212:213], v[218:219], 0, s[22:23]
	s_mov_b32 m0, s30
	s_nop 0
	global_load_lds_dwordx4 v[212:213], off
	s_waitcnt vmcnt(8)
	s_waitcnt lgkmcnt(0)
	s_barrier
	s_setprio 1
	s_waitcnt lgkmcnt(0)
	v_mfma_f32_16x16x32_bf16 v[60:63], v[140:143], v[180:183], v[60:63]
	v_mfma_f32_16x16x32_bf16 v[56:59], v[156:159], v[180:183], v[56:59]
	v_mfma_f32_16x16x32_bf16 v[44:47], v[140:143], v[188:191], v[44:47]
	v_mfma_f32_16x16x32_bf16 v[40:43], v[156:159], v[188:191], v[40:43]
	v_mfma_f32_16x16x32_bf16 v[28:31], v[140:143], v[196:199], v[28:31]
	v_mfma_f32_16x16x32_bf16 v[24:27], v[156:159], v[196:199], v[24:27]
	v_mfma_f32_16x16x32_bf16 v[12:15], v[140:143], v[204:207], v[12:15]
	v_mfma_f32_16x16x32_bf16 v[8:11], v[156:159], v[204:207], v[8:11]
	v_mfma_f32_16x16x32_bf16 v[60:63], v[152:155], v[184:187], v[60:63]
	v_mfma_f32_16x16x32_bf16 v[56:59], v[160:163], v[184:187], v[56:59]
	v_mfma_f32_16x16x32_bf16 v[44:47], v[152:155], v[192:195], v[44:47]
	v_mfma_f32_16x16x32_bf16 v[40:43], v[160:163], v[192:195], v[40:43]
	v_mfma_f32_16x16x32_bf16 v[28:31], v[152:155], v[200:203], v[28:31]
	v_mfma_f32_16x16x32_bf16 v[24:27], v[160:163], v[200:203], v[24:27]
	v_mfma_f32_16x16x32_bf16 v[12:15], v[152:155], v[208:211], v[12:15]
	v_mfma_f32_16x16x32_bf16 v[8:11], v[160:163], v[208:211], v[8:11]
	v_mfma_f32_16x16x32_bf16 v[52:55], v[164:167], v[180:183], v[52:55]
	v_mfma_f32_16x16x32_bf16 v[48:51], v[172:175], v[180:183], v[48:51]
	v_mfma_f32_16x16x32_bf16 v[36:39], v[164:167], v[188:191], v[36:39]
	v_mfma_f32_16x16x32_bf16 v[32:35], v[172:175], v[188:191], v[32:35]
	v_mfma_f32_16x16x32_bf16 v[20:23], v[164:167], v[196:199], v[20:23]
	v_mfma_f32_16x16x32_bf16 v[16:19], v[172:175], v[196:199], v[16:19]
	v_mfma_f32_16x16x32_bf16 v[4:7], v[164:167], v[204:207], v[4:7]
	v_mfma_f32_16x16x32_bf16 v[0:3], v[172:175], v[204:207], v[0:3]
	v_mfma_f32_16x16x32_bf16 v[52:55], v[168:171], v[184:187], v[52:55]
	v_mfma_f32_16x16x32_bf16 v[48:51], v[176:179], v[184:187], v[48:51]
	v_mfma_f32_16x16x32_bf16 v[36:39], v[168:171], v[192:195], v[36:39]
	v_mfma_f32_16x16x32_bf16 v[32:35], v[176:179], v[192:195], v[32:35]
	v_mfma_f32_16x16x32_bf16 v[20:23], v[168:171], v[200:203], v[20:23]
	v_mfma_f32_16x16x32_bf16 v[16:19], v[176:179], v[200:203], v[16:19]
	v_mfma_f32_16x16x32_bf16 v[4:7], v[168:171], v[208:211], v[4:7]
	v_mfma_f32_16x16x32_bf16 v[0:3], v[176:179], v[208:211], v[0:3]
	s_setprio 0
	s_barrier
	s_add_i32 s79, s79, 2
	s_add_u32 s72, s72, 0x100
	s_addc_u32 s73, s73, 0
	s_add_u32 s71, s71, 0x100
	s_addc_u32 s78, s78, 0
	s_cmpk_gt_u32 s79, 0x7d
	s_cbranch_scc0 .LBB0_1897
	s_and_b64 vcc, exec, s[58:59]
	s_cbranch_vccz .LBB0_1900
	s_barrier

.LBB0_2128:
	ds_read_b128 v[148:151], v179
	ds_read_b128 v[152:155], v179 offset:1024
	ds_read_b128 v[156:159], v179 offset:2048
	ds_read_b128 v[160:163], v179 offset:3072
	ds_read_b128 v[164:167], v180
	ds_read_b128 v[168:171], v180 offset:1024
	ds_read_b128 v[184:187], v180 offset:2048
	ds_read_b128 v[188:191], v180 offset:3072
	s_add_u32 s60, s84, 0xfff80080
	s_addc_u32 s61, s85, -1
	s_cmp_eq_u32 s95, 28
	s_cselect_b32 s89, s23, s61
	s_cselect_b32 s88, s79, s60
	s_cselect_b32 s87, s77, s97
	s_cselect_b32 s86, vcc_lo, vcc_hi
	v_lshl_add_u64 v[172:173], s[84:85], 0, v[140:141]
	s_add_i32 m0, s6, 0xc000
	ds_read_b128 v[192:195], v181
	ds_read_b128 v[196:199], v181 offset:1024
	ds_read_b128 v[200:203], v181 offset:2048
	ds_read_b128 v[204:207], v181 offset:3072
	ds_read_b128 v[208:211], v181 offset:4096
	ds_read_b128 v[212:215], v181 offset:5120
	ds_read_b128 v[216:219], v181 offset:6144
	ds_read_b128 v[220:223], v181 offset:7168
	global_load_lds_dwordx4 v[172:173], off
	v_lshl_add_u64 v[172:173], s[84:85], 0, v[142:143]
	s_add_i32 m0, s6, 0xe000
	s_nop 0
	global_load_lds_dwordx4 v[172:173], off
	s_waitcnt vmcnt(8)
	s_waitcnt lgkmcnt(0)
	s_barrier
	s_setprio 1
	s_waitcnt lgkmcnt(0)
	v_mfma_f32_16x16x32_bf16 v[124:127], v[148:151], v[192:195], v[124:127]
	v_mfma_f32_16x16x32_bf16 v[120:123], v[156:159], v[192:195], v[120:123]
	v_mfma_f32_16x16x32_bf16 v[108:111], v[148:151], v[200:203], v[108:111]
	v_mfma_f32_16x16x32_bf16 v[104:107], v[156:159], v[200:203], v[104:107]
	v_mfma_f32_16x16x32_bf16 v[92:95], v[148:151], v[208:211], v[92:95]
	v_mfma_f32_16x16x32_bf16 v[88:91], v[156:159], v[208:211], v[88:91]
	v_mfma_f32_16x16x32_bf16 v[76:79], v[148:151], v[216:219], v[76:79]
	v_mfma_f32_16x16x32_bf16 v[72:75], v[156:159], v[216:219], v[72:75]
	v_mfma_f32_16x16x32_bf16 v[124:127], v[152:155], v[196:199], v[124:127]
	v_mfma_f32_16x16x32_bf16 v[120:123], v[160:163], v[196:199], v[120:123]
	v_mfma_f32_16x16x32_bf16 v[108:111], v[152:155], v[204:207], v[108:111]
	v_mfma_f32_16x16x32_bf16 v[104:107], v[160:163], v[204:207], v[104:107]
	v_mfma_f32_16x16x32_bf16 v[92:95], v[152:155], v[212:215], v[92:95]
	v_mfma_f32_16x16x32_bf16 v[88:91], v[160:163], v[212:215], v[88:91]
	v_mfma_f32_16x16x32_bf16 v[76:79], v[152:155], v[220:223], v[76:79]
	v_mfma_f32_16x16x32_bf16 v[72:75], v[160:163], v[220:223], v[72:75]
	v_mfma_f32_16x16x32_bf16 v[116:119], v[164:167], v[192:195], v[116:119]
	v_mfma_f32_16x16x32_bf16 v[112:115], v[184:187], v[192:195], v[112:115]
	v_mfma_f32_16x16x32_bf16 v[100:103], v[164:167], v[200:203], v[100:103]
	v_mfma_f32_16x16x32_bf16 v[96:99], v[184:187], v[200:203], v[96:99]
	v_mfma_f32_16x16x32_bf16 v[84:87], v[164:167], v[208:211], v[84:87]
	v_mfma_f32_16x16x32_bf16 v[80:83], v[184:187], v[208:211], v[80:83]
	v_mfma_f32_16x16x32_bf16 v[68:71], v[164:167], v[216:219], v[68:71]
	v_mfma_f32_16x16x32_bf16 v[64:67], v[184:187], v[216:219], v[64:67]
	v_mfma_f32_16x16x32_bf16 v[116:119], v[168:171], v[196:199], v[116:119]
	v_mfma_f32_16x16x32_bf16 v[112:115], v[188:191], v[196:199], v[112:115]
	v_mfma_f32_16x16x32_bf16 v[100:103], v[168:171], v[204:207], v[100:103]
	v_mfma_f32_16x16x32_bf16 v[96:99], v[188:191], v[204:207], v[96:99]
	v_mfma_f32_16x16x32_bf16 v[84:87], v[168:171], v[212:215], v[84:87]
	v_mfma_f32_16x16x32_bf16 v[80:83], v[188:191], v[212:215], v[80:83]
	v_mfma_f32_16x16x32_bf16 v[68:71], v[168:171], v[220:223], v[68:71]
	v_mfma_f32_16x16x32_bf16 v[64:67], v[188:191], v[220:223], v[64:67]
	s_setprio 0
	s_barrier
	s_add_i32 s60, s12, s94
	v_lshl_add_u64 v[172:173], s[86:87], 0, v[130:131]
	s_mov_b32 m0, s60
	ds_read_b128 v[192:195], v181 offset:16384
	ds_read_b128 v[196:199], v181 offset:17408
	ds_read_b128 v[200:203], v181 offset:18432
	ds_read_b128 v[204:207], v181 offset:19456
	ds_read_b128 v[208:211], v181 offset:20480
	ds_read_b128 v[212:215], v181 offset:21504
	ds_read_b128 v[216:219], v181 offset:22528
	ds_read_b128 v[220:223], v181 offset:23552
	global_load_lds_dwordx4 v[172:173], off
	s_add_i32 m0, s60, 0x2000
	s_add_u32 s60, s86, 0x80000
	v_lshl_add_u64 v[224:225], s[86:87], 0, v[134:135]
	s_addc_u32 s61, s87, 0
	s_add_i32 s96, s13, s94
	global_load_lds_dwordx4 v[224:225], off
	v_lshl_add_u64 v[226:227], s[60:61], 0, v[130:131]
	s_mov_b32 m0, s96
	v_lshl_add_u64 v[228:229], s[88:89], 0, v[132:133]
	global_load_lds_dwordx4 v[226:227], off
	v_lshl_add_u64 v[226:227], s[60:61], 0, v[134:135]
	s_add_i32 m0, s96, 0x2000
	s_nop 0
	global_load_lds_dwordx4 v[226:227], off
	v_lshl_add_u64 v[226:227], s[88:89], 0, v[128:129]
	s_mov_b32 m0, s6
	s_nop 0
	global_load_lds_dwordx4 v[226:227], off
	s_mov_b32 m0, s7
	s_nop 0
	global_load_lds_dwordx4 v[228:229], off
	s_waitcnt vmcnt(8)
	s_waitcnt lgkmcnt(0)
	s_barrier
	s_setprio 1
	s_waitcnt lgkmcnt(0)
	v_mfma_f32_16x16x32_bf16 v[60:63], v[148:151], v[192:195], v[60:63]
	v_mfma_f32_16x16x32_bf16 v[56:59], v[156:159], v[192:195], v[56:59]
	v_mfma_f32_16x16x32_bf16 v[44:47], v[148:151], v[200:203], v[44:47]
	v_mfma_f32_16x16x32_bf16 v[40:43], v[156:159], v[200:203], v[40:43]
	v_mfma_f32_16x16x32_bf16 v[28:31], v[148:151], v[208:211], v[28:31]
	v_mfma_f32_16x16x32_bf16 v[24:27], v[156:159], v[208:211], v[24:27]
	v_mfma_f32_16x16x32_bf16 v[12:15], v[148:151], v[216:219], v[12:15]
	v_mfma_f32_16x16x32_bf16 v[8:11], v[156:159], v[216:219], v[8:11]
	v_mfma_f32_16x16x32_bf16 v[60:63], v[152:155], v[196:199], v[60:63]
	v_mfma_f32_16x16x32_bf16 v[56:59], v[160:163], v[196:199], v[56:59]
	v_mfma_f32_16x16x32_bf16 v[44:47], v[152:155], v[204:207], v[44:47]
	v_mfma_f32_16x16x32_bf16 v[40:43], v[160:163], v[204:207], v[40:43]
	v_mfma_f32_16x16x32_bf16 v[28:31], v[152:155], v[212:215], v[28:31]
	v_mfma_f32_16x16x32_bf16 v[24:27], v[160:163], v[212:215], v[24:27]
	v_mfma_f32_16x16x32_bf16 v[12:15], v[152:155], v[220:223], v[12:15]
	v_mfma_f32_16x16x32_bf16 v[8:11], v[160:163], v[220:223], v[8:11]
	v_mfma_f32_16x16x32_bf16 v[52:55], v[164:167], v[192:195], v[52:55]
	v_mfma_f32_16x16x32_bf16 v[48:51], v[184:187], v[192:195], v[48:51]
	v_mfma_f32_16x16x32_bf16 v[36:39], v[164:167], v[200:203], v[36:39]
	v_mfma_f32_16x16x32_bf16 v[32:35], v[184:187], v[200:203], v[32:35]
	v_mfma_f32_16x16x32_bf16 v[20:23], v[164:167], v[208:211], v[20:23]
	v_mfma_f32_16x16x32_bf16 v[16:19], v[184:187], v[208:211], v[16:19]
	v_mfma_f32_16x16x32_bf16 v[4:7], v[164:167], v[216:219], v[4:7]
	v_mfma_f32_16x16x32_bf16 v[0:3], v[184:187], v[216:219], v[0:3]
	v_mfma_f32_16x16x32_bf16 v[52:55], v[168:171], v[196:199], v[52:55]
	v_mfma_f32_16x16x32_bf16 v[48:51], v[188:191], v[196:199], v[48:51]
	v_mfma_f32_16x16x32_bf16 v[36:39], v[168:171], v[204:207], v[36:39]
	v_mfma_f32_16x16x32_bf16 v[32:35], v[188:191], v[204:207], v[32:35]
	v_mfma_f32_16x16x32_bf16 v[20:23], v[168:171], v[212:215], v[20:23]
	v_mfma_f32_16x16x32_bf16 v[16:19], v[188:191], v[212:215], v[16:19]
	v_mfma_f32_16x16x32_bf16 v[4:7], v[168:171], v[220:223], v[4:7]
	v_mfma_f32_16x16x32_bf16 v[0:3], v[188:191], v[220:223], v[0:3]
	s_setprio 0
	s_barrier
	s_add_i32 s96, 0, 0x18000
	v_add_u32_e32 v136, s96, v175
	s_add_i32 s8, 0, 0x1c000
	ds_read_b128 v[148:151], v136
	ds_read_b128 v[152:155], v136 offset:1024
	ds_read_b128 v[156:159], v136 offset:2048
	ds_read_b128 v[160:163], v136 offset:3072
	v_add_u32_e32 v136, s8, v175
	ds_read_b128 v[164:167], v136
	ds_read_b128 v[168:171], v136 offset:1024
	ds_read_b128 v[184:187], v136 offset:2048
	ds_read_b128 v[188:191], v136 offset:3072
	s_add_u32 s60, s88, 0x80000
	s_addc_u32 s61, s89, 0
	s_mov_b32 m0, s34
	v_lshl_add_u64 v[230:231], s[60:61], 0, v[128:129]
	ds_read_b128 v[192:195], v181 offset:32768
	ds_read_b128 v[196:199], v181 offset:33792
	ds_read_b128 v[200:203], v181 offset:34816
	ds_read_b128 v[204:207], v181 offset:35840
	ds_read_b128 v[208:211], v181 offset:36864
	ds_read_b128 v[212:215], v181 offset:37888
	ds_read_b128 v[216:219], v181 offset:38912
	ds_read_b128 v[220:223], v181 offset:39936
	global_load_lds_dwordx4 v[230:231], off
	v_lshl_add_u64 v[230:231], s[60:61], 0, v[132:133]
	s_mov_b32 m0, s46
	s_nop 0
	global_load_lds_dwordx4 v[230:231], off
	s_waitcnt vmcnt(8)
	s_waitcnt lgkmcnt(0)
	s_barrier
	s_setprio 1
	s_waitcnt lgkmcnt(0)
	v_mfma_f32_16x16x32_bf16 v[124:127], v[148:151], v[192:195], v[124:127]
	v_mfma_f32_16x16x32_bf16 v[120:123], v[156:159], v[192:195], v[120:123]
	v_mfma_f32_16x16x32_bf16 v[108:111], v[148:151], v[200:203], v[108:111]
	v_mfma_f32_16x16x32_bf16 v[104:107], v[156:159], v[200:203], v[104:107]
	v_mfma_f32_16x16x32_bf16 v[92:95], v[148:151], v[208:211], v[92:95]
	v_mfma_f32_16x16x32_bf16 v[88:91], v[156:159], v[208:211], v[88:91]
	v_mfma_f32_16x16x32_bf16 v[76:79], v[148:151], v[216:219], v[76:79]
	v_mfma_f32_16x16x32_bf16 v[72:75], v[156:159], v[216:219], v[72:75]
	v_mfma_f32_16x16x32_bf16 v[124:127], v[152:155], v[196:199], v[124:127]
	v_mfma_f32_16x16x32_bf16 v[120:123], v[160:163], v[196:199], v[120:123]
	v_mfma_f32_16x16x32_bf16 v[108:111], v[152:155], v[204:207], v[108:111]
	v_mfma_f32_16x16x32_bf16 v[104:107], v[160:163], v[204:207], v[104:107]
	v_mfma_f32_16x16x32_bf16 v[92:95], v[152:155], v[212:215], v[92:95]
	v_mfma_f32_16x16x32_bf16 v[88:91], v[160:163], v[212:215], v[88:91]
	v_mfma_f32_16x16x32_bf16 v[76:79], v[152:155], v[220:223], v[76:79]
	v_mfma_f32_16x16x32_bf16 v[72:75], v[160:163], v[220:223], v[72:75]
	v_mfma_f32_16x16x32_bf16 v[116:119], v[164:167], v[192:195], v[116:119]
	v_mfma_f32_16x16x32_bf16 v[112:115], v[184:187], v[192:195], v[112:115]
	v_mfma_f32_16x16x32_bf16 v[100:103], v[164:167], v[200:203], v[100:103]
	v_mfma_f32_16x16x32_bf16 v[96:99], v[184:187], v[200:203], v[96:99]
	v_mfma_f32_16x16x32_bf16 v[84:87], v[164:167], v[208:211], v[84:87]
	v_mfma_f32_16x16x32_bf16 v[80:83], v[184:187], v[208:211], v[80:83]
	v_mfma_f32_16x16x32_bf16 v[68:71], v[164:167], v[216:219], v[68:71]
	v_mfma_f32_16x16x32_bf16 v[64:67], v[184:187], v[216:219], v[64:67]
	v_mfma_f32_16x16x32_bf16 v[116:119], v[168:171], v[196:199], v[116:119]
	v_mfma_f32_16x16x32_bf16 v[112:115], v[188:191], v[196:199], v[112:115]
	v_mfma_f32_16x16x32_bf16 v[100:103], v[168:171], v[204:207], v[100:103]
	v_mfma_f32_16x16x32_bf16 v[96:99], v[188:191], v[204:207], v[96:99]
	v_mfma_f32_16x16x32_bf16 v[84:87], v[168:171], v[212:215], v[84:87]
	v_mfma_f32_16x16x32_bf16 v[80:83], v[188:191], v[212:215], v[80:83]
	v_mfma_f32_16x16x32_bf16 v[68:71], v[168:171], v[220:223], v[68:71]
	v_mfma_f32_16x16x32_bf16 v[64:67], v[188:191], v[220:223], v[64:67]
	s_setprio 0
	s_barrier
	s_add_i32 s9, s96, s94
	v_lshl_add_u64 v[172:173], v[172:173], 0, s[74:75]
	s_mov_b32 m0, s9
	ds_read_b128 v[192:195], v181 offset:49152
	ds_read_b128 v[196:199], v181 offset:50176
	ds_read_b128 v[200:203], v181 offset:51200
	ds_read_b128 v[204:207], v181 offset:52224
	ds_read_b128 v[208:211], v181 offset:53248
	ds_read_b128 v[212:215], v181 offset:54272
	ds_read_b128 v[216:219], v181 offset:55296
	ds_read_b128 v[220:223], v181 offset:56320
	global_load_lds_dwordx4 v[172:173], off
	s_add_i32 m0, s9, 0x2000
	s_add_u32 s60, s86, 0x80080
	v_lshl_add_u64 v[172:173], v[224:225], 0, s[74:75]
	s_addc_u32 s61, s87, 0
	s_add_i32 s8, s8, s94
	global_load_lds_dwordx4 v[172:173], off
	v_lshl_add_u64 v[172:173], s[60:61], 0, v[130:131]
	s_mov_b32 m0, s8
	s_nop 0
	global_load_lds_dwordx4 v[172:173], off
	v_lshl_add_u64 v[172:173], s[60:61], 0, v[134:135]
	s_add_i32 m0, s8, 0x2000
	s_nop 0
	global_load_lds_dwordx4 v[172:173], off
	v_lshl_add_u64 v[172:173], v[226:227], 0, s[74:75]
	s_mov_b32 m0, s56
	s_nop 0
	global_load_lds_dwordx4 v[172:173], off
	v_lshl_add_u64 v[172:173], v[228:229], 0, s[74:75]
	s_mov_b32 m0, s57
	s_nop 0
	global_load_lds_dwordx4 v[172:173], off
	s_waitcnt vmcnt(8)
	s_waitcnt lgkmcnt(0)
	s_barrier
	s_setprio 1
	s_waitcnt lgkmcnt(0)
	v_mfma_f32_16x16x32_bf16 v[60:63], v[148:151], v[192:195], v[60:63]
	v_mfma_f32_16x16x32_bf16 v[56:59], v[156:159], v[192:195], v[56:59]
	v_mfma_f32_16x16x32_bf16 v[44:47], v[148:151], v[200:203], v[44:47]
	v_mfma_f32_16x16x32_bf16 v[40:43], v[156:159], v[200:203], v[40:43]
	v_mfma_f32_16x16x32_bf16 v[28:31], v[148:151], v[208:211], v[28:31]
	v_mfma_f32_16x16x32_bf16 v[24:27], v[156:159], v[208:211], v[24:27]
	v_mfma_f32_16x16x32_bf16 v[12:15], v[148:151], v[216:219], v[12:15]
	v_mfma_f32_16x16x32_bf16 v[8:11], v[156:159], v[216:219], v[8:11]
	v_mfma_f32_16x16x32_bf16 v[60:63], v[152:155], v[196:199], v[60:63]
	v_mfma_f32_16x16x32_bf16 v[56:59], v[160:163], v[196:199], v[56:59]
	v_mfma_f32_16x16x32_bf16 v[44:47], v[152:155], v[204:207], v[44:47]
	v_mfma_f32_16x16x32_bf16 v[40:43], v[160:163], v[204:207], v[40:43]
	v_mfma_f32_16x16x32_bf16 v[28:31], v[152:155], v[212:215], v[28:31]
	v_mfma_f32_16x16x32_bf16 v[24:27], v[160:163], v[212:215], v[24:27]
	v_mfma_f32_16x16x32_bf16 v[12:15], v[152:155], v[220:223], v[12:15]
	v_mfma_f32_16x16x32_bf16 v[8:11], v[160:163], v[220:223], v[8:11]
	v_mfma_f32_16x16x32_bf16 v[52:55], v[164:167], v[192:195], v[52:55]
	v_mfma_f32_16x16x32_bf16 v[48:51], v[184:187], v[192:195], v[48:51]
	v_mfma_f32_16x16x32_bf16 v[36:39], v[164:167], v[200:203], v[36:39]
	v_mfma_f32_16x16x32_bf16 v[32:35], v[184:187], v[200:203], v[32:35]
	v_mfma_f32_16x16x32_bf16 v[20:23], v[164:167], v[208:211], v[20:23]
	v_mfma_f32_16x16x32_bf16 v[16:19], v[184:187], v[208:211], v[16:19]
	v_mfma_f32_16x16x32_bf16 v[4:7], v[164:167], v[216:219], v[4:7]
	v_mfma_f32_16x16x32_bf16 v[0:3], v[184:187], v[216:219], v[0:3]
	v_mfma_f32_16x16x32_bf16 v[52:55], v[168:171], v[196:199], v[52:55]
	v_mfma_f32_16x16x32_bf16 v[48:51], v[188:191], v[196:199], v[48:51]
	v_mfma_f32_16x16x32_bf16 v[36:39], v[168:171], v[204:207], v[36:39]
	v_mfma_f32_16x16x32_bf16 v[32:35], v[188:191], v[204:207], v[32:35]
	v_mfma_f32_16x16x32_bf16 v[20:23], v[168:171], v[212:215], v[20:23]
	v_mfma_f32_16x16x32_bf16 v[16:19], v[188:191], v[212:215], v[16:19]
	v_mfma_f32_16x16x32_bf16 v[4:7], v[168:171], v[220:223], v[4:7]
	v_mfma_f32_16x16x32_bf16 v[0:3], v[188:191], v[220:223], v[0:3]
	s_setprio 0
	s_barrier
	s_add_i32 s95, s95, 2
	s_add_u32 s84, s84, 0x100
	s_addc_u32 s85, s85, 0
	s_add_u32 vcc_hi, vcc_hi, 0x100
	s_addc_u32 s97, s97, 0
	s_cmp_gt_u32 s95, 29
	s_cbranch_scc0 .LBB0_2128
	s_and_b64 vcc, exec, s[58:59]
	s_cbranch_vccz .LBB0_2131
	s_barrier

.LBB0_2459:
	ds_read_b128 v[148:151], v163
	ds_read_b128 v[152:155], v163 offset:1024
	ds_read_b128 v[168:171], v163 offset:2048
	ds_read_b128 v[172:175], v163 offset:3072
	ds_read_b128 v[176:179], v164
	ds_read_b128 v[180:183], v164 offset:1024
	ds_read_b128 v[184:187], v164 offset:2048
	ds_read_b128 v[188:191], v164 offset:3072
	s_add_u32 s16, s70, 0x100
	s_addc_u32 s17, s71, 0
	s_cmp_eq_u32 s86, 8
	s_cselect_b32 s75, s23, s17
	s_cselect_b32 s74, s22, s16
	s_cselect_b32 s73, s49, s85
	s_cselect_b32 s72, s48, s84
	v_lshl_add_u64 v[156:157], s[70:71], 0, v[140:141]
	s_add_i32 m0, s12, 0xc000
	ds_read_b128 v[192:195], v165
	ds_read_b128 v[196:199], v165 offset:1024
	ds_read_b128 v[200:203], v165 offset:2048
	ds_read_b128 v[204:207], v165 offset:3072
	ds_read_b128 v[208:211], v165 offset:4096
	ds_read_b128 v[212:215], v165 offset:5120
	ds_read_b128 v[216:219], v165 offset:6144
	ds_read_b128 v[220:223], v165 offset:7168
	global_load_lds_dwordx4 v[156:157], off
	v_lshl_add_u64 v[156:157], s[70:71], 0, v[142:143]
	s_add_i32 m0, s12, 0xe000
	s_nop 0
	global_load_lds_dwordx4 v[156:157], off
	s_waitcnt vmcnt(8)
	s_waitcnt lgkmcnt(0)
	s_barrier
	s_setprio 1
	s_waitcnt lgkmcnt(0)
	v_mfma_f32_16x16x32_bf16 v[124:127], v[148:151], v[192:195], v[124:127]
	v_mfma_f32_16x16x32_bf16 v[120:123], v[168:171], v[192:195], v[120:123]
	v_mfma_f32_16x16x32_bf16 v[108:111], v[148:151], v[200:203], v[108:111]
	v_mfma_f32_16x16x32_bf16 v[104:107], v[168:171], v[200:203], v[104:107]
	v_mfma_f32_16x16x32_bf16 v[92:95], v[148:151], v[208:211], v[92:95]
	v_mfma_f32_16x16x32_bf16 v[88:91], v[168:171], v[208:211], v[88:91]
	v_mfma_f32_16x16x32_bf16 v[76:79], v[148:151], v[216:219], v[76:79]
	v_mfma_f32_16x16x32_bf16 v[72:75], v[168:171], v[216:219], v[72:75]
	v_mfma_f32_16x16x32_bf16 v[124:127], v[152:155], v[196:199], v[124:127]
	v_mfma_f32_16x16x32_bf16 v[120:123], v[172:175], v[196:199], v[120:123]
	v_mfma_f32_16x16x32_bf16 v[108:111], v[152:155], v[204:207], v[108:111]
	v_mfma_f32_16x16x32_bf16 v[104:107], v[172:175], v[204:207], v[104:107]
	v_mfma_f32_16x16x32_bf16 v[92:95], v[152:155], v[212:215], v[92:95]
	v_mfma_f32_16x16x32_bf16 v[88:91], v[172:175], v[212:215], v[88:91]
	v_mfma_f32_16x16x32_bf16 v[76:79], v[152:155], v[220:223], v[76:79]
	v_mfma_f32_16x16x32_bf16 v[72:75], v[172:175], v[220:223], v[72:75]
	v_mfma_f32_16x16x32_bf16 v[116:119], v[176:179], v[192:195], v[116:119]
	v_mfma_f32_16x16x32_bf16 v[112:115], v[184:187], v[192:195], v[112:115]
	v_mfma_f32_16x16x32_bf16 v[100:103], v[176:179], v[200:203], v[100:103]
	v_mfma_f32_16x16x32_bf16 v[96:99], v[184:187], v[200:203], v[96:99]
	v_mfma_f32_16x16x32_bf16 v[84:87], v[176:179], v[208:211], v[84:87]
	v_mfma_f32_16x16x32_bf16 v[80:83], v[184:187], v[208:211], v[80:83]
	v_mfma_f32_16x16x32_bf16 v[68:71], v[176:179], v[216:219], v[68:71]
	v_mfma_f32_16x16x32_bf16 v[64:67], v[184:187], v[216:219], v[64:67]
	v_mfma_f32_16x16x32_bf16 v[116:119], v[180:183], v[196:199], v[116:119]
	v_mfma_f32_16x16x32_bf16 v[112:115], v[188:191], v[196:199], v[112:115]
	v_mfma_f32_16x16x32_bf16 v[100:103], v[180:183], v[204:207], v[100:103]
	v_mfma_f32_16x16x32_bf16 v[96:99], v[188:191], v[204:207], v[96:99]
	v_mfma_f32_16x16x32_bf16 v[84:87], v[180:183], v[212:215], v[84:87]
	v_mfma_f32_16x16x32_bf16 v[80:83], v[188:191], v[212:215], v[80:83]
	v_mfma_f32_16x16x32_bf16 v[68:71], v[180:183], v[220:223], v[68:71]
	v_mfma_f32_16x16x32_bf16 v[64:67], v[188:191], v[220:223], v[64:67]
	s_setprio 0
	s_barrier
	s_add_i32 s8, s76, s94
	v_lshl_add_u64 v[156:157], s[72:73], 0, v[130:131]
	s_mov_b32 m0, s8
	ds_read_b128 v[192:195], v165 offset:16384
	ds_read_b128 v[196:199], v165 offset:17408
	ds_read_b128 v[200:203], v165 offset:18432
	ds_read_b128 v[204:207], v165 offset:19456
	ds_read_b128 v[208:211], v165 offset:20480
	ds_read_b128 v[212:215], v165 offset:21504
	ds_read_b128 v[216:219], v165 offset:22528
	ds_read_b128 v[220:223], v165 offset:23552
	global_load_lds_dwordx4 v[156:157], off
	s_add_i32 m0, s8, 0x2000
	s_add_u32 s60, s72, 0x30000
	v_lshl_add_u64 v[224:225], s[72:73], 0, v[134:135]
	s_addc_u32 s61, s73, 0
	s_add_i32 s8, s77, s94
	global_load_lds_dwordx4 v[224:225], off
	v_lshl_add_u64 v[226:227], s[60:61], 0, v[130:131]
	s_mov_b32 m0, s8
	v_lshl_add_u64 v[228:229], s[74:75], 0, v[132:133]
	global_load_lds_dwordx4 v[226:227], off
	v_lshl_add_u64 v[226:227], s[60:61], 0, v[134:135]
	s_add_i32 m0, s8, 0x2000
	s_nop 0
	global_load_lds_dwordx4 v[226:227], off
	v_lshl_add_u64 v[226:227], s[74:75], 0, v[128:129]
	s_mov_b32 m0, s12
	s_nop 0
	global_load_lds_dwordx4 v[226:227], off
	s_mov_b32 m0, s13
	s_nop 0
	global_load_lds_dwordx4 v[228:229], off
	s_waitcnt vmcnt(8)
	s_waitcnt lgkmcnt(0)
	s_barrier
	s_setprio 1
	s_waitcnt lgkmcnt(0)
	v_mfma_f32_16x16x32_bf16 v[60:63], v[148:151], v[192:195], v[60:63]
	v_mfma_f32_16x16x32_bf16 v[56:59], v[168:171], v[192:195], v[56:59]
	v_mfma_f32_16x16x32_bf16 v[44:47], v[148:151], v[200:203], v[44:47]
	v_mfma_f32_16x16x32_bf16 v[40:43], v[168:171], v[200:203], v[40:43]
	v_mfma_f32_16x16x32_bf16 v[28:31], v[148:151], v[208:211], v[28:31]
	v_mfma_f32_16x16x32_bf16 v[24:27], v[168:171], v[208:211], v[24:27]
	v_mfma_f32_16x16x32_bf16 v[12:15], v[148:151], v[216:219], v[12:15]
	v_mfma_f32_16x16x32_bf16 v[8:11], v[168:171], v[216:219], v[8:11]
	v_mfma_f32_16x16x32_bf16 v[60:63], v[152:155], v[196:199], v[60:63]
	v_mfma_f32_16x16x32_bf16 v[56:59], v[172:175], v[196:199], v[56:59]
	v_mfma_f32_16x16x32_bf16 v[44:47], v[152:155], v[204:207], v[44:47]
	v_mfma_f32_16x16x32_bf16 v[40:43], v[172:175], v[204:207], v[40:43]
	v_mfma_f32_16x16x32_bf16 v[28:31], v[152:155], v[212:215], v[28:31]
	v_mfma_f32_16x16x32_bf16 v[24:27], v[172:175], v[212:215], v[24:27]
	v_mfma_f32_16x16x32_bf16 v[12:15], v[152:155], v[220:223], v[12:15]
	v_mfma_f32_16x16x32_bf16 v[8:11], v[172:175], v[220:223], v[8:11]
	v_mfma_f32_16x16x32_bf16 v[52:55], v[176:179], v[192:195], v[52:55]
	v_mfma_f32_16x16x32_bf16 v[48:51], v[184:187], v[192:195], v[48:51]
	v_mfma_f32_16x16x32_bf16 v[36:39], v[176:179], v[200:203], v[36:39]
	v_mfma_f32_16x16x32_bf16 v[32:35], v[184:187], v[200:203], v[32:35]
	v_mfma_f32_16x16x32_bf16 v[20:23], v[176:179], v[208:211], v[20:23]
	v_mfma_f32_16x16x32_bf16 v[16:19], v[184:187], v[208:211], v[16:19]
	v_mfma_f32_16x16x32_bf16 v[4:7], v[176:179], v[216:219], v[4:7]
	v_mfma_f32_16x16x32_bf16 v[0:3], v[184:187], v[216:219], v[0:3]
	v_mfma_f32_16x16x32_bf16 v[52:55], v[180:183], v[196:199], v[52:55]
	v_mfma_f32_16x16x32_bf16 v[48:51], v[188:191], v[196:199], v[48:51]
	v_mfma_f32_16x16x32_bf16 v[36:39], v[180:183], v[204:207], v[36:39]
	v_mfma_f32_16x16x32_bf16 v[32:35], v[188:191], v[204:207], v[32:35]
	v_mfma_f32_16x16x32_bf16 v[20:23], v[180:183], v[212:215], v[20:23]
	v_mfma_f32_16x16x32_bf16 v[16:19], v[188:191], v[212:215], v[16:19]
	v_mfma_f32_16x16x32_bf16 v[4:7], v[180:183], v[220:223], v[4:7]
	v_mfma_f32_16x16x32_bf16 v[0:3], v[188:191], v[220:223], v[0:3]
	s_setprio 0
	s_barrier
	s_add_i32 s8, 0, 0x18000
	v_add_u32_e32 v136, s8, v159
	s_add_i32 s9, 0, 0x1c000
	ds_read_b128 v[148:151], v136
	ds_read_b128 v[152:155], v136 offset:1024
	ds_read_b128 v[168:171], v136 offset:2048
	ds_read_b128 v[172:175], v136 offset:3072
	v_add_u32_e32 v136, s9, v159
	ds_read_b128 v[176:179], v136
	ds_read_b128 v[180:183], v136 offset:1024
	ds_read_b128 v[184:187], v136 offset:2048
	ds_read_b128 v[188:191], v136 offset:3072
	s_add_u32 s60, s74, 0x60000
	s_addc_u32 s61, s75, 0
	s_mov_b32 m0, s29
	v_lshl_add_u64 v[230:231], s[60:61], 0, v[128:129]
	ds_read_b128 v[192:195], v165 offset:32768
	ds_read_b128 v[196:199], v165 offset:33792
	ds_read_b128 v[200:203], v165 offset:34816
	ds_read_b128 v[204:207], v165 offset:35840
	ds_read_b128 v[208:211], v165 offset:36864
	ds_read_b128 v[212:215], v165 offset:37888
	ds_read_b128 v[216:219], v165 offset:38912
	ds_read_b128 v[220:223], v165 offset:39936
	global_load_lds_dwordx4 v[230:231], off
	v_lshl_add_u64 v[230:231], s[60:61], 0, v[132:133]
	s_mov_b32 m0, s30
	s_nop 0
	global_load_lds_dwordx4 v[230:231], off
	s_waitcnt vmcnt(8)
	s_waitcnt lgkmcnt(0)
	s_barrier
	s_setprio 1
	s_waitcnt lgkmcnt(0)
	v_mfma_f32_16x16x32_bf16 v[124:127], v[148:151], v[192:195], v[124:127]
	v_mfma_f32_16x16x32_bf16 v[120:123], v[168:171], v[192:195], v[120:123]
	v_mfma_f32_16x16x32_bf16 v[108:111], v[148:151], v[200:203], v[108:111]
	v_mfma_f32_16x16x32_bf16 v[104:107], v[168:171], v[200:203], v[104:107]
	v_mfma_f32_16x16x32_bf16 v[92:95], v[148:151], v[208:211], v[92:95]
	v_mfma_f32_16x16x32_bf16 v[88:91], v[168:171], v[208:211], v[88:91]
	v_mfma_f32_16x16x32_bf16 v[76:79], v[148:151], v[216:219], v[76:79]
	v_mfma_f32_16x16x32_bf16 v[72:75], v[168:171], v[216:219], v[72:75]
	v_mfma_f32_16x16x32_bf16 v[124:127], v[152:155], v[196:199], v[124:127]
	v_mfma_f32_16x16x32_bf16 v[120:123], v[172:175], v[196:199], v[120:123]
	v_mfma_f32_16x16x32_bf16 v[108:111], v[152:155], v[204:207], v[108:111]
	v_mfma_f32_16x16x32_bf16 v[104:107], v[172:175], v[204:207], v[104:107]
	v_mfma_f32_16x16x32_bf16 v[92:95], v[152:155], v[212:215], v[92:95]
	v_mfma_f32_16x16x32_bf16 v[88:91], v[172:175], v[212:215], v[88:91]
	v_mfma_f32_16x16x32_bf16 v[76:79], v[152:155], v[220:223], v[76:79]
	v_mfma_f32_16x16x32_bf16 v[72:75], v[172:175], v[220:223], v[72:75]
	v_mfma_f32_16x16x32_bf16 v[116:119], v[176:179], v[192:195], v[116:119]
	v_mfma_f32_16x16x32_bf16 v[112:115], v[184:187], v[192:195], v[112:115]
	v_mfma_f32_16x16x32_bf16 v[100:103], v[176:179], v[200:203], v[100:103]
	v_mfma_f32_16x16x32_bf16 v[96:99], v[184:187], v[200:203], v[96:99]
	v_mfma_f32_16x16x32_bf16 v[84:87], v[176:179], v[208:211], v[84:87]
	v_mfma_f32_16x16x32_bf16 v[80:83], v[184:187], v[208:211], v[80:83]
	v_mfma_f32_16x16x32_bf16 v[68:71], v[176:179], v[216:219], v[68:71]
	v_mfma_f32_16x16x32_bf16 v[64:67], v[184:187], v[216:219], v[64:67]
	v_mfma_f32_16x16x32_bf16 v[116:119], v[180:183], v[196:199], v[116:119]
	v_mfma_f32_16x16x32_bf16 v[112:115], v[188:191], v[196:199], v[112:115]
	v_mfma_f32_16x16x32_bf16 v[100:103], v[180:183], v[204:207], v[100:103]
	v_mfma_f32_16x16x32_bf16 v[96:99], v[188:191], v[204:207], v[96:99]
	v_mfma_f32_16x16x32_bf16 v[84:87], v[180:183], v[212:215], v[84:87]
	v_mfma_f32_16x16x32_bf16 v[80:83], v[188:191], v[212:215], v[80:83]
	v_mfma_f32_16x16x32_bf16 v[68:71], v[180:183], v[220:223], v[68:71]
	v_mfma_f32_16x16x32_bf16 v[64:67], v[188:191], v[220:223], v[64:67]
	s_setprio 0
	s_barrier
	s_add_i32 s8, s8, s94
	v_lshl_add_u64 v[156:157], v[156:157], 0, s[20:21]
	s_mov_b32 m0, s8
	ds_read_b128 v[192:195], v165 offset:49152
	ds_read_b128 v[196:199], v165 offset:50176
	ds_read_b128 v[200:203], v165 offset:51200
	ds_read_b128 v[204:207], v165 offset:52224
	ds_read_b128 v[208:211], v165 offset:53248
	ds_read_b128 v[212:215], v165 offset:54272
	ds_read_b128 v[216:219], v165 offset:55296
	ds_read_b128 v[220:223], v165 offset:56320
	global_load_lds_dwordx4 v[156:157], off
	s_add_i32 m0, s8, 0x2000
	s_add_u32 s60, s72, 0x30080
	v_lshl_add_u64 v[156:157], v[224:225], 0, s[20:21]
	s_addc_u32 s61, s73, 0
	s_add_i32 s8, s9, s94
	global_load_lds_dwordx4 v[156:157], off
	v_lshl_add_u64 v[156:157], s[60:61], 0, v[130:131]
	s_mov_b32 m0, s8
	s_nop 0
	global_load_lds_dwordx4 v[156:157], off
	v_lshl_add_u64 v[156:157], s[60:61], 0, v[134:135]
	s_add_i32 m0, s8, 0x2000
	s_nop 0
	global_load_lds_dwordx4 v[156:157], off
	v_lshl_add_u64 v[156:157], v[226:227], 0, s[20:21]
	s_mov_b32 m0, s46
	s_nop 0
	global_load_lds_dwordx4 v[156:157], off
	v_lshl_add_u64 v[156:157], v[228:229], 0, s[20:21]
	s_mov_b32 m0, s56
	s_nop 0
	global_load_lds_dwordx4 v[156:157], off
	s_waitcnt vmcnt(8)
	s_waitcnt lgkmcnt(0)
	s_barrier
	s_setprio 1
	s_waitcnt lgkmcnt(0)
	v_mfma_f32_16x16x32_bf16 v[60:63], v[148:151], v[192:195], v[60:63]
	v_mfma_f32_16x16x32_bf16 v[56:59], v[168:171], v[192:195], v[56:59]
	v_mfma_f32_16x16x32_bf16 v[44:47], v[148:151], v[200:203], v[44:47]
	v_mfma_f32_16x16x32_bf16 v[40:43], v[168:171], v[200:203], v[40:43]
	v_mfma_f32_16x16x32_bf16 v[28:31], v[148:151], v[208:211], v[28:31]
	v_mfma_f32_16x16x32_bf16 v[24:27], v[168:171], v[208:211], v[24:27]
	v_mfma_f32_16x16x32_bf16 v[12:15], v[148:151], v[216:219], v[12:15]
	v_mfma_f32_16x16x32_bf16 v[8:11], v[168:171], v[216:219], v[8:11]
	v_mfma_f32_16x16x32_bf16 v[60:63], v[152:155], v[196:199], v[60:63]
	v_mfma_f32_16x16x32_bf16 v[56:59], v[172:175], v[196:199], v[56:59]
	v_mfma_f32_16x16x32_bf16 v[44:47], v[152:155], v[204:207], v[44:47]
	v_mfma_f32_16x16x32_bf16 v[40:43], v[172:175], v[204:207], v[40:43]
	v_mfma_f32_16x16x32_bf16 v[28:31], v[152:155], v[212:215], v[28:31]
	v_mfma_f32_16x16x32_bf16 v[24:27], v[172:175], v[212:215], v[24:27]
	v_mfma_f32_16x16x32_bf16 v[12:15], v[152:155], v[220:223], v[12:15]
	v_mfma_f32_16x16x32_bf16 v[8:11], v[172:175], v[220:223], v[8:11]
	v_mfma_f32_16x16x32_bf16 v[52:55], v[176:179], v[192:195], v[52:55]
	v_mfma_f32_16x16x32_bf16 v[48:51], v[184:187], v[192:195], v[48:51]
	v_mfma_f32_16x16x32_bf16 v[36:39], v[176:179], v[200:203], v[36:39]
	v_mfma_f32_16x16x32_bf16 v[32:35], v[184:187], v[200:203], v[32:35]
	v_mfma_f32_16x16x32_bf16 v[20:23], v[176:179], v[208:211], v[20:23]
	v_mfma_f32_16x16x32_bf16 v[16:19], v[184:187], v[208:211], v[16:19]
	v_mfma_f32_16x16x32_bf16 v[4:7], v[176:179], v[216:219], v[4:7]
	v_mfma_f32_16x16x32_bf16 v[0:3], v[184:187], v[216:219], v[0:3]
	v_mfma_f32_16x16x32_bf16 v[52:55], v[180:183], v[196:199], v[52:55]
	v_mfma_f32_16x16x32_bf16 v[48:51], v[188:191], v[196:199], v[48:51]
	v_mfma_f32_16x16x32_bf16 v[36:39], v[180:183], v[204:207], v[36:39]
	v_mfma_f32_16x16x32_bf16 v[32:35], v[188:191], v[204:207], v[32:35]
	v_mfma_f32_16x16x32_bf16 v[20:23], v[180:183], v[212:215], v[20:23]
	v_mfma_f32_16x16x32_bf16 v[16:19], v[188:191], v[212:215], v[16:19]
	v_mfma_f32_16x16x32_bf16 v[4:7], v[180:183], v[220:223], v[4:7]
	v_mfma_f32_16x16x32_bf16 v[0:3], v[188:191], v[220:223], v[0:3]
	s_setprio 0
	s_barrier
	s_add_i32 s86, s86, 2
	s_add_u32 s84, s84, 0x100
	s_addc_u32 s85, s85, 0
	s_cmp_gt_u32 s86, 9
	s_mov_b64 s[70:71], s[16:17]
	s_cbranch_scc0 .LBB0_2459
	s_and_b64 vcc, exec, s[58:59]
	s_cbranch_vccz .LBB0_2462
	s_barrier

.LBB0_2535:
	ds_read_b128 v[146:149], v155
	ds_read_b128 v[160:163], v155 offset:1024
	ds_read_b128 v[164:167], v155 offset:2048
	ds_read_b128 v[168:171], v155 offset:3072
	ds_read_b128 v[172:175], v156
	ds_read_b128 v[176:179], v156 offset:1024
	ds_read_b128 v[180:183], v156 offset:2048
	ds_read_b128 v[184:187], v156 offset:3072
	s_add_u32 s16, s68, 0x100
	s_addc_u32 s17, s69, 0
	s_cmp_eq_u32 s80, 4
	s_cselect_b32 s73, s49, s17
	s_cselect_b32 s72, s48, s16
	s_cselect_b32 s71, s43, s79
	s_cselect_b32 s70, s77, s78
	v_lshl_add_u64 v[220:221], s[68:69], 0, v[138:139]
	s_add_i32 m0, s29, 0xc000
	ds_read_b128 v[188:191], v157
	ds_read_b128 v[192:195], v157 offset:1024
	ds_read_b128 v[196:199], v157 offset:2048
	ds_read_b128 v[200:203], v157 offset:3072
	ds_read_b128 v[204:207], v157 offset:4096
	ds_read_b128 v[208:211], v157 offset:5120
	ds_read_b128 v[212:215], v157 offset:6144
	ds_read_b128 v[216:219], v157 offset:7168
	global_load_lds_dwordx4 v[220:221], off
	v_lshl_add_u64 v[220:221], s[68:69], 0, v[140:141]
	s_add_i32 m0, s29, 0xe000
	s_nop 0
	global_load_lds_dwordx4 v[220:221], off
	s_waitcnt vmcnt(8)
	s_waitcnt lgkmcnt(0)
	s_barrier
	s_setprio 1
	s_waitcnt lgkmcnt(0)
	v_mfma_f32_16x16x32_bf16 v[124:127], v[146:149], v[188:191], v[124:127]
	v_mfma_f32_16x16x32_bf16 v[120:123], v[164:167], v[188:191], v[120:123]
	v_mfma_f32_16x16x32_bf16 v[108:111], v[146:149], v[196:199], v[108:111]
	v_mfma_f32_16x16x32_bf16 v[104:107], v[164:167], v[196:199], v[104:107]
	v_mfma_f32_16x16x32_bf16 v[92:95], v[146:149], v[204:207], v[92:95]
	v_mfma_f32_16x16x32_bf16 v[88:91], v[164:167], v[204:207], v[88:91]
	v_mfma_f32_16x16x32_bf16 v[76:79], v[146:149], v[212:215], v[76:79]
	v_mfma_f32_16x16x32_bf16 v[72:75], v[164:167], v[212:215], v[72:75]
	v_mfma_f32_16x16x32_bf16 v[124:127], v[160:163], v[192:195], v[124:127]
	v_mfma_f32_16x16x32_bf16 v[120:123], v[168:171], v[192:195], v[120:123]
	v_mfma_f32_16x16x32_bf16 v[108:111], v[160:163], v[200:203], v[108:111]
	v_mfma_f32_16x16x32_bf16 v[104:107], v[168:171], v[200:203], v[104:107]
	v_mfma_f32_16x16x32_bf16 v[92:95], v[160:163], v[208:211], v[92:95]
	v_mfma_f32_16x16x32_bf16 v[88:91], v[168:171], v[208:211], v[88:91]
	v_mfma_f32_16x16x32_bf16 v[76:79], v[160:163], v[216:219], v[76:79]
	v_mfma_f32_16x16x32_bf16 v[72:75], v[168:171], v[216:219], v[72:75]
	v_mfma_f32_16x16x32_bf16 v[116:119], v[172:175], v[188:191], v[116:119]
	v_mfma_f32_16x16x32_bf16 v[112:115], v[180:183], v[188:191], v[112:115]
	v_mfma_f32_16x16x32_bf16 v[100:103], v[172:175], v[196:199], v[100:103]
	v_mfma_f32_16x16x32_bf16 v[96:99], v[180:183], v[196:199], v[96:99]
	v_mfma_f32_16x16x32_bf16 v[84:87], v[172:175], v[204:207], v[84:87]
	v_mfma_f32_16x16x32_bf16 v[80:83], v[180:183], v[204:207], v[80:83]
	v_mfma_f32_16x16x32_bf16 v[68:71], v[172:175], v[212:215], v[68:71]
	v_mfma_f32_16x16x32_bf16 v[64:67], v[180:183], v[212:215], v[64:67]
	v_mfma_f32_16x16x32_bf16 v[116:119], v[176:179], v[192:195], v[116:119]
	v_mfma_f32_16x16x32_bf16 v[112:115], v[184:187], v[192:195], v[112:115]
	v_mfma_f32_16x16x32_bf16 v[100:103], v[176:179], v[200:203], v[100:103]
	v_mfma_f32_16x16x32_bf16 v[96:99], v[184:187], v[200:203], v[96:99]
	v_mfma_f32_16x16x32_bf16 v[84:87], v[176:179], v[208:211], v[84:87]
	v_mfma_f32_16x16x32_bf16 v[80:83], v[184:187], v[208:211], v[80:83]
	v_mfma_f32_16x16x32_bf16 v[68:71], v[176:179], v[216:219], v[68:71]
	v_mfma_f32_16x16x32_bf16 v[64:67], v[184:187], v[216:219], v[64:67]
	s_setprio 0
	s_barrier
	s_add_i32 s8, s67, s94
	v_lshl_add_u64 v[220:221], s[70:71], 0, v[130:131]
	s_mov_b32 m0, s8
	ds_read_b128 v[188:191], v157 offset:16384
	ds_read_b128 v[192:195], v157 offset:17408
	ds_read_b128 v[196:199], v157 offset:18432
	ds_read_b128 v[200:203], v157 offset:19456
	ds_read_b128 v[204:207], v157 offset:20480
	ds_read_b128 v[208:211], v157 offset:21504
	ds_read_b128 v[212:215], v157 offset:22528
	ds_read_b128 v[216:219], v157 offset:23552
	global_load_lds_dwordx4 v[220:221], off
	s_add_i32 m0, s8, 0x2000
	s_add_u32 s60, s70, 0x20000
	v_lshl_add_u64 v[222:223], s[70:71], 0, v[134:135]
	s_addc_u32 s61, s71, 0
	s_add_i32 s8, s74, s94
	global_load_lds_dwordx4 v[222:223], off
	v_lshl_add_u64 v[224:225], s[60:61], 0, v[130:131]
	s_mov_b32 m0, s8
	v_lshl_add_u64 v[226:227], s[72:73], 0, v[132:133]
	global_load_lds_dwordx4 v[224:225], off
	v_lshl_add_u64 v[224:225], s[60:61], 0, v[134:135]
	s_add_i32 m0, s8, 0x2000
	s_nop 0
	global_load_lds_dwordx4 v[224:225], off
	v_lshl_add_u64 v[224:225], s[72:73], 0, v[128:129]
	s_mov_b32 m0, s29
	s_nop 0
	global_load_lds_dwordx4 v[224:225], off
	s_mov_b32 m0, s30
	s_nop 0
	global_load_lds_dwordx4 v[226:227], off
	s_waitcnt vmcnt(8)
	s_waitcnt lgkmcnt(0)
	s_barrier
	s_setprio 1
	s_waitcnt lgkmcnt(0)
	v_mfma_f32_16x16x32_bf16 v[60:63], v[146:149], v[188:191], v[60:63]
	v_mfma_f32_16x16x32_bf16 v[56:59], v[164:167], v[188:191], v[56:59]
	v_mfma_f32_16x16x32_bf16 v[44:47], v[146:149], v[196:199], v[44:47]
	v_mfma_f32_16x16x32_bf16 v[40:43], v[164:167], v[196:199], v[40:43]
	v_mfma_f32_16x16x32_bf16 v[28:31], v[146:149], v[204:207], v[28:31]
	v_mfma_f32_16x16x32_bf16 v[24:27], v[164:167], v[204:207], v[24:27]
	v_mfma_f32_16x16x32_bf16 v[12:15], v[146:149], v[212:215], v[12:15]
	v_mfma_f32_16x16x32_bf16 v[8:11], v[164:167], v[212:215], v[8:11]
	v_mfma_f32_16x16x32_bf16 v[60:63], v[160:163], v[192:195], v[60:63]
	v_mfma_f32_16x16x32_bf16 v[56:59], v[168:171], v[192:195], v[56:59]
	v_mfma_f32_16x16x32_bf16 v[44:47], v[160:163], v[200:203], v[44:47]
	v_mfma_f32_16x16x32_bf16 v[40:43], v[168:171], v[200:203], v[40:43]
	v_mfma_f32_16x16x32_bf16 v[28:31], v[160:163], v[208:211], v[28:31]
	v_mfma_f32_16x16x32_bf16 v[24:27], v[168:171], v[208:211], v[24:27]
	v_mfma_f32_16x16x32_bf16 v[12:15], v[160:163], v[216:219], v[12:15]
	v_mfma_f32_16x16x32_bf16 v[8:11], v[168:171], v[216:219], v[8:11]
	v_mfma_f32_16x16x32_bf16 v[52:55], v[172:175], v[188:191], v[52:55]
	v_mfma_f32_16x16x32_bf16 v[48:51], v[180:183], v[188:191], v[48:51]
	v_mfma_f32_16x16x32_bf16 v[36:39], v[172:175], v[196:199], v[36:39]
	v_mfma_f32_16x16x32_bf16 v[32:35], v[180:183], v[196:199], v[32:35]
	v_mfma_f32_16x16x32_bf16 v[20:23], v[172:175], v[204:207], v[20:23]
	v_mfma_f32_16x16x32_bf16 v[16:19], v[180:183], v[204:207], v[16:19]
	v_mfma_f32_16x16x32_bf16 v[4:7], v[172:175], v[212:215], v[4:7]
	v_mfma_f32_16x16x32_bf16 v[0:3], v[180:183], v[212:215], v[0:3]
	v_mfma_f32_16x16x32_bf16 v[52:55], v[176:179], v[192:195], v[52:55]
	v_mfma_f32_16x16x32_bf16 v[48:51], v[184:187], v[192:195], v[48:51]
	v_mfma_f32_16x16x32_bf16 v[36:39], v[176:179], v[200:203], v[36:39]
	v_mfma_f32_16x16x32_bf16 v[32:35], v[184:187], v[200:203], v[32:35]
	v_mfma_f32_16x16x32_bf16 v[20:23], v[176:179], v[208:211], v[20:23]
	v_mfma_f32_16x16x32_bf16 v[16:19], v[184:187], v[208:211], v[16:19]
	v_mfma_f32_16x16x32_bf16 v[4:7], v[176:179], v[216:219], v[4:7]
	v_mfma_f32_16x16x32_bf16 v[0:3], v[184:187], v[216:219], v[0:3]
	s_setprio 0
	s_barrier
	s_add_i32 s8, 0, 0x18000
	v_add_u32_e32 v159, s8, v151
	s_add_i32 s9, 0, 0x1c000
	ds_read_b128 v[146:149], v159
	ds_read_b128 v[160:163], v159 offset:1024
	ds_read_b128 v[164:167], v159 offset:2048
	ds_read_b128 v[168:171], v159 offset:3072
	v_add_u32_e32 v159, s9, v151
	ds_read_b128 v[172:175], v159
	ds_read_b128 v[176:179], v159 offset:1024
	ds_read_b128 v[180:183], v159 offset:2048
	ds_read_b128 v[184:187], v159 offset:3072
	s_add_u32 s60, s72, 0x60000
	s_addc_u32 s61, s73, 0
	s_mov_b32 m0, s34
	v_lshl_add_u64 v[228:229], s[60:61], 0, v[128:129]
	ds_read_b128 v[188:191], v157 offset:32768
	ds_read_b128 v[192:195], v157 offset:33792
	ds_read_b128 v[196:199], v157 offset:34816
	ds_read_b128 v[200:203], v157 offset:35840
	ds_read_b128 v[204:207], v157 offset:36864
	ds_read_b128 v[208:211], v157 offset:37888
	ds_read_b128 v[212:215], v157 offset:38912
	ds_read_b128 v[216:219], v157 offset:39936
	global_load_lds_dwordx4 v[228:229], off
	v_lshl_add_u64 v[228:229], s[60:61], 0, v[132:133]
	s_mov_b32 m0, s35
	s_nop 0
	global_load_lds_dwordx4 v[228:229], off
	s_waitcnt vmcnt(8)
	s_waitcnt lgkmcnt(0)
	s_barrier
	s_setprio 1
	s_waitcnt lgkmcnt(0)
	v_mfma_f32_16x16x32_bf16 v[124:127], v[146:149], v[188:191], v[124:127]
	v_mfma_f32_16x16x32_bf16 v[120:123], v[164:167], v[188:191], v[120:123]
	v_mfma_f32_16x16x32_bf16 v[108:111], v[146:149], v[196:199], v[108:111]
	v_mfma_f32_16x16x32_bf16 v[104:107], v[164:167], v[196:199], v[104:107]
	v_mfma_f32_16x16x32_bf16 v[92:95], v[146:149], v[204:207], v[92:95]
	v_mfma_f32_16x16x32_bf16 v[88:91], v[164:167], v[204:207], v[88:91]
	v_mfma_f32_16x16x32_bf16 v[76:79], v[146:149], v[212:215], v[76:79]
	v_mfma_f32_16x16x32_bf16 v[72:75], v[164:167], v[212:215], v[72:75]
	v_mfma_f32_16x16x32_bf16 v[124:127], v[160:163], v[192:195], v[124:127]
	v_mfma_f32_16x16x32_bf16 v[120:123], v[168:171], v[192:195], v[120:123]
	v_mfma_f32_16x16x32_bf16 v[108:111], v[160:163], v[200:203], v[108:111]
	v_mfma_f32_16x16x32_bf16 v[104:107], v[168:171], v[200:203], v[104:107]
	v_mfma_f32_16x16x32_bf16 v[92:95], v[160:163], v[208:211], v[92:95]
	v_mfma_f32_16x16x32_bf16 v[88:91], v[168:171], v[208:211], v[88:91]
	v_mfma_f32_16x16x32_bf16 v[76:79], v[160:163], v[216:219], v[76:79]
	v_mfma_f32_16x16x32_bf16 v[72:75], v[168:171], v[216:219], v[72:75]
	v_mfma_f32_16x16x32_bf16 v[116:119], v[172:175], v[188:191], v[116:119]
	v_mfma_f32_16x16x32_bf16 v[112:115], v[180:183], v[188:191], v[112:115]
	v_mfma_f32_16x16x32_bf16 v[100:103], v[172:175], v[196:199], v[100:103]
	v_mfma_f32_16x16x32_bf16 v[96:99], v[180:183], v[196:199], v[96:99]
	v_mfma_f32_16x16x32_bf16 v[84:87], v[172:175], v[204:207], v[84:87]
	v_mfma_f32_16x16x32_bf16 v[80:83], v[180:183], v[204:207], v[80:83]
	v_mfma_f32_16x16x32_bf16 v[68:71], v[172:175], v[212:215], v[68:71]
	v_mfma_f32_16x16x32_bf16 v[64:67], v[180:183], v[212:215], v[64:67]
	v_mfma_f32_16x16x32_bf16 v[116:119], v[176:179], v[192:195], v[116:119]
	v_mfma_f32_16x16x32_bf16 v[112:115], v[184:187], v[192:195], v[112:115]
	v_mfma_f32_16x16x32_bf16 v[100:103], v[176:179], v[200:203], v[100:103]
	v_mfma_f32_16x16x32_bf16 v[96:99], v[184:187], v[200:203], v[96:99]
	v_mfma_f32_16x16x32_bf16 v[84:87], v[176:179], v[208:211], v[84:87]
	v_mfma_f32_16x16x32_bf16 v[80:83], v[184:187], v[208:211], v[80:83]
	v_mfma_f32_16x16x32_bf16 v[68:71], v[176:179], v[216:219], v[68:71]
	v_mfma_f32_16x16x32_bf16 v[64:67], v[184:187], v[216:219], v[64:67]
	s_setprio 0
	s_barrier
	s_add_i32 s8, s8, s94
	v_lshl_add_u64 v[220:221], v[220:221], 0, s[22:23]
	s_mov_b32 m0, s8
	ds_read_b128 v[188:191], v157 offset:49152
	ds_read_b128 v[192:195], v157 offset:50176
	ds_read_b128 v[196:199], v157 offset:51200
	ds_read_b128 v[200:203], v157 offset:52224
	ds_read_b128 v[204:207], v157 offset:53248
	ds_read_b128 v[208:211], v157 offset:54272
	ds_read_b128 v[212:215], v157 offset:55296
	ds_read_b128 v[216:219], v157 offset:56320
	global_load_lds_dwordx4 v[220:221], off
	s_add_i32 m0, s8, 0x2000
	s_add_u32 s60, s70, 0x20080
	v_lshl_add_u64 v[220:221], v[222:223], 0, s[22:23]
	s_addc_u32 s61, s71, 0
	s_add_i32 s8, s9, s94
	global_load_lds_dwordx4 v[220:221], off
	v_lshl_add_u64 v[220:221], s[60:61], 0, v[130:131]
	s_mov_b32 m0, s8
	s_nop 0
	global_load_lds_dwordx4 v[220:221], off
	v_lshl_add_u64 v[220:221], s[60:61], 0, v[134:135]
	s_add_i32 m0, s8, 0x2000
	s_nop 0
	global_load_lds_dwordx4 v[220:221], off
	v_lshl_add_u64 v[220:221], v[224:225], 0, s[22:23]
	s_mov_b32 m0, s56
	s_nop 0
	global_load_lds_dwordx4 v[220:221], off
	v_lshl_add_u64 v[220:221], v[226:227], 0, s[22:23]
	s_mov_b32 m0, s57
	s_nop 0
	global_load_lds_dwordx4 v[220:221], off
	s_waitcnt vmcnt(8)
	s_waitcnt lgkmcnt(0)
	s_barrier
	s_setprio 1
	s_waitcnt lgkmcnt(0)
	v_mfma_f32_16x16x32_bf16 v[60:63], v[146:149], v[188:191], v[60:63]
	v_mfma_f32_16x16x32_bf16 v[56:59], v[164:167], v[188:191], v[56:59]
	v_mfma_f32_16x16x32_bf16 v[44:47], v[146:149], v[196:199], v[44:47]
	v_mfma_f32_16x16x32_bf16 v[40:43], v[164:167], v[196:199], v[40:43]
	v_mfma_f32_16x16x32_bf16 v[28:31], v[146:149], v[204:207], v[28:31]
	v_mfma_f32_16x16x32_bf16 v[24:27], v[164:167], v[204:207], v[24:27]
	v_mfma_f32_16x16x32_bf16 v[12:15], v[146:149], v[212:215], v[12:15]
	v_mfma_f32_16x16x32_bf16 v[8:11], v[164:167], v[212:215], v[8:11]
	v_mfma_f32_16x16x32_bf16 v[60:63], v[160:163], v[192:195], v[60:63]
	v_mfma_f32_16x16x32_bf16 v[56:59], v[168:171], v[192:195], v[56:59]
	v_mfma_f32_16x16x32_bf16 v[44:47], v[160:163], v[200:203], v[44:47]
	v_mfma_f32_16x16x32_bf16 v[40:43], v[168:171], v[200:203], v[40:43]
	v_mfma_f32_16x16x32_bf16 v[28:31], v[160:163], v[208:211], v[28:31]
	v_mfma_f32_16x16x32_bf16 v[24:27], v[168:171], v[208:211], v[24:27]
	v_mfma_f32_16x16x32_bf16 v[12:15], v[160:163], v[216:219], v[12:15]
	v_mfma_f32_16x16x32_bf16 v[8:11], v[168:171], v[216:219], v[8:11]
	v_mfma_f32_16x16x32_bf16 v[52:55], v[172:175], v[188:191], v[52:55]
	v_mfma_f32_16x16x32_bf16 v[48:51], v[180:183], v[188:191], v[48:51]
	v_mfma_f32_16x16x32_bf16 v[36:39], v[172:175], v[196:199], v[36:39]
	v_mfma_f32_16x16x32_bf16 v[32:35], v[180:183], v[196:199], v[32:35]
	v_mfma_f32_16x16x32_bf16 v[20:23], v[172:175], v[204:207], v[20:23]
	v_mfma_f32_16x16x32_bf16 v[16:19], v[180:183], v[204:207], v[16:19]
	v_mfma_f32_16x16x32_bf16 v[4:7], v[172:175], v[212:215], v[4:7]
	v_mfma_f32_16x16x32_bf16 v[0:3], v[180:183], v[212:215], v[0:3]
	v_mfma_f32_16x16x32_bf16 v[52:55], v[176:179], v[192:195], v[52:55]
	v_mfma_f32_16x16x32_bf16 v[48:51], v[184:187], v[192:195], v[48:51]
	v_mfma_f32_16x16x32_bf16 v[36:39], v[176:179], v[200:203], v[36:39]
	v_mfma_f32_16x16x32_bf16 v[32:35], v[184:187], v[200:203], v[32:35]
	v_mfma_f32_16x16x32_bf16 v[20:23], v[176:179], v[208:211], v[20:23]
	v_mfma_f32_16x16x32_bf16 v[16:19], v[184:187], v[208:211], v[16:19]
	v_mfma_f32_16x16x32_bf16 v[4:7], v[176:179], v[216:219], v[4:7]
	v_mfma_f32_16x16x32_bf16 v[0:3], v[184:187], v[216:219], v[0:3]
	s_setprio 0
	s_barrier
	s_add_i32 s80, s80, 2
	s_add_u32 s78, s78, 0x100
	s_addc_u32 s79, s79, 0
	s_cmp_gt_u32 s80, 5
	s_mov_b64 s[68:69], s[16:17]
	s_cbranch_scc0 .LBB0_2535
	s_and_b64 vcc, exec, s[58:59]
	s_cbranch_vccz .LBB0_2538
	s_barrier

.LBB0_2713:
	ds_read_b128 v[140:143], v149
	ds_read_b128 v[152:155], v149 offset:1024
	ds_read_b128 v[156:159], v149 offset:2048
	ds_read_b128 v[160:163], v149 offset:3072
	ds_read_b128 v[164:167], v150
	ds_read_b128 v[168:171], v150 offset:1024
	ds_read_b128 v[172:175], v150 offset:2048
	ds_read_b128 v[176:179], v150 offset:3072
	s_add_u32 s8, s62, 0xfff80080
	s_addc_u32 s9, s63, -1
	s_cmp_eq_u32 s72, 28
	s_cselect_b32 s67, s43, s9
	s_cselect_b32 s66, s57, s8
	s_cselect_b32 s65, s23, s71
	s_cselect_b32 s64, s69, s70
	v_lshl_add_u64 v[212:213], s[62:63], 0, v[132:133]
	s_add_i32 m0, s12, 0xc000
	ds_read_b128 v[180:183], v151
	ds_read_b128 v[184:187], v151 offset:1024
	ds_read_b128 v[188:191], v151 offset:2048
	ds_read_b128 v[192:195], v151 offset:3072
	ds_read_b128 v[196:199], v151 offset:4096
	ds_read_b128 v[200:203], v151 offset:5120
	ds_read_b128 v[204:207], v151 offset:6144
	ds_read_b128 v[208:211], v151 offset:7168
	global_load_lds_dwordx4 v[212:213], off
	v_lshl_add_u64 v[212:213], s[62:63], 0, v[134:135]
	s_add_i32 m0, s12, 0xe000
	s_nop 0
	global_load_lds_dwordx4 v[212:213], off
	s_waitcnt vmcnt(8)
	s_waitcnt lgkmcnt(0)
	s_barrier
	s_setprio 1
	s_waitcnt lgkmcnt(0)
	v_mfma_f32_16x16x32_bf16 v[124:127], v[140:143], v[180:183], v[124:127]
	v_mfma_f32_16x16x32_bf16 v[120:123], v[156:159], v[180:183], v[120:123]
	v_mfma_f32_16x16x32_bf16 v[108:111], v[140:143], v[188:191], v[108:111]
	v_mfma_f32_16x16x32_bf16 v[104:107], v[156:159], v[188:191], v[104:107]
	v_mfma_f32_16x16x32_bf16 v[92:95], v[140:143], v[196:199], v[92:95]
	v_mfma_f32_16x16x32_bf16 v[88:91], v[156:159], v[196:199], v[88:91]
	v_mfma_f32_16x16x32_bf16 v[76:79], v[140:143], v[204:207], v[76:79]
	v_mfma_f32_16x16x32_bf16 v[72:75], v[156:159], v[204:207], v[72:75]
	v_mfma_f32_16x16x32_bf16 v[124:127], v[152:155], v[184:187], v[124:127]
	v_mfma_f32_16x16x32_bf16 v[120:123], v[160:163], v[184:187], v[120:123]
	v_mfma_f32_16x16x32_bf16 v[108:111], v[152:155], v[192:195], v[108:111]
	v_mfma_f32_16x16x32_bf16 v[104:107], v[160:163], v[192:195], v[104:107]
	v_mfma_f32_16x16x32_bf16 v[92:95], v[152:155], v[200:203], v[92:95]
	v_mfma_f32_16x16x32_bf16 v[88:91], v[160:163], v[200:203], v[88:91]
	v_mfma_f32_16x16x32_bf16 v[76:79], v[152:155], v[208:211], v[76:79]
	v_mfma_f32_16x16x32_bf16 v[72:75], v[160:163], v[208:211], v[72:75]
	v_mfma_f32_16x16x32_bf16 v[116:119], v[164:167], v[180:183], v[116:119]
	v_mfma_f32_16x16x32_bf16 v[112:115], v[172:175], v[180:183], v[112:115]
	v_mfma_f32_16x16x32_bf16 v[100:103], v[164:167], v[188:191], v[100:103]
	v_mfma_f32_16x16x32_bf16 v[96:99], v[172:175], v[188:191], v[96:99]
	v_mfma_f32_16x16x32_bf16 v[84:87], v[164:167], v[196:199], v[84:87]
	v_mfma_f32_16x16x32_bf16 v[80:83], v[172:175], v[196:199], v[80:83]
	v_mfma_f32_16x16x32_bf16 v[68:71], v[164:167], v[204:207], v[68:71]
	v_mfma_f32_16x16x32_bf16 v[64:67], v[172:175], v[204:207], v[64:67]
	v_mfma_f32_16x16x32_bf16 v[116:119], v[168:171], v[184:187], v[116:119]
	v_mfma_f32_16x16x32_bf16 v[112:115], v[176:179], v[184:187], v[112:115]
	v_mfma_f32_16x16x32_bf16 v[100:103], v[168:171], v[192:195], v[100:103]
	v_mfma_f32_16x16x32_bf16 v[96:99], v[176:179], v[192:195], v[96:99]
	v_mfma_f32_16x16x32_bf16 v[84:87], v[168:171], v[200:203], v[84:87]
	v_mfma_f32_16x16x32_bf16 v[80:83], v[176:179], v[200:203], v[80:83]
	v_mfma_f32_16x16x32_bf16 v[68:71], v[168:171], v[208:211], v[68:71]
	v_mfma_f32_16x16x32_bf16 v[64:67], v[176:179], v[208:211], v[64:67]
	s_setprio 0
	s_barrier
	s_add_i32 s8, s46, s94
	v_lshl_add_u64 v[212:213], s[64:65], 0, v[128:129]
	s_mov_b32 m0, s8
	ds_read_b128 v[180:183], v151 offset:16384
	ds_read_b128 v[184:187], v151 offset:17408
	ds_read_b128 v[188:191], v151 offset:18432
	ds_read_b128 v[192:195], v151 offset:19456
	ds_read_b128 v[196:199], v151 offset:20480
	ds_read_b128 v[200:203], v151 offset:21504
	ds_read_b128 v[204:207], v151 offset:22528
	ds_read_b128 v[208:211], v151 offset:23552
	global_load_lds_dwordx4 v[212:213], off
	s_add_i32 m0, s8, 0x2000
	s_add_u32 s60, s64, 0x80000
	v_lshl_add_u64 v[214:215], s[64:65], 0, v[130:131]
	s_addc_u32 s61, s65, 0
	s_add_i32 s8, s47, s94
	global_load_lds_dwordx4 v[214:215], off
	v_lshl_add_u64 v[216:217], s[60:61], 0, v[128:129]
	s_mov_b32 m0, s8
	v_lshl_add_u64 v[218:219], s[66:67], 0, v[130:131]
	global_load_lds_dwordx4 v[216:217], off
	v_lshl_add_u64 v[216:217], s[60:61], 0, v[130:131]
	s_add_i32 m0, s8, 0x2000
	s_nop 0
	global_load_lds_dwordx4 v[216:217], off
	v_lshl_add_u64 v[216:217], s[66:67], 0, v[128:129]
	s_mov_b32 m0, s12
	s_nop 0
	global_load_lds_dwordx4 v[216:217], off
	s_mov_b32 m0, s13
	s_nop 0
	global_load_lds_dwordx4 v[218:219], off
	s_waitcnt vmcnt(8)
	s_waitcnt lgkmcnt(0)
	s_barrier
	s_setprio 1
	s_waitcnt lgkmcnt(0)
	v_mfma_f32_16x16x32_bf16 v[60:63], v[140:143], v[180:183], v[60:63]
	v_mfma_f32_16x16x32_bf16 v[56:59], v[156:159], v[180:183], v[56:59]
	v_mfma_f32_16x16x32_bf16 v[44:47], v[140:143], v[188:191], v[44:47]
	v_mfma_f32_16x16x32_bf16 v[40:43], v[156:159], v[188:191], v[40:43]
	v_mfma_f32_16x16x32_bf16 v[28:31], v[140:143], v[196:199], v[28:31]
	v_mfma_f32_16x16x32_bf16 v[24:27], v[156:159], v[196:199], v[24:27]
	v_mfma_f32_16x16x32_bf16 v[12:15], v[140:143], v[204:207], v[12:15]
	v_mfma_f32_16x16x32_bf16 v[8:11], v[156:159], v[204:207], v[8:11]
	v_mfma_f32_16x16x32_bf16 v[60:63], v[152:155], v[184:187], v[60:63]
	v_mfma_f32_16x16x32_bf16 v[56:59], v[160:163], v[184:187], v[56:59]
	v_mfma_f32_16x16x32_bf16 v[44:47], v[152:155], v[192:195], v[44:47]
	v_mfma_f32_16x16x32_bf16 v[40:43], v[160:163], v[192:195], v[40:43]
	v_mfma_f32_16x16x32_bf16 v[28:31], v[152:155], v[200:203], v[28:31]
	v_mfma_f32_16x16x32_bf16 v[24:27], v[160:163], v[200:203], v[24:27]
	v_mfma_f32_16x16x32_bf16 v[12:15], v[152:155], v[208:211], v[12:15]
	v_mfma_f32_16x16x32_bf16 v[8:11], v[160:163], v[208:211], v[8:11]
	v_mfma_f32_16x16x32_bf16 v[52:55], v[164:167], v[180:183], v[52:55]
	v_mfma_f32_16x16x32_bf16 v[48:51], v[172:175], v[180:183], v[48:51]
	v_mfma_f32_16x16x32_bf16 v[36:39], v[164:167], v[188:191], v[36:39]
	v_mfma_f32_16x16x32_bf16 v[32:35], v[172:175], v[188:191], v[32:35]
	v_mfma_f32_16x16x32_bf16 v[20:23], v[164:167], v[196:199], v[20:23]
	v_mfma_f32_16x16x32_bf16 v[16:19], v[172:175], v[196:199], v[16:19]
	v_mfma_f32_16x16x32_bf16 v[4:7], v[164:167], v[204:207], v[4:7]
	v_mfma_f32_16x16x32_bf16 v[0:3], v[172:175], v[204:207], v[0:3]
	v_mfma_f32_16x16x32_bf16 v[52:55], v[168:171], v[184:187], v[52:55]
	v_mfma_f32_16x16x32_bf16 v[48:51], v[176:179], v[184:187], v[48:51]
	v_mfma_f32_16x16x32_bf16 v[36:39], v[168:171], v[192:195], v[36:39]
	v_mfma_f32_16x16x32_bf16 v[32:35], v[176:179], v[192:195], v[32:35]
	v_mfma_f32_16x16x32_bf16 v[20:23], v[168:171], v[200:203], v[20:23]
	v_mfma_f32_16x16x32_bf16 v[16:19], v[176:179], v[200:203], v[16:19]
	v_mfma_f32_16x16x32_bf16 v[4:7], v[168:171], v[208:211], v[4:7]
	v_mfma_f32_16x16x32_bf16 v[0:3], v[176:179], v[208:211], v[0:3]
	s_setprio 0
	s_barrier
	s_add_i32 s8, 0, 0x18000
	s_add_i32 s9, 0, 0x1c000
	v_add_u32_e32 v160, s8, v145
	v_add_u32_e32 v176, s9, v145
	ds_read_b128 v[140:143], v160
	ds_read_b128 v[152:155], v160 offset:1024
	ds_read_b128 v[156:159], v160 offset:2048
	ds_read_b128 v[160:163], v160 offset:3072
	ds_read_b128 v[164:167], v176
	ds_read_b128 v[168:171], v176 offset:1024
	ds_read_b128 v[172:175], v176 offset:2048
	ds_read_b128 v[176:179], v176 offset:3072
	s_add_u32 s60, s66, 0x80000
	s_addc_u32 s61, s67, 0
	s_mov_b32 m0, s29
	v_lshl_add_u64 v[220:221], s[60:61], 0, v[128:129]
	ds_read_b128 v[180:183], v151 offset:32768
	ds_read_b128 v[184:187], v151 offset:33792
	ds_read_b128 v[188:191], v151 offset:34816
	ds_read_b128 v[192:195], v151 offset:35840
	ds_read_b128 v[196:199], v151 offset:36864
	ds_read_b128 v[200:203], v151 offset:37888
	ds_read_b128 v[204:207], v151 offset:38912
	ds_read_b128 v[208:211], v151 offset:39936
	global_load_lds_dwordx4 v[220:221], off
	v_lshl_add_u64 v[220:221], s[60:61], 0, v[130:131]
	s_mov_b32 m0, s30
	s_nop 0
	global_load_lds_dwordx4 v[220:221], off
	s_waitcnt vmcnt(8)
	s_waitcnt lgkmcnt(0)
	s_barrier
	s_setprio 1
	s_waitcnt lgkmcnt(0)
	v_mfma_f32_16x16x32_bf16 v[124:127], v[140:143], v[180:183], v[124:127]
	v_mfma_f32_16x16x32_bf16 v[120:123], v[156:159], v[180:183], v[120:123]
	v_mfma_f32_16x16x32_bf16 v[108:111], v[140:143], v[188:191], v[108:111]
	v_mfma_f32_16x16x32_bf16 v[104:107], v[156:159], v[188:191], v[104:107]
	v_mfma_f32_16x16x32_bf16 v[92:95], v[140:143], v[196:199], v[92:95]
	v_mfma_f32_16x16x32_bf16 v[88:91], v[156:159], v[196:199], v[88:91]
	v_mfma_f32_16x16x32_bf16 v[76:79], v[140:143], v[204:207], v[76:79]
	v_mfma_f32_16x16x32_bf16 v[72:75], v[156:159], v[204:207], v[72:75]
	v_mfma_f32_16x16x32_bf16 v[124:127], v[152:155], v[184:187], v[124:127]
	v_mfma_f32_16x16x32_bf16 v[120:123], v[160:163], v[184:187], v[120:123]
	v_mfma_f32_16x16x32_bf16 v[108:111], v[152:155], v[192:195], v[108:111]
	v_mfma_f32_16x16x32_bf16 v[104:107], v[160:163], v[192:195], v[104:107]
	v_mfma_f32_16x16x32_bf16 v[92:95], v[152:155], v[200:203], v[92:95]
	v_mfma_f32_16x16x32_bf16 v[88:91], v[160:163], v[200:203], v[88:91]
	v_mfma_f32_16x16x32_bf16 v[76:79], v[152:155], v[208:211], v[76:79]
	v_mfma_f32_16x16x32_bf16 v[72:75], v[160:163], v[208:211], v[72:75]
	v_mfma_f32_16x16x32_bf16 v[116:119], v[164:167], v[180:183], v[116:119]
	v_mfma_f32_16x16x32_bf16 v[112:115], v[172:175], v[180:183], v[112:115]
	v_mfma_f32_16x16x32_bf16 v[100:103], v[164:167], v[188:191], v[100:103]
	v_mfma_f32_16x16x32_bf16 v[96:99], v[172:175], v[188:191], v[96:99]
	v_mfma_f32_16x16x32_bf16 v[84:87], v[164:167], v[196:199], v[84:87]
	v_mfma_f32_16x16x32_bf16 v[80:83], v[172:175], v[196:199], v[80:83]
	v_mfma_f32_16x16x32_bf16 v[68:71], v[164:167], v[204:207], v[68:71]
	v_mfma_f32_16x16x32_bf16 v[64:67], v[172:175], v[204:207], v[64:67]
	v_mfma_f32_16x16x32_bf16 v[116:119], v[168:171], v[184:187], v[116:119]
	v_mfma_f32_16x16x32_bf16 v[112:115], v[176:179], v[184:187], v[112:115]
	v_mfma_f32_16x16x32_bf16 v[100:103], v[168:171], v[192:195], v[100:103]
	v_mfma_f32_16x16x32_bf16 v[96:99], v[176:179], v[192:195], v[96:99]
	v_mfma_f32_16x16x32_bf16 v[84:87], v[168:171], v[200:203], v[84:87]
	v_mfma_f32_16x16x32_bf16 v[80:83], v[176:179], v[200:203], v[80:83]
	v_mfma_f32_16x16x32_bf16 v[68:71], v[168:171], v[208:211], v[68:71]
	v_mfma_f32_16x16x32_bf16 v[64:67], v[176:179], v[208:211], v[64:67]
	s_setprio 0
	s_barrier
	s_add_i32 s8, s8, s94
	v_lshl_add_u64 v[212:213], v[212:213], 0, s[20:21]
	s_mov_b32 m0, s8
	ds_read_b128 v[180:183], v151 offset:49152
	ds_read_b128 v[184:187], v151 offset:50176
	ds_read_b128 v[188:191], v151 offset:51200
	ds_read_b128 v[192:195], v151 offset:52224
	ds_read_b128 v[196:199], v151 offset:53248
	ds_read_b128 v[200:203], v151 offset:54272
	ds_read_b128 v[204:207], v151 offset:55296
	ds_read_b128 v[208:211], v151 offset:56320
	global_load_lds_dwordx4 v[212:213], off
	s_add_i32 m0, s8, 0x2000
	s_add_u32 s60, s64, 0x80080
	v_lshl_add_u64 v[212:213], v[214:215], 0, s[20:21]
	s_addc_u32 s61, s65, 0
	s_add_i32 s8, s9, s94
	global_load_lds_dwordx4 v[212:213], off
	v_lshl_add_u64 v[212:213], s[60:61], 0, v[128:129]
	s_mov_b32 m0, s8
	s_nop 0
	global_load_lds_dwordx4 v[212:213], off
	v_lshl_add_u64 v[212:213], s[60:61], 0, v[130:131]
	s_add_i32 m0, s8, 0x2000
	s_nop 0
	global_load_lds_dwordx4 v[212:213], off
	v_lshl_add_u64 v[212:213], v[216:217], 0, s[20:21]
	s_mov_b32 m0, s34
	s_nop 0
	global_load_lds_dwordx4 v[212:213], off
	v_lshl_add_u64 v[212:213], v[218:219], 0, s[20:21]
	s_mov_b32 m0, s35
	s_nop 0
	global_load_lds_dwordx4 v[212:213], off
	s_waitcnt vmcnt(8)
	s_waitcnt lgkmcnt(0)
	s_barrier
	s_setprio 1
	s_waitcnt lgkmcnt(0)
	v_mfma_f32_16x16x32_bf16 v[60:63], v[140:143], v[180:183], v[60:63]
	v_mfma_f32_16x16x32_bf16 v[56:59], v[156:159], v[180:183], v[56:59]
	v_mfma_f32_16x16x32_bf16 v[44:47], v[140:143], v[188:191], v[44:47]
	v_mfma_f32_16x16x32_bf16 v[40:43], v[156:159], v[188:191], v[40:43]
	v_mfma_f32_16x16x32_bf16 v[28:31], v[140:143], v[196:199], v[28:31]
	v_mfma_f32_16x16x32_bf16 v[24:27], v[156:159], v[196:199], v[24:27]
	v_mfma_f32_16x16x32_bf16 v[12:15], v[140:143], v[204:207], v[12:15]
	v_mfma_f32_16x16x32_bf16 v[8:11], v[156:159], v[204:207], v[8:11]
	v_mfma_f32_16x16x32_bf16 v[60:63], v[152:155], v[184:187], v[60:63]
	v_mfma_f32_16x16x32_bf16 v[56:59], v[160:163], v[184:187], v[56:59]
	v_mfma_f32_16x16x32_bf16 v[44:47], v[152:155], v[192:195], v[44:47]
	v_mfma_f32_16x16x32_bf16 v[40:43], v[160:163], v[192:195], v[40:43]
	v_mfma_f32_16x16x32_bf16 v[28:31], v[152:155], v[200:203], v[28:31]
	v_mfma_f32_16x16x32_bf16 v[24:27], v[160:163], v[200:203], v[24:27]
	v_mfma_f32_16x16x32_bf16 v[12:15], v[152:155], v[208:211], v[12:15]
	v_mfma_f32_16x16x32_bf16 v[8:11], v[160:163], v[208:211], v[8:11]
	v_mfma_f32_16x16x32_bf16 v[52:55], v[164:167], v[180:183], v[52:55]
	v_mfma_f32_16x16x32_bf16 v[48:51], v[172:175], v[180:183], v[48:51]
	v_mfma_f32_16x16x32_bf16 v[36:39], v[164:167], v[188:191], v[36:39]
	v_mfma_f32_16x16x32_bf16 v[32:35], v[172:175], v[188:191], v[32:35]
	v_mfma_f32_16x16x32_bf16 v[20:23], v[164:167], v[196:199], v[20:23]
	v_mfma_f32_16x16x32_bf16 v[16:19], v[172:175], v[196:199], v[16:19]
	v_mfma_f32_16x16x32_bf16 v[4:7], v[164:167], v[204:207], v[4:7]
	v_mfma_f32_16x16x32_bf16 v[0:3], v[172:175], v[204:207], v[0:3]
	v_mfma_f32_16x16x32_bf16 v[52:55], v[168:171], v[184:187], v[52:55]
	v_mfma_f32_16x16x32_bf16 v[48:51], v[176:179], v[184:187], v[48:51]
	v_mfma_f32_16x16x32_bf16 v[36:39], v[168:171], v[192:195], v[36:39]
	v_mfma_f32_16x16x32_bf16 v[32:35], v[176:179], v[192:195], v[32:35]
	v_mfma_f32_16x16x32_bf16 v[20:23], v[168:171], v[200:203], v[20:23]
	v_mfma_f32_16x16x32_bf16 v[16:19], v[176:179], v[200:203], v[16:19]
	v_mfma_f32_16x16x32_bf16 v[4:7], v[168:171], v[208:211], v[4:7]
	v_mfma_f32_16x16x32_bf16 v[0:3], v[176:179], v[208:211], v[0:3]
	s_setprio 0
	s_barrier
	s_add_i32 s72, s72, 2
	s_add_u32 s62, s62, 0x100
	s_addc_u32 s63, s63, 0
	s_add_u32 s70, s70, 0x100
	s_addc_u32 s71, s71, 0
	s_cmp_gt_u32 s72, 29
	s_cbranch_scc0 .LBB0_2713
	s_and_b64 vcc, exec, s[58:59]
	s_cbranch_vccz .LBB0_2716
	s_barrier

.LBB0_2805:
	ds_read_b128 v[146:149], v155
	ds_read_b128 v[160:163], v155 offset:1024
	ds_read_b128 v[164:167], v155 offset:2048
	ds_read_b128 v[168:171], v155 offset:3072
	ds_read_b128 v[172:175], v156
	ds_read_b128 v[176:179], v156 offset:1024
	ds_read_b128 v[180:183], v156 offset:2048
	ds_read_b128 v[184:187], v156 offset:3072
	s_add_u32 s8, s48, 0xfff80080
	s_addc_u32 s9, s49, -1
	s_cmp_eq_u32 s67, 28
	s_cselect_b32 s61, s21, s9
	s_cselect_b32 s60, s43, s8
	s_cselect_b32 s57, s19, s66
	s_cselect_b32 s56, s45, s65
	v_lshl_add_u64 v[220:221], s[48:49], 0, v[138:139]
	s_add_i32 m0, s29, 0xc000
	ds_read_b128 v[188:191], v157
	ds_read_b128 v[192:195], v157 offset:1024
	ds_read_b128 v[196:199], v157 offset:2048
	ds_read_b128 v[200:203], v157 offset:3072
	ds_read_b128 v[204:207], v157 offset:4096
	ds_read_b128 v[208:211], v157 offset:5120
	ds_read_b128 v[212:215], v157 offset:6144
	ds_read_b128 v[216:219], v157 offset:7168
	global_load_lds_dwordx4 v[220:221], off
	v_lshl_add_u64 v[220:221], s[48:49], 0, v[140:141]
	s_add_i32 m0, s29, 0xe000
	s_nop 0
	global_load_lds_dwordx4 v[220:221], off
	s_waitcnt vmcnt(8)
	s_waitcnt lgkmcnt(0)
	s_barrier
	s_setprio 1
	s_waitcnt lgkmcnt(0)
	v_mfma_f32_16x16x32_bf16 v[124:127], v[146:149], v[188:191], v[124:127]
	v_mfma_f32_16x16x32_bf16 v[120:123], v[164:167], v[188:191], v[120:123]
	v_mfma_f32_16x16x32_bf16 v[108:111], v[146:149], v[196:199], v[108:111]
	v_mfma_f32_16x16x32_bf16 v[104:107], v[164:167], v[196:199], v[104:107]
	v_mfma_f32_16x16x32_bf16 v[92:95], v[146:149], v[204:207], v[92:95]
	v_mfma_f32_16x16x32_bf16 v[88:91], v[164:167], v[204:207], v[88:91]
	v_mfma_f32_16x16x32_bf16 v[76:79], v[146:149], v[212:215], v[76:79]
	v_mfma_f32_16x16x32_bf16 v[72:75], v[164:167], v[212:215], v[72:75]
	v_mfma_f32_16x16x32_bf16 v[124:127], v[160:163], v[192:195], v[124:127]
	v_mfma_f32_16x16x32_bf16 v[120:123], v[168:171], v[192:195], v[120:123]
	v_mfma_f32_16x16x32_bf16 v[108:111], v[160:163], v[200:203], v[108:111]
	v_mfma_f32_16x16x32_bf16 v[104:107], v[168:171], v[200:203], v[104:107]
	v_mfma_f32_16x16x32_bf16 v[92:95], v[160:163], v[208:211], v[92:95]
	v_mfma_f32_16x16x32_bf16 v[88:91], v[168:171], v[208:211], v[88:91]
	v_mfma_f32_16x16x32_bf16 v[76:79], v[160:163], v[216:219], v[76:79]
	v_mfma_f32_16x16x32_bf16 v[72:75], v[168:171], v[216:219], v[72:75]
	v_mfma_f32_16x16x32_bf16 v[116:119], v[172:175], v[188:191], v[116:119]
	v_mfma_f32_16x16x32_bf16 v[112:115], v[180:183], v[188:191], v[112:115]
	v_mfma_f32_16x16x32_bf16 v[100:103], v[172:175], v[196:199], v[100:103]
	v_mfma_f32_16x16x32_bf16 v[96:99], v[180:183], v[196:199], v[96:99]
	v_mfma_f32_16x16x32_bf16 v[84:87], v[172:175], v[204:207], v[84:87]
	v_mfma_f32_16x16x32_bf16 v[80:83], v[180:183], v[204:207], v[80:83]
	v_mfma_f32_16x16x32_bf16 v[68:71], v[172:175], v[212:215], v[68:71]
	v_mfma_f32_16x16x32_bf16 v[64:67], v[180:183], v[212:215], v[64:67]
	v_mfma_f32_16x16x32_bf16 v[116:119], v[176:179], v[192:195], v[116:119]
	v_mfma_f32_16x16x32_bf16 v[112:115], v[184:187], v[192:195], v[112:115]
	v_mfma_f32_16x16x32_bf16 v[100:103], v[176:179], v[200:203], v[100:103]
	v_mfma_f32_16x16x32_bf16 v[96:99], v[184:187], v[200:203], v[96:99]
	v_mfma_f32_16x16x32_bf16 v[84:87], v[176:179], v[208:211], v[84:87]
	v_mfma_f32_16x16x32_bf16 v[80:83], v[184:187], v[208:211], v[80:83]
	v_mfma_f32_16x16x32_bf16 v[68:71], v[176:179], v[216:219], v[68:71]
	v_mfma_f32_16x16x32_bf16 v[64:67], v[184:187], v[216:219], v[64:67]
	s_setprio 0
	s_barrier
	s_add_i32 s8, s63, s94
	v_lshl_add_u64 v[220:221], s[56:57], 0, v[130:131]
	s_mov_b32 m0, s8
	ds_read_b128 v[188:191], v157 offset:16384
	ds_read_b128 v[192:195], v157 offset:17408
	ds_read_b128 v[196:199], v157 offset:18432
	ds_read_b128 v[200:203], v157 offset:19456
	ds_read_b128 v[204:207], v157 offset:20480
	ds_read_b128 v[208:211], v157 offset:21504
	ds_read_b128 v[212:215], v157 offset:22528
	ds_read_b128 v[216:219], v157 offset:23552
	global_load_lds_dwordx4 v[220:221], off
	s_add_i32 m0, s8, 0x2000
	s_add_u32 s68, s56, 0x80000
	v_lshl_add_u64 v[222:223], s[56:57], 0, v[134:135]
	s_addc_u32 s69, s57, 0
	s_add_i32 s8, s64, s94
	global_load_lds_dwordx4 v[222:223], off
	v_lshl_add_u64 v[224:225], s[68:69], 0, v[130:131]
	s_mov_b32 m0, s8
	v_lshl_add_u64 v[226:227], s[60:61], 0, v[132:133]
	global_load_lds_dwordx4 v[224:225], off
	v_lshl_add_u64 v[224:225], s[68:69], 0, v[134:135]
	s_add_i32 m0, s8, 0x2000
	s_nop 0
	global_load_lds_dwordx4 v[224:225], off
	v_lshl_add_u64 v[224:225], s[60:61], 0, v[128:129]
	s_mov_b32 m0, s29
	s_nop 0
	global_load_lds_dwordx4 v[224:225], off
	s_mov_b32 m0, s30
	s_nop 0
	global_load_lds_dwordx4 v[226:227], off
	s_waitcnt vmcnt(8)
	s_waitcnt lgkmcnt(0)
	s_barrier
	s_setprio 1
	s_waitcnt lgkmcnt(0)
	v_mfma_f32_16x16x32_bf16 v[60:63], v[146:149], v[188:191], v[60:63]
	v_mfma_f32_16x16x32_bf16 v[56:59], v[164:167], v[188:191], v[56:59]
	v_mfma_f32_16x16x32_bf16 v[44:47], v[146:149], v[196:199], v[44:47]
	v_mfma_f32_16x16x32_bf16 v[40:43], v[164:167], v[196:199], v[40:43]
	v_mfma_f32_16x16x32_bf16 v[28:31], v[146:149], v[204:207], v[28:31]
	v_mfma_f32_16x16x32_bf16 v[24:27], v[164:167], v[204:207], v[24:27]
	v_mfma_f32_16x16x32_bf16 v[12:15], v[146:149], v[212:215], v[12:15]
	v_mfma_f32_16x16x32_bf16 v[8:11], v[164:167], v[212:215], v[8:11]
	v_mfma_f32_16x16x32_bf16 v[60:63], v[160:163], v[192:195], v[60:63]
	v_mfma_f32_16x16x32_bf16 v[56:59], v[168:171], v[192:195], v[56:59]
	v_mfma_f32_16x16x32_bf16 v[44:47], v[160:163], v[200:203], v[44:47]
	v_mfma_f32_16x16x32_bf16 v[40:43], v[168:171], v[200:203], v[40:43]
	v_mfma_f32_16x16x32_bf16 v[28:31], v[160:163], v[208:211], v[28:31]
	v_mfma_f32_16x16x32_bf16 v[24:27], v[168:171], v[208:211], v[24:27]
	v_mfma_f32_16x16x32_bf16 v[12:15], v[160:163], v[216:219], v[12:15]
	v_mfma_f32_16x16x32_bf16 v[8:11], v[168:171], v[216:219], v[8:11]
	v_mfma_f32_16x16x32_bf16 v[52:55], v[172:175], v[188:191], v[52:55]
	v_mfma_f32_16x16x32_bf16 v[48:51], v[180:183], v[188:191], v[48:51]
	v_mfma_f32_16x16x32_bf16 v[36:39], v[172:175], v[196:199], v[36:39]
	v_mfma_f32_16x16x32_bf16 v[32:35], v[180:183], v[196:199], v[32:35]
	v_mfma_f32_16x16x32_bf16 v[20:23], v[172:175], v[204:207], v[20:23]
	v_mfma_f32_16x16x32_bf16 v[16:19], v[180:183], v[204:207], v[16:19]
	v_mfma_f32_16x16x32_bf16 v[4:7], v[172:175], v[212:215], v[4:7]
	v_mfma_f32_16x16x32_bf16 v[0:3], v[180:183], v[212:215], v[0:3]
	v_mfma_f32_16x16x32_bf16 v[52:55], v[176:179], v[192:195], v[52:55]
	v_mfma_f32_16x16x32_bf16 v[48:51], v[184:187], v[192:195], v[48:51]
	v_mfma_f32_16x16x32_bf16 v[36:39], v[176:179], v[200:203], v[36:39]
	v_mfma_f32_16x16x32_bf16 v[32:35], v[184:187], v[200:203], v[32:35]
	v_mfma_f32_16x16x32_bf16 v[20:23], v[176:179], v[208:211], v[20:23]
	v_mfma_f32_16x16x32_bf16 v[16:19], v[184:187], v[208:211], v[16:19]
	v_mfma_f32_16x16x32_bf16 v[4:7], v[176:179], v[216:219], v[4:7]
	v_mfma_f32_16x16x32_bf16 v[0:3], v[184:187], v[216:219], v[0:3]
	s_setprio 0
	s_barrier
	s_add_i32 s8, 0, 0x18000
	v_add_u32_e32 v159, s8, v151
	s_add_i32 s9, 0, 0x1c000
	ds_read_b128 v[146:149], v159
	ds_read_b128 v[160:163], v159 offset:1024
	ds_read_b128 v[164:167], v159 offset:2048
	ds_read_b128 v[168:171], v159 offset:3072
	v_add_u32_e32 v159, s9, v151
	ds_read_b128 v[172:175], v159
	ds_read_b128 v[176:179], v159 offset:1024
	ds_read_b128 v[180:183], v159 offset:2048
	ds_read_b128 v[184:187], v159 offset:3072
	s_add_u32 s60, s60, 0x80000
	s_addc_u32 s61, s61, 0
	s_mov_b32 m0, s34
	v_lshl_add_u64 v[228:229], s[60:61], 0, v[128:129]
	ds_read_b128 v[188:191], v157 offset:32768
	ds_read_b128 v[192:195], v157 offset:33792
	ds_read_b128 v[196:199], v157 offset:34816
	ds_read_b128 v[200:203], v157 offset:35840
	ds_read_b128 v[204:207], v157 offset:36864
	ds_read_b128 v[208:211], v157 offset:37888
	ds_read_b128 v[212:215], v157 offset:38912
	ds_read_b128 v[216:219], v157 offset:39936
	global_load_lds_dwordx4 v[228:229], off
	v_lshl_add_u64 v[228:229], s[60:61], 0, v[132:133]
	s_mov_b32 m0, s35
	s_nop 0
	global_load_lds_dwordx4 v[228:229], off
	s_waitcnt vmcnt(8)
	s_waitcnt lgkmcnt(0)
	s_barrier
	s_setprio 1
	s_waitcnt lgkmcnt(0)
	v_mfma_f32_16x16x32_bf16 v[124:127], v[146:149], v[188:191], v[124:127]
	v_mfma_f32_16x16x32_bf16 v[120:123], v[164:167], v[188:191], v[120:123]
	v_mfma_f32_16x16x32_bf16 v[108:111], v[146:149], v[196:199], v[108:111]
	v_mfma_f32_16x16x32_bf16 v[104:107], v[164:167], v[196:199], v[104:107]
	v_mfma_f32_16x16x32_bf16 v[92:95], v[146:149], v[204:207], v[92:95]
	v_mfma_f32_16x16x32_bf16 v[88:91], v[164:167], v[204:207], v[88:91]
	v_mfma_f32_16x16x32_bf16 v[76:79], v[146:149], v[212:215], v[76:79]
	v_mfma_f32_16x16x32_bf16 v[72:75], v[164:167], v[212:215], v[72:75]
	v_mfma_f32_16x16x32_bf16 v[124:127], v[160:163], v[192:195], v[124:127]
	v_mfma_f32_16x16x32_bf16 v[120:123], v[168:171], v[192:195], v[120:123]
	v_mfma_f32_16x16x32_bf16 v[108:111], v[160:163], v[200:203], v[108:111]
	v_mfma_f32_16x16x32_bf16 v[104:107], v[168:171], v[200:203], v[104:107]
	v_mfma_f32_16x16x32_bf16 v[92:95], v[160:163], v[208:211], v[92:95]
	v_mfma_f32_16x16x32_bf16 v[88:91], v[168:171], v[208:211], v[88:91]
	v_mfma_f32_16x16x32_bf16 v[76:79], v[160:163], v[216:219], v[76:79]
	v_mfma_f32_16x16x32_bf16 v[72:75], v[168:171], v[216:219], v[72:75]
	v_mfma_f32_16x16x32_bf16 v[116:119], v[172:175], v[188:191], v[116:119]
	v_mfma_f32_16x16x32_bf16 v[112:115], v[180:183], v[188:191], v[112:115]
	v_mfma_f32_16x16x32_bf16 v[100:103], v[172:175], v[196:199], v[100:103]
	v_mfma_f32_16x16x32_bf16 v[96:99], v[180:183], v[196:199], v[96:99]
	v_mfma_f32_16x16x32_bf16 v[84:87], v[172:175], v[204:207], v[84:87]
	v_mfma_f32_16x16x32_bf16 v[80:83], v[180:183], v[204:207], v[80:83]
	v_mfma_f32_16x16x32_bf16 v[68:71], v[172:175], v[212:215], v[68:71]
	v_mfma_f32_16x16x32_bf16 v[64:67], v[180:183], v[212:215], v[64:67]
	v_mfma_f32_16x16x32_bf16 v[116:119], v[176:179], v[192:195], v[116:119]
	v_mfma_f32_16x16x32_bf16 v[112:115], v[184:187], v[192:195], v[112:115]
	v_mfma_f32_16x16x32_bf16 v[100:103], v[176:179], v[200:203], v[100:103]
	v_mfma_f32_16x16x32_bf16 v[96:99], v[184:187], v[200:203], v[96:99]
	v_mfma_f32_16x16x32_bf16 v[84:87], v[176:179], v[208:211], v[84:87]
	v_mfma_f32_16x16x32_bf16 v[80:83], v[184:187], v[208:211], v[80:83]
	v_mfma_f32_16x16x32_bf16 v[68:71], v[176:179], v[216:219], v[68:71]
	v_mfma_f32_16x16x32_bf16 v[64:67], v[184:187], v[216:219], v[64:67]
	s_setprio 0
	s_barrier
	s_add_i32 s8, s8, s94
	v_lshl_add_u64 v[220:221], v[220:221], 0, s[16:17]
	s_mov_b32 m0, s8
	ds_read_b128 v[188:191], v157 offset:49152
	ds_read_b128 v[192:195], v157 offset:50176
	ds_read_b128 v[196:199], v157 offset:51200
	ds_read_b128 v[200:203], v157 offset:52224
	ds_read_b128 v[204:207], v157 offset:53248
	ds_read_b128 v[208:211], v157 offset:54272
	ds_read_b128 v[212:215], v157 offset:55296
	ds_read_b128 v[216:219], v157 offset:56320
	global_load_lds_dwordx4 v[220:221], off
	s_add_i32 m0, s8, 0x2000
	s_add_u32 s56, s56, 0x80080
	v_lshl_add_u64 v[220:221], v[222:223], 0, s[16:17]
	s_addc_u32 s57, s57, 0
	s_add_i32 s8, s9, s94
	global_load_lds_dwordx4 v[220:221], off
	v_lshl_add_u64 v[220:221], s[56:57], 0, v[130:131]
	s_mov_b32 m0, s8
	s_nop 0
	global_load_lds_dwordx4 v[220:221], off
	v_lshl_add_u64 v[220:221], s[56:57], 0, v[134:135]
	s_add_i32 m0, s8, 0x2000
	s_nop 0
	global_load_lds_dwordx4 v[220:221], off
	v_lshl_add_u64 v[220:221], v[224:225], 0, s[16:17]
	s_mov_b32 m0, s47
	s_nop 0
	global_load_lds_dwordx4 v[220:221], off
	v_lshl_add_u64 v[220:221], v[226:227], 0, s[16:17]
	s_mov_b32 m0, s62
	s_nop 0
	global_load_lds_dwordx4 v[220:221], off
	s_waitcnt vmcnt(8)
	s_waitcnt lgkmcnt(0)
	s_barrier
	s_setprio 1
	s_waitcnt lgkmcnt(0)
	v_mfma_f32_16x16x32_bf16 v[60:63], v[146:149], v[188:191], v[60:63]
	v_mfma_f32_16x16x32_bf16 v[56:59], v[164:167], v[188:191], v[56:59]
	v_mfma_f32_16x16x32_bf16 v[44:47], v[146:149], v[196:199], v[44:47]
	v_mfma_f32_16x16x32_bf16 v[40:43], v[164:167], v[196:199], v[40:43]
	v_mfma_f32_16x16x32_bf16 v[28:31], v[146:149], v[204:207], v[28:31]
	v_mfma_f32_16x16x32_bf16 v[24:27], v[164:167], v[204:207], v[24:27]
	v_mfma_f32_16x16x32_bf16 v[12:15], v[146:149], v[212:215], v[12:15]
	v_mfma_f32_16x16x32_bf16 v[8:11], v[164:167], v[212:215], v[8:11]
	v_mfma_f32_16x16x32_bf16 v[60:63], v[160:163], v[192:195], v[60:63]
	v_mfma_f32_16x16x32_bf16 v[56:59], v[168:171], v[192:195], v[56:59]
	v_mfma_f32_16x16x32_bf16 v[44:47], v[160:163], v[200:203], v[44:47]
	v_mfma_f32_16x16x32_bf16 v[40:43], v[168:171], v[200:203], v[40:43]
	v_mfma_f32_16x16x32_bf16 v[28:31], v[160:163], v[208:211], v[28:31]
	v_mfma_f32_16x16x32_bf16 v[24:27], v[168:171], v[208:211], v[24:27]
	v_mfma_f32_16x16x32_bf16 v[12:15], v[160:163], v[216:219], v[12:15]
	v_mfma_f32_16x16x32_bf16 v[8:11], v[168:171], v[216:219], v[8:11]
	v_mfma_f32_16x16x32_bf16 v[52:55], v[172:175], v[188:191], v[52:55]
	v_mfma_f32_16x16x32_bf16 v[48:51], v[180:183], v[188:191], v[48:51]
	v_mfma_f32_16x16x32_bf16 v[36:39], v[172:175], v[196:199], v[36:39]
	v_mfma_f32_16x16x32_bf16 v[32:35], v[180:183], v[196:199], v[32:35]
	v_mfma_f32_16x16x32_bf16 v[20:23], v[172:175], v[204:207], v[20:23]
	v_mfma_f32_16x16x32_bf16 v[16:19], v[180:183], v[204:207], v[16:19]
	v_mfma_f32_16x16x32_bf16 v[4:7], v[172:175], v[212:215], v[4:7]
	v_mfma_f32_16x16x32_bf16 v[0:3], v[180:183], v[212:215], v[0:3]
	v_mfma_f32_16x16x32_bf16 v[52:55], v[176:179], v[192:195], v[52:55]
	v_mfma_f32_16x16x32_bf16 v[48:51], v[184:187], v[192:195], v[48:51]
	v_mfma_f32_16x16x32_bf16 v[36:39], v[176:179], v[200:203], v[36:39]
	v_mfma_f32_16x16x32_bf16 v[32:35], v[184:187], v[200:203], v[32:35]
	v_mfma_f32_16x16x32_bf16 v[20:23], v[176:179], v[208:211], v[20:23]
	v_mfma_f32_16x16x32_bf16 v[16:19], v[184:187], v[208:211], v[16:19]
	v_mfma_f32_16x16x32_bf16 v[4:7], v[176:179], v[216:219], v[4:7]
	v_mfma_f32_16x16x32_bf16 v[0:3], v[184:187], v[216:219], v[0:3]
	s_setprio 0
	s_barrier
	s_add_i32 s67, s67, 2
	s_add_u32 s48, s48, 0x100
	s_addc_u32 s49, s49, 0
	s_add_u32 s65, s65, 0x100
	s_addc_u32 s66, s66, 0
	s_cmp_gt_u32 s67, 29
	s_cbranch_scc0 .LBB0_2805
	s_and_b64 vcc, exec, s[58:59]
	s_cbranch_vccz .LBB0_2808
	s_barrier

.LBB0_2917:
	ds_read_b128 v[140:143], v149
	ds_read_b128 v[152:155], v149 offset:1024
	ds_read_b128 v[156:159], v149 offset:2048
	ds_read_b128 v[160:163], v149 offset:3072
	ds_read_b128 v[164:167], v150
	ds_read_b128 v[168:171], v150 offset:1024
	ds_read_b128 v[172:175], v150 offset:2048
	ds_read_b128 v[176:179], v150 offset:3072
	s_add_u32 s42, s40, 0xffe00080
	s_addc_u32 s43, s41, -1
	s_cmpk_eq_i32 s64, 0x7c
	s_cselect_b32 s45, s21, s43
	s_cselect_b32 s44, s39, s42
	s_cselect_b32 s43, s19, s63
	s_cselect_b32 s42, s61, s62
	v_lshl_add_u64 v[212:213], s[40:41], 0, v[132:133]
	s_add_i32 m0, s29, 0xc000
	ds_read_b128 v[180:183], v151
	ds_read_b128 v[184:187], v151 offset:1024
	ds_read_b128 v[188:191], v151 offset:2048
	ds_read_b128 v[192:195], v151 offset:3072
	ds_read_b128 v[196:199], v151 offset:4096
	ds_read_b128 v[200:203], v151 offset:5120
	ds_read_b128 v[204:207], v151 offset:6144
	ds_read_b128 v[208:211], v151 offset:7168
	global_load_lds_dwordx4 v[212:213], off
	v_lshl_add_u64 v[212:213], s[40:41], 0, v[134:135]
	s_add_i32 m0, s29, 0xe000
	s_nop 0
	global_load_lds_dwordx4 v[212:213], off
	s_waitcnt vmcnt(8)
	s_waitcnt lgkmcnt(0)
	s_barrier
	s_setprio 1
	s_waitcnt lgkmcnt(0)
	v_mfma_f32_16x16x32_bf16 v[124:127], v[140:143], v[180:183], v[124:127]
	v_mfma_f32_16x16x32_bf16 v[120:123], v[156:159], v[180:183], v[120:123]
	v_mfma_f32_16x16x32_bf16 v[108:111], v[140:143], v[188:191], v[108:111]
	v_mfma_f32_16x16x32_bf16 v[104:107], v[156:159], v[188:191], v[104:107]
	v_mfma_f32_16x16x32_bf16 v[92:95], v[140:143], v[196:199], v[92:95]
	v_mfma_f32_16x16x32_bf16 v[88:91], v[156:159], v[196:199], v[88:91]
	v_mfma_f32_16x16x32_bf16 v[76:79], v[140:143], v[204:207], v[76:79]
	v_mfma_f32_16x16x32_bf16 v[72:75], v[156:159], v[204:207], v[72:75]
	v_mfma_f32_16x16x32_bf16 v[124:127], v[152:155], v[184:187], v[124:127]
	v_mfma_f32_16x16x32_bf16 v[120:123], v[160:163], v[184:187], v[120:123]
	v_mfma_f32_16x16x32_bf16 v[108:111], v[152:155], v[192:195], v[108:111]
	v_mfma_f32_16x16x32_bf16 v[104:107], v[160:163], v[192:195], v[104:107]
	v_mfma_f32_16x16x32_bf16 v[92:95], v[152:155], v[200:203], v[92:95]
	v_mfma_f32_16x16x32_bf16 v[88:91], v[160:163], v[200:203], v[88:91]
	v_mfma_f32_16x16x32_bf16 v[76:79], v[152:155], v[208:211], v[76:79]
	v_mfma_f32_16x16x32_bf16 v[72:75], v[160:163], v[208:211], v[72:75]
	v_mfma_f32_16x16x32_bf16 v[116:119], v[164:167], v[180:183], v[116:119]
	v_mfma_f32_16x16x32_bf16 v[112:115], v[172:175], v[180:183], v[112:115]
	v_mfma_f32_16x16x32_bf16 v[100:103], v[164:167], v[188:191], v[100:103]
	v_mfma_f32_16x16x32_bf16 v[96:99], v[172:175], v[188:191], v[96:99]
	v_mfma_f32_16x16x32_bf16 v[84:87], v[164:167], v[196:199], v[84:87]
	v_mfma_f32_16x16x32_bf16 v[80:83], v[172:175], v[196:199], v[80:83]
	v_mfma_f32_16x16x32_bf16 v[68:71], v[164:167], v[204:207], v[68:71]
	v_mfma_f32_16x16x32_bf16 v[64:67], v[172:175], v[204:207], v[64:67]
	v_mfma_f32_16x16x32_bf16 v[116:119], v[168:171], v[184:187], v[116:119]
	v_mfma_f32_16x16x32_bf16 v[112:115], v[176:179], v[184:187], v[112:115]
	v_mfma_f32_16x16x32_bf16 v[100:103], v[168:171], v[192:195], v[100:103]
	v_mfma_f32_16x16x32_bf16 v[96:99], v[176:179], v[192:195], v[96:99]
	v_mfma_f32_16x16x32_bf16 v[84:87], v[168:171], v[200:203], v[84:87]
	v_mfma_f32_16x16x32_bf16 v[80:83], v[176:179], v[200:203], v[80:83]
	v_mfma_f32_16x16x32_bf16 v[68:71], v[168:171], v[208:211], v[68:71]
	v_mfma_f32_16x16x32_bf16 v[64:67], v[176:179], v[208:211], v[64:67]
	s_setprio 0
	s_barrier
	s_add_i32 s65, s56, s94
	v_lshl_add_u64 v[212:213], s[42:43], 0, v[128:129]
	s_mov_b32 m0, s65
	ds_read_b128 v[180:183], v151 offset:16384
	ds_read_b128 v[184:187], v151 offset:17408
	ds_read_b128 v[188:191], v151 offset:18432
	ds_read_b128 v[192:195], v151 offset:19456
	ds_read_b128 v[196:199], v151 offset:20480
	ds_read_b128 v[200:203], v151 offset:21504
	ds_read_b128 v[204:207], v151 offset:22528
	ds_read_b128 v[208:211], v151 offset:23552
	global_load_lds_dwordx4 v[212:213], off
	s_add_i32 m0, s65, 0x2000
	s_add_u32 s66, s42, 0x200000
	v_lshl_add_u64 v[214:215], s[42:43], 0, v[130:131]
	s_addc_u32 s67, s43, 0
	s_add_i32 s65, s57, s94
	global_load_lds_dwordx4 v[214:215], off
	v_lshl_add_u64 v[216:217], s[66:67], 0, v[128:129]
	s_mov_b32 m0, s65
	v_lshl_add_u64 v[218:219], s[44:45], 0, v[130:131]
	global_load_lds_dwordx4 v[216:217], off
	v_lshl_add_u64 v[216:217], s[66:67], 0, v[130:131]
	s_add_i32 m0, s65, 0x2000
	s_nop 0
	global_load_lds_dwordx4 v[216:217], off
	v_lshl_add_u64 v[216:217], s[44:45], 0, v[128:129]
	s_mov_b32 m0, s29
	s_nop 0
	global_load_lds_dwordx4 v[216:217], off
	s_mov_b32 m0, s30
	s_nop 0
	global_load_lds_dwordx4 v[218:219], off
	s_waitcnt vmcnt(8)
	s_waitcnt lgkmcnt(0)
	s_barrier
	s_setprio 1
	s_waitcnt lgkmcnt(0)
	v_mfma_f32_16x16x32_bf16 v[60:63], v[140:143], v[180:183], v[60:63]
	v_mfma_f32_16x16x32_bf16 v[56:59], v[156:159], v[180:183], v[56:59]
	v_mfma_f32_16x16x32_bf16 v[44:47], v[140:143], v[188:191], v[44:47]
	v_mfma_f32_16x16x32_bf16 v[40:43], v[156:159], v[188:191], v[40:43]
	v_mfma_f32_16x16x32_bf16 v[28:31], v[140:143], v[196:199], v[28:31]
	v_mfma_f32_16x16x32_bf16 v[24:27], v[156:159], v[196:199], v[24:27]
	v_mfma_f32_16x16x32_bf16 v[12:15], v[140:143], v[204:207], v[12:15]
	v_mfma_f32_16x16x32_bf16 v[8:11], v[156:159], v[204:207], v[8:11]
	v_mfma_f32_16x16x32_bf16 v[60:63], v[152:155], v[184:187], v[60:63]
	v_mfma_f32_16x16x32_bf16 v[56:59], v[160:163], v[184:187], v[56:59]
	v_mfma_f32_16x16x32_bf16 v[44:47], v[152:155], v[192:195], v[44:47]
	v_mfma_f32_16x16x32_bf16 v[40:43], v[160:163], v[192:195], v[40:43]
	v_mfma_f32_16x16x32_bf16 v[28:31], v[152:155], v[200:203], v[28:31]
	v_mfma_f32_16x16x32_bf16 v[24:27], v[160:163], v[200:203], v[24:27]
	v_mfma_f32_16x16x32_bf16 v[12:15], v[152:155], v[208:211], v[12:15]
	v_mfma_f32_16x16x32_bf16 v[8:11], v[160:163], v[208:211], v[8:11]
	v_mfma_f32_16x16x32_bf16 v[52:55], v[164:167], v[180:183], v[52:55]
	v_mfma_f32_16x16x32_bf16 v[48:51], v[172:175], v[180:183], v[48:51]
	v_mfma_f32_16x16x32_bf16 v[36:39], v[164:167], v[188:191], v[36:39]
	v_mfma_f32_16x16x32_bf16 v[32:35], v[172:175], v[188:191], v[32:35]
	v_mfma_f32_16x16x32_bf16 v[20:23], v[164:167], v[196:199], v[20:23]
	v_mfma_f32_16x16x32_bf16 v[16:19], v[172:175], v[196:199], v[16:19]
	v_mfma_f32_16x16x32_bf16 v[4:7], v[164:167], v[204:207], v[4:7]
	v_mfma_f32_16x16x32_bf16 v[0:3], v[172:175], v[204:207], v[0:3]
	v_mfma_f32_16x16x32_bf16 v[52:55], v[168:171], v[184:187], v[52:55]
	v_mfma_f32_16x16x32_bf16 v[48:51], v[176:179], v[184:187], v[48:51]
	v_mfma_f32_16x16x32_bf16 v[36:39], v[168:171], v[192:195], v[36:39]
	v_mfma_f32_16x16x32_bf16 v[32:35], v[176:179], v[192:195], v[32:35]
	v_mfma_f32_16x16x32_bf16 v[20:23], v[168:171], v[200:203], v[20:23]
	v_mfma_f32_16x16x32_bf16 v[16:19], v[176:179], v[200:203], v[16:19]
	v_mfma_f32_16x16x32_bf16 v[4:7], v[168:171], v[208:211], v[4:7]
	v_mfma_f32_16x16x32_bf16 v[0:3], v[176:179], v[208:211], v[0:3]
	s_setprio 0
	s_barrier
	s_add_i32 s65, 0, 0x18000
	s_add_i32 s66, 0, 0x1c000
	v_add_u32_e32 v160, s65, v145
	v_add_u32_e32 v176, s66, v145
	ds_read_b128 v[140:143], v160
	ds_read_b128 v[152:155], v160 offset:1024
	ds_read_b128 v[156:159], v160 offset:2048
	ds_read_b128 v[160:163], v160 offset:3072
	ds_read_b128 v[164:167], v176
	ds_read_b128 v[168:171], v176 offset:1024
	ds_read_b128 v[172:175], v176 offset:2048
	ds_read_b128 v[176:179], v176 offset:3072
	s_add_u32 s44, s44, 0x200000
	s_addc_u32 s45, s45, 0
	s_mov_b32 m0, s46
	v_lshl_add_u64 v[220:221], s[44:45], 0, v[128:129]
	ds_read_b128 v[180:183], v151 offset:32768
	ds_read_b128 v[184:187], v151 offset:33792
	ds_read_b128 v[188:191], v151 offset:34816
	ds_read_b128 v[192:195], v151 offset:35840
	ds_read_b128 v[196:199], v151 offset:36864
	ds_read_b128 v[200:203], v151 offset:37888
	ds_read_b128 v[204:207], v151 offset:38912
	ds_read_b128 v[208:211], v151 offset:39936
	global_load_lds_dwordx4 v[220:221], off
	v_lshl_add_u64 v[220:221], s[44:45], 0, v[130:131]
	s_mov_b32 m0, s47
	s_nop 0
	global_load_lds_dwordx4 v[220:221], off
	s_waitcnt vmcnt(8)
	s_waitcnt lgkmcnt(0)
	s_barrier
	s_setprio 1
	s_waitcnt lgkmcnt(0)
	v_mfma_f32_16x16x32_bf16 v[124:127], v[140:143], v[180:183], v[124:127]
	v_mfma_f32_16x16x32_bf16 v[120:123], v[156:159], v[180:183], v[120:123]
	v_mfma_f32_16x16x32_bf16 v[108:111], v[140:143], v[188:191], v[108:111]
	v_mfma_f32_16x16x32_bf16 v[104:107], v[156:159], v[188:191], v[104:107]
	v_mfma_f32_16x16x32_bf16 v[92:95], v[140:143], v[196:199], v[92:95]
	v_mfma_f32_16x16x32_bf16 v[88:91], v[156:159], v[196:199], v[88:91]
	v_mfma_f32_16x16x32_bf16 v[76:79], v[140:143], v[204:207], v[76:79]
	v_mfma_f32_16x16x32_bf16 v[72:75], v[156:159], v[204:207], v[72:75]
	v_mfma_f32_16x16x32_bf16 v[124:127], v[152:155], v[184:187], v[124:127]
	v_mfma_f32_16x16x32_bf16 v[120:123], v[160:163], v[184:187], v[120:123]
	v_mfma_f32_16x16x32_bf16 v[108:111], v[152:155], v[192:195], v[108:111]
	v_mfma_f32_16x16x32_bf16 v[104:107], v[160:163], v[192:195], v[104:107]
	v_mfma_f32_16x16x32_bf16 v[92:95], v[152:155], v[200:203], v[92:95]
	v_mfma_f32_16x16x32_bf16 v[88:91], v[160:163], v[200:203], v[88:91]
	v_mfma_f32_16x16x32_bf16 v[76:79], v[152:155], v[208:211], v[76:79]
	v_mfma_f32_16x16x32_bf16 v[72:75], v[160:163], v[208:211], v[72:75]
	v_mfma_f32_16x16x32_bf16 v[116:119], v[164:167], v[180:183], v[116:119]
	v_mfma_f32_16x16x32_bf16 v[112:115], v[172:175], v[180:183], v[112:115]
	v_mfma_f32_16x16x32_bf16 v[100:103], v[164:167], v[188:191], v[100:103]
	v_mfma_f32_16x16x32_bf16 v[96:99], v[172:175], v[188:191], v[96:99]
	v_mfma_f32_16x16x32_bf16 v[84:87], v[164:167], v[196:199], v[84:87]
	v_mfma_f32_16x16x32_bf16 v[80:83], v[172:175], v[196:199], v[80:83]
	v_mfma_f32_16x16x32_bf16 v[68:71], v[164:167], v[204:207], v[68:71]
	v_mfma_f32_16x16x32_bf16 v[64:67], v[172:175], v[204:207], v[64:67]
	v_mfma_f32_16x16x32_bf16 v[116:119], v[168:171], v[184:187], v[116:119]
	v_mfma_f32_16x16x32_bf16 v[112:115], v[176:179], v[184:187], v[112:115]
	v_mfma_f32_16x16x32_bf16 v[100:103], v[168:171], v[192:195], v[100:103]
	v_mfma_f32_16x16x32_bf16 v[96:99], v[176:179], v[192:195], v[96:99]
	v_mfma_f32_16x16x32_bf16 v[84:87], v[168:171], v[200:203], v[84:87]
	v_mfma_f32_16x16x32_bf16 v[80:83], v[176:179], v[200:203], v[80:83]
	v_mfma_f32_16x16x32_bf16 v[68:71], v[168:171], v[208:211], v[68:71]
	v_mfma_f32_16x16x32_bf16 v[64:67], v[176:179], v[208:211], v[64:67]
	s_setprio 0
	s_barrier
	s_add_i32 s44, s65, s94
	v_lshl_add_u64 v[212:213], v[212:213], 0, s[16:17]
	s_mov_b32 m0, s44
	ds_read_b128 v[180:183], v151 offset:49152
	ds_read_b128 v[184:187], v151 offset:50176
	ds_read_b128 v[188:191], v151 offset:51200
	ds_read_b128 v[192:195], v151 offset:52224
	ds_read_b128 v[196:199], v151 offset:53248
	ds_read_b128 v[200:203], v151 offset:54272
	ds_read_b128 v[204:207], v151 offset:55296
	ds_read_b128 v[208:211], v151 offset:56320
	global_load_lds_dwordx4 v[212:213], off
	s_add_i32 m0, s44, 0x2000
	s_add_u32 s42, s42, 0x200080
	v_lshl_add_u64 v[212:213], v[214:215], 0, s[16:17]
	s_addc_u32 s43, s43, 0
	s_add_i32 s44, s66, s94
	global_load_lds_dwordx4 v[212:213], off
	v_lshl_add_u64 v[212:213], s[42:43], 0, v[128:129]
	s_mov_b32 m0, s44
	s_nop 0
	global_load_lds_dwordx4 v[212:213], off
	v_lshl_add_u64 v[212:213], s[42:43], 0, v[130:131]
	s_add_i32 m0, s44, 0x2000
	s_nop 0
	global_load_lds_dwordx4 v[212:213], off
	v_lshl_add_u64 v[212:213], v[216:217], 0, s[16:17]
	s_mov_b32 m0, s48
	s_nop 0
	global_load_lds_dwordx4 v[212:213], off
	v_lshl_add_u64 v[212:213], v[218:219], 0, s[16:17]
	s_mov_b32 m0, s49
	s_nop 0
	global_load_lds_dwordx4 v[212:213], off
	s_waitcnt vmcnt(8)
	s_waitcnt lgkmcnt(0)
	s_barrier
	s_setprio 1
	s_waitcnt lgkmcnt(0)
	v_mfma_f32_16x16x32_bf16 v[60:63], v[140:143], v[180:183], v[60:63]
	v_mfma_f32_16x16x32_bf16 v[56:59], v[156:159], v[180:183], v[56:59]
	v_mfma_f32_16x16x32_bf16 v[44:47], v[140:143], v[188:191], v[44:47]
	v_mfma_f32_16x16x32_bf16 v[40:43], v[156:159], v[188:191], v[40:43]
	v_mfma_f32_16x16x32_bf16 v[28:31], v[140:143], v[196:199], v[28:31]
	v_mfma_f32_16x16x32_bf16 v[24:27], v[156:159], v[196:199], v[24:27]
	v_mfma_f32_16x16x32_bf16 v[12:15], v[140:143], v[204:207], v[12:15]
	v_mfma_f32_16x16x32_bf16 v[8:11], v[156:159], v[204:207], v[8:11]
	v_mfma_f32_16x16x32_bf16 v[60:63], v[152:155], v[184:187], v[60:63]
	v_mfma_f32_16x16x32_bf16 v[56:59], v[160:163], v[184:187], v[56:59]
	v_mfma_f32_16x16x32_bf16 v[44:47], v[152:155], v[192:195], v[44:47]
	v_mfma_f32_16x16x32_bf16 v[40:43], v[160:163], v[192:195], v[40:43]
	v_mfma_f32_16x16x32_bf16 v[28:31], v[152:155], v[200:203], v[28:31]
	v_mfma_f32_16x16x32_bf16 v[24:27], v[160:163], v[200:203], v[24:27]
	v_mfma_f32_16x16x32_bf16 v[12:15], v[152:155], v[208:211], v[12:15]
	v_mfma_f32_16x16x32_bf16 v[8:11], v[160:163], v[208:211], v[8:11]
	v_mfma_f32_16x16x32_bf16 v[52:55], v[164:167], v[180:183], v[52:55]
	v_mfma_f32_16x16x32_bf16 v[48:51], v[172:175], v[180:183], v[48:51]
	v_mfma_f32_16x16x32_bf16 v[36:39], v[164:167], v[188:191], v[36:39]
	v_mfma_f32_16x16x32_bf16 v[32:35], v[172:175], v[188:191], v[32:35]
	v_mfma_f32_16x16x32_bf16 v[20:23], v[164:167], v[196:199], v[20:23]
	v_mfma_f32_16x16x32_bf16 v[16:19], v[172:175], v[196:199], v[16:19]
	v_mfma_f32_16x16x32_bf16 v[4:7], v[164:167], v[204:207], v[4:7]
	v_mfma_f32_16x16x32_bf16 v[0:3], v[172:175], v[204:207], v[0:3]
	v_mfma_f32_16x16x32_bf16 v[52:55], v[168:171], v[184:187], v[52:55]
	v_mfma_f32_16x16x32_bf16 v[48:51], v[176:179], v[184:187], v[48:51]
	v_mfma_f32_16x16x32_bf16 v[36:39], v[168:171], v[192:195], v[36:39]
	v_mfma_f32_16x16x32_bf16 v[32:35], v[176:179], v[192:195], v[32:35]
	v_mfma_f32_16x16x32_bf16 v[20:23], v[168:171], v[200:203], v[20:23]
	v_mfma_f32_16x16x32_bf16 v[16:19], v[176:179], v[200:203], v[16:19]
	v_mfma_f32_16x16x32_bf16 v[4:7], v[168:171], v[208:211], v[4:7]
	v_mfma_f32_16x16x32_bf16 v[0:3], v[176:179], v[208:211], v[0:3]
	s_setprio 0
	s_barrier
	s_add_i32 s64, s64, 2
	s_add_u32 s40, s40, 0x100
	s_addc_u32 s41, s41, 0
	s_add_u32 s62, s62, 0x100
	s_addc_u32 s63, s63, 0
	s_cmpk_gt_u32 s64, 0x7d
	s_cbranch_scc0 .LBB0_2917
	s_and_b64 vcc, exec, s[58:59]
	s_cbranch_vccz .LBB0_2920
	s_barrier
